# a9 + all s_setprio toggles removed from the 10 GEMM K-loops
# baseline (speedup 1.0000x reference)
.LBB0_297:
	ds_read_b128 v[164:167], v157
	ds_read_b128 v[168:171], v157 offset:1024
	ds_read_b128 v[172:175], v157 offset:2048
	ds_read_b128 v[176:179], v157 offset:3072
	ds_read_b128 v[180:183], v159
	ds_read_b128 v[184:187], v159 offset:1024
	ds_read_b128 v[188:191], v159 offset:2048
	ds_read_b128 v[192:195], v159 offset:3072
	s_add_u32 s66, s64, 0xfffc0080
	s_addc_u32 s67, s65, -1
	s_cmp_eq_u32 s86, 12
	s_cselect_b32 s69, s8, s67
	s_cselect_b32 s68, s9, s66
	s_cselect_b32 s67, s19, s85
	s_cselect_b32 s66, s39, s63
	v_lshl_add_u64 v[148:149], s[64:65], 0, v[140:141]
	s_add_i32 m0, s61, 0xc000
	ds_read_b128 v[196:199], v161
	ds_read_b128 v[200:203], v161 offset:1024
	ds_read_b128 v[204:207], v161 offset:2048
	ds_read_b128 v[208:211], v161 offset:3072
	ds_read_b128 v[212:215], v161 offset:4096
	ds_read_b128 v[216:219], v161 offset:5120
	ds_read_b128 v[220:223], v161 offset:6144
	ds_read_b128 v[224:227], v161 offset:7168
	global_load_lds_dwordx4 v[148:149], off
	v_lshl_add_u64 v[148:149], s[64:65], 0, v[142:143]
	s_add_i32 m0, s61, 0xe000
	s_nop 0
	global_load_lds_dwordx4 v[148:149], off
	s_waitcnt vmcnt(8)
	s_waitcnt lgkmcnt(0)
	s_barrier
	s_waitcnt lgkmcnt(0)
	v_mfma_f32_16x16x32_bf16 v[124:127], v[164:167], v[196:199], v[124:127]
	v_mfma_f32_16x16x32_bf16 v[120:123], v[172:175], v[196:199], v[120:123]
	v_mfma_f32_16x16x32_bf16 v[108:111], v[164:167], v[204:207], v[108:111]
	v_mfma_f32_16x16x32_bf16 v[104:107], v[172:175], v[204:207], v[104:107]
	v_mfma_f32_16x16x32_bf16 v[92:95], v[164:167], v[212:215], v[92:95]
	v_mfma_f32_16x16x32_bf16 v[88:91], v[172:175], v[212:215], v[88:91]
	v_mfma_f32_16x16x32_bf16 v[76:79], v[164:167], v[220:223], v[76:79]
	v_mfma_f32_16x16x32_bf16 v[72:75], v[172:175], v[220:223], v[72:75]
	v_mfma_f32_16x16x32_bf16 v[124:127], v[168:171], v[200:203], v[124:127]
	v_mfma_f32_16x16x32_bf16 v[120:123], v[176:179], v[200:203], v[120:123]
	v_mfma_f32_16x16x32_bf16 v[108:111], v[168:171], v[208:211], v[108:111]
	v_mfma_f32_16x16x32_bf16 v[104:107], v[176:179], v[208:211], v[104:107]
	v_mfma_f32_16x16x32_bf16 v[92:95], v[168:171], v[216:219], v[92:95]
	v_mfma_f32_16x16x32_bf16 v[88:91], v[176:179], v[216:219], v[88:91]
	v_mfma_f32_16x16x32_bf16 v[76:79], v[168:171], v[224:227], v[76:79]
	v_mfma_f32_16x16x32_bf16 v[72:75], v[176:179], v[224:227], v[72:75]
	v_mfma_f32_16x16x32_bf16 v[116:119], v[180:183], v[196:199], v[116:119]
	v_mfma_f32_16x16x32_bf16 v[112:115], v[188:191], v[196:199], v[112:115]
	v_mfma_f32_16x16x32_bf16 v[100:103], v[180:183], v[204:207], v[100:103]
	v_mfma_f32_16x16x32_bf16 v[96:99], v[188:191], v[204:207], v[96:99]
	v_mfma_f32_16x16x32_bf16 v[84:87], v[180:183], v[212:215], v[84:87]
	v_mfma_f32_16x16x32_bf16 v[80:83], v[188:191], v[212:215], v[80:83]
	v_mfma_f32_16x16x32_bf16 v[68:71], v[180:183], v[220:223], v[68:71]
	v_mfma_f32_16x16x32_bf16 v[64:67], v[188:191], v[220:223], v[64:67]
	v_mfma_f32_16x16x32_bf16 v[116:119], v[184:187], v[200:203], v[116:119]
	v_mfma_f32_16x16x32_bf16 v[112:115], v[192:195], v[200:203], v[112:115]
	v_mfma_f32_16x16x32_bf16 v[100:103], v[184:187], v[208:211], v[100:103]
	v_mfma_f32_16x16x32_bf16 v[96:99], v[192:195], v[208:211], v[96:99]
	v_mfma_f32_16x16x32_bf16 v[84:87], v[184:187], v[216:219], v[84:87]
	v_mfma_f32_16x16x32_bf16 v[80:83], v[192:195], v[216:219], v[80:83]
	v_mfma_f32_16x16x32_bf16 v[68:71], v[184:187], v[224:227], v[68:71]
	v_mfma_f32_16x16x32_bf16 v[64:67], v[192:195], v[224:227], v[64:67]
	s_barrier
	s_add_i32 s90, s82, s35
	v_lshl_add_u64 v[148:149], s[66:67], 0, v[130:131]
	s_mov_b32 m0, s90
	ds_read_b128 v[196:199], v161 offset:16384
	ds_read_b128 v[200:203], v161 offset:17408
	ds_read_b128 v[204:207], v161 offset:18432
	ds_read_b128 v[208:211], v161 offset:19456
	ds_read_b128 v[212:215], v161 offset:20480
	ds_read_b128 v[216:219], v161 offset:21504
	ds_read_b128 v[220:223], v161 offset:22528
	ds_read_b128 v[224:227], v161 offset:23552
	global_load_lds_dwordx4 v[148:149], off
	s_add_i32 m0, s90, 0x2000
	s_add_u32 s90, s66, 0x40000
	v_lshl_add_u64 v[152:153], s[66:67], 0, v[134:135]
	s_addc_u32 s91, s67, 0
	s_add_i32 s92, s83, s35
	global_load_lds_dwordx4 v[152:153], off
	v_lshl_add_u64 v[228:229], s[90:91], 0, v[130:131]
	s_mov_b32 m0, s92
	v_lshl_add_u64 v[230:231], s[68:69], 0, v[132:133]
	global_load_lds_dwordx4 v[228:229], off
	v_lshl_add_u64 v[228:229], s[90:91], 0, v[134:135]
	s_add_i32 m0, s92, 0x2000
	s_nop 0
	global_load_lds_dwordx4 v[228:229], off
	v_lshl_add_u64 v[228:229], s[68:69], 0, v[128:129]
	s_mov_b32 m0, s61
	s_nop 0
	global_load_lds_dwordx4 v[228:229], off
	s_mov_b32 m0, s70
	s_nop 0
	global_load_lds_dwordx4 v[230:231], off
	s_waitcnt vmcnt(8)
	s_waitcnt lgkmcnt(0)
	s_barrier
	s_waitcnt lgkmcnt(0)
	v_mfma_f32_16x16x32_bf16 v[60:63], v[164:167], v[196:199], v[60:63]
	v_mfma_f32_16x16x32_bf16 v[56:59], v[172:175], v[196:199], v[56:59]
	v_mfma_f32_16x16x32_bf16 v[44:47], v[164:167], v[204:207], v[44:47]
	v_mfma_f32_16x16x32_bf16 v[40:43], v[172:175], v[204:207], v[40:43]
	v_mfma_f32_16x16x32_bf16 v[28:31], v[164:167], v[212:215], v[28:31]
	v_mfma_f32_16x16x32_bf16 v[24:27], v[172:175], v[212:215], v[24:27]
	v_mfma_f32_16x16x32_bf16 v[12:15], v[164:167], v[220:223], v[12:15]
	v_mfma_f32_16x16x32_bf16 v[8:11], v[172:175], v[220:223], v[8:11]
	v_mfma_f32_16x16x32_bf16 v[60:63], v[168:171], v[200:203], v[60:63]
	v_mfma_f32_16x16x32_bf16 v[56:59], v[176:179], v[200:203], v[56:59]
	v_mfma_f32_16x16x32_bf16 v[44:47], v[168:171], v[208:211], v[44:47]
	v_mfma_f32_16x16x32_bf16 v[40:43], v[176:179], v[208:211], v[40:43]
	v_mfma_f32_16x16x32_bf16 v[28:31], v[168:171], v[216:219], v[28:31]
	v_mfma_f32_16x16x32_bf16 v[24:27], v[176:179], v[216:219], v[24:27]
	v_mfma_f32_16x16x32_bf16 v[12:15], v[168:171], v[224:227], v[12:15]
	v_mfma_f32_16x16x32_bf16 v[8:11], v[176:179], v[224:227], v[8:11]
	v_mfma_f32_16x16x32_bf16 v[52:55], v[180:183], v[196:199], v[52:55]
	v_mfma_f32_16x16x32_bf16 v[48:51], v[188:191], v[196:199], v[48:51]
	v_mfma_f32_16x16x32_bf16 v[36:39], v[180:183], v[204:207], v[36:39]
	v_mfma_f32_16x16x32_bf16 v[32:35], v[188:191], v[204:207], v[32:35]
	v_mfma_f32_16x16x32_bf16 v[20:23], v[180:183], v[212:215], v[20:23]
	v_mfma_f32_16x16x32_bf16 v[16:19], v[188:191], v[212:215], v[16:19]
	v_mfma_f32_16x16x32_bf16 v[4:7], v[180:183], v[220:223], v[4:7]
	v_mfma_f32_16x16x32_bf16 v[0:3], v[188:191], v[220:223], v[0:3]
	v_mfma_f32_16x16x32_bf16 v[52:55], v[184:187], v[200:203], v[52:55]
	v_mfma_f32_16x16x32_bf16 v[48:51], v[192:195], v[200:203], v[48:51]
	v_mfma_f32_16x16x32_bf16 v[36:39], v[184:187], v[208:211], v[36:39]
	v_mfma_f32_16x16x32_bf16 v[32:35], v[192:195], v[208:211], v[32:35]
	v_mfma_f32_16x16x32_bf16 v[20:23], v[184:187], v[216:219], v[20:23]
	v_mfma_f32_16x16x32_bf16 v[16:19], v[192:195], v[216:219], v[16:19]
	v_mfma_f32_16x16x32_bf16 v[4:7], v[184:187], v[224:227], v[4:7]
	v_mfma_f32_16x16x32_bf16 v[0:3], v[192:195], v[224:227], v[0:3]
	s_barrier
	s_add_i32 s90, 0, 0x18000
	v_add_u32_e32 v136, s90, v151
	s_add_i32 s91, 0, 0x1c000
	ds_read_b128 v[164:167], v136
	ds_read_b128 v[168:171], v136 offset:1024
	ds_read_b128 v[172:175], v136 offset:2048
	ds_read_b128 v[176:179], v136 offset:3072
	v_add_u32_e32 v136, s91, v151
	ds_read_b128 v[180:183], v136
	ds_read_b128 v[184:187], v136 offset:1024
	ds_read_b128 v[188:191], v136 offset:2048
	ds_read_b128 v[192:195], v136 offset:3072
	s_add_u32 s68, s68, 0x40000
	s_addc_u32 s69, s69, 0
	s_mov_b32 m0, s71
	v_lshl_add_u64 v[232:233], s[68:69], 0, v[128:129]
	ds_read_b128 v[196:199], v161 offset:32768
	ds_read_b128 v[200:203], v161 offset:33792
	ds_read_b128 v[204:207], v161 offset:34816
	ds_read_b128 v[208:211], v161 offset:35840
	ds_read_b128 v[212:215], v161 offset:36864
	ds_read_b128 v[216:219], v161 offset:37888
	ds_read_b128 v[220:223], v161 offset:38912
	ds_read_b128 v[224:227], v161 offset:39936
	global_load_lds_dwordx4 v[232:233], off
	v_lshl_add_u64 v[232:233], s[68:69], 0, v[132:133]
	s_mov_b32 m0, s72
	s_nop 0
	global_load_lds_dwordx4 v[232:233], off
	s_waitcnt vmcnt(8)
	s_waitcnt lgkmcnt(0)
	s_barrier
	s_waitcnt lgkmcnt(0)
	v_mfma_f32_16x16x32_bf16 v[124:127], v[164:167], v[196:199], v[124:127]
	v_mfma_f32_16x16x32_bf16 v[120:123], v[172:175], v[196:199], v[120:123]
	v_mfma_f32_16x16x32_bf16 v[108:111], v[164:167], v[204:207], v[108:111]
	v_mfma_f32_16x16x32_bf16 v[104:107], v[172:175], v[204:207], v[104:107]
	v_mfma_f32_16x16x32_bf16 v[92:95], v[164:167], v[212:215], v[92:95]
	v_mfma_f32_16x16x32_bf16 v[88:91], v[172:175], v[212:215], v[88:91]
	v_mfma_f32_16x16x32_bf16 v[76:79], v[164:167], v[220:223], v[76:79]
	v_mfma_f32_16x16x32_bf16 v[72:75], v[172:175], v[220:223], v[72:75]
	v_mfma_f32_16x16x32_bf16 v[124:127], v[168:171], v[200:203], v[124:127]
	v_mfma_f32_16x16x32_bf16 v[120:123], v[176:179], v[200:203], v[120:123]
	v_mfma_f32_16x16x32_bf16 v[108:111], v[168:171], v[208:211], v[108:111]
	v_mfma_f32_16x16x32_bf16 v[104:107], v[176:179], v[208:211], v[104:107]
	v_mfma_f32_16x16x32_bf16 v[92:95], v[168:171], v[216:219], v[92:95]
	v_mfma_f32_16x16x32_bf16 v[88:91], v[176:179], v[216:219], v[88:91]
	v_mfma_f32_16x16x32_bf16 v[76:79], v[168:171], v[224:227], v[76:79]
	v_mfma_f32_16x16x32_bf16 v[72:75], v[176:179], v[224:227], v[72:75]
	v_mfma_f32_16x16x32_bf16 v[116:119], v[180:183], v[196:199], v[116:119]
	v_mfma_f32_16x16x32_bf16 v[112:115], v[188:191], v[196:199], v[112:115]
	v_mfma_f32_16x16x32_bf16 v[100:103], v[180:183], v[204:207], v[100:103]
	v_mfma_f32_16x16x32_bf16 v[96:99], v[188:191], v[204:207], v[96:99]
	v_mfma_f32_16x16x32_bf16 v[84:87], v[180:183], v[212:215], v[84:87]
	v_mfma_f32_16x16x32_bf16 v[80:83], v[188:191], v[212:215], v[80:83]
	v_mfma_f32_16x16x32_bf16 v[68:71], v[180:183], v[220:223], v[68:71]
	v_mfma_f32_16x16x32_bf16 v[64:67], v[188:191], v[220:223], v[64:67]
	v_mfma_f32_16x16x32_bf16 v[116:119], v[184:187], v[200:203], v[116:119]
	v_mfma_f32_16x16x32_bf16 v[112:115], v[192:195], v[200:203], v[112:115]
	v_mfma_f32_16x16x32_bf16 v[100:103], v[184:187], v[208:211], v[100:103]
	v_mfma_f32_16x16x32_bf16 v[96:99], v[192:195], v[208:211], v[96:99]
	v_mfma_f32_16x16x32_bf16 v[84:87], v[184:187], v[216:219], v[84:87]
	v_mfma_f32_16x16x32_bf16 v[80:83], v[192:195], v[216:219], v[80:83]
	v_mfma_f32_16x16x32_bf16 v[68:71], v[184:187], v[224:227], v[68:71]
	v_mfma_f32_16x16x32_bf16 v[64:67], v[192:195], v[224:227], v[64:67]
	s_barrier
	s_add_i32 s68, s90, s35
	v_lshl_add_u64 v[148:149], v[148:149], 0, s[6:7]
	s_mov_b32 m0, s68
	ds_read_b128 v[196:199], v161 offset:49152
	ds_read_b128 v[200:203], v161 offset:50176
	ds_read_b128 v[204:207], v161 offset:51200
	ds_read_b128 v[208:211], v161 offset:52224
	ds_read_b128 v[212:215], v161 offset:53248
	ds_read_b128 v[216:219], v161 offset:54272
	ds_read_b128 v[220:223], v161 offset:55296
	ds_read_b128 v[224:227], v161 offset:56320
	global_load_lds_dwordx4 v[148:149], off
	s_add_i32 m0, s68, 0x2000
	s_add_u32 s66, s66, 0x40080
	v_lshl_add_u64 v[148:149], v[152:153], 0, s[6:7]
	s_addc_u32 s67, s67, 0
	s_add_i32 s68, s91, s35
	global_load_lds_dwordx4 v[148:149], off
	v_lshl_add_u64 v[148:149], s[66:67], 0, v[130:131]
	s_mov_b32 m0, s68
	s_nop 0
	global_load_lds_dwordx4 v[148:149], off
	v_lshl_add_u64 v[148:149], s[66:67], 0, v[134:135]
	s_add_i32 m0, s68, 0x2000
	s_nop 0
	global_load_lds_dwordx4 v[148:149], off
	v_lshl_add_u64 v[148:149], v[228:229], 0, s[6:7]
	s_mov_b32 m0, s75
	s_nop 0
	global_load_lds_dwordx4 v[148:149], off
	v_lshl_add_u64 v[148:149], v[230:231], 0, s[6:7]
	s_mov_b32 m0, s76
	s_nop 0
	global_load_lds_dwordx4 v[148:149], off
	s_waitcnt vmcnt(8)
	s_waitcnt lgkmcnt(0)
	s_barrier
	s_waitcnt lgkmcnt(0)
	v_mfma_f32_16x16x32_bf16 v[60:63], v[164:167], v[196:199], v[60:63]
	v_mfma_f32_16x16x32_bf16 v[56:59], v[172:175], v[196:199], v[56:59]
	v_mfma_f32_16x16x32_bf16 v[44:47], v[164:167], v[204:207], v[44:47]
	v_mfma_f32_16x16x32_bf16 v[40:43], v[172:175], v[204:207], v[40:43]
	v_mfma_f32_16x16x32_bf16 v[28:31], v[164:167], v[212:215], v[28:31]
	v_mfma_f32_16x16x32_bf16 v[24:27], v[172:175], v[212:215], v[24:27]
	v_mfma_f32_16x16x32_bf16 v[12:15], v[164:167], v[220:223], v[12:15]
	v_mfma_f32_16x16x32_bf16 v[8:11], v[172:175], v[220:223], v[8:11]
	v_mfma_f32_16x16x32_bf16 v[60:63], v[168:171], v[200:203], v[60:63]
	v_mfma_f32_16x16x32_bf16 v[56:59], v[176:179], v[200:203], v[56:59]
	v_mfma_f32_16x16x32_bf16 v[44:47], v[168:171], v[208:211], v[44:47]
	v_mfma_f32_16x16x32_bf16 v[40:43], v[176:179], v[208:211], v[40:43]
	v_mfma_f32_16x16x32_bf16 v[28:31], v[168:171], v[216:219], v[28:31]
	v_mfma_f32_16x16x32_bf16 v[24:27], v[176:179], v[216:219], v[24:27]
	v_mfma_f32_16x16x32_bf16 v[12:15], v[168:171], v[224:227], v[12:15]
	v_mfma_f32_16x16x32_bf16 v[8:11], v[176:179], v[224:227], v[8:11]
	v_mfma_f32_16x16x32_bf16 v[52:55], v[180:183], v[196:199], v[52:55]
	v_mfma_f32_16x16x32_bf16 v[48:51], v[188:191], v[196:199], v[48:51]
	v_mfma_f32_16x16x32_bf16 v[36:39], v[180:183], v[204:207], v[36:39]
	v_mfma_f32_16x16x32_bf16 v[32:35], v[188:191], v[204:207], v[32:35]
	v_mfma_f32_16x16x32_bf16 v[20:23], v[180:183], v[212:215], v[20:23]
	v_mfma_f32_16x16x32_bf16 v[16:19], v[188:191], v[212:215], v[16:19]
	v_mfma_f32_16x16x32_bf16 v[4:7], v[180:183], v[220:223], v[4:7]
	v_mfma_f32_16x16x32_bf16 v[0:3], v[188:191], v[220:223], v[0:3]
	v_mfma_f32_16x16x32_bf16 v[52:55], v[184:187], v[200:203], v[52:55]
	v_mfma_f32_16x16x32_bf16 v[48:51], v[192:195], v[200:203], v[48:51]
	v_mfma_f32_16x16x32_bf16 v[36:39], v[184:187], v[208:211], v[36:39]
	v_mfma_f32_16x16x32_bf16 v[32:35], v[192:195], v[208:211], v[32:35]
	v_mfma_f32_16x16x32_bf16 v[20:23], v[184:187], v[216:219], v[20:23]
	v_mfma_f32_16x16x32_bf16 v[16:19], v[192:195], v[216:219], v[16:19]
	v_mfma_f32_16x16x32_bf16 v[4:7], v[184:187], v[224:227], v[4:7]
	v_mfma_f32_16x16x32_bf16 v[0:3], v[192:195], v[224:227], v[0:3]
	s_barrier
	s_add_i32 s86, s86, 2
	s_add_u32 s64, s64, 0x100
	s_addc_u32 s65, s65, 0
	s_add_u32 s63, s63, 0x100
	s_addc_u32 s85, s85, 0
	s_cmp_gt_u32 s86, 13
	s_cbranch_scc0 .LBB0_297
	s_and_b64 vcc, exec, s[10:11]
	s_cbranch_vccz .LBB0_300
	s_barrier

.LBB0_445:
	ds_read_b128 v[150:153], v147
	ds_read_b128 v[154:157], v147 offset:1024
	ds_read_b128 v[158:161], v147 offset:2048
	ds_read_b128 v[162:165], v147 offset:3072
	ds_read_b128 v[166:169], v148
	ds_read_b128 v[170:173], v148 offset:1024
	ds_read_b128 v[174:177], v148 offset:2048
	ds_read_b128 v[178:181], v148 offset:3072
	s_add_i32 s73, s42, 2
	s_add_u32 s74, s40, 0x80
	s_addc_u32 s43, s41, 0
	s_cmp_eq_u32 s61, s42
	s_cselect_b32 s42, s6, s74
	s_cselect_b32 s43, s7, s43
	s_cselect_b32 s75, s39, s72
	s_cselect_b32 s74, s38, s71
	v_lshl_add_u64 v[214:215], s[40:41], 0, v[136:137]
	s_add_i32 m0, s9, 0xc000
	ds_read_b128 v[182:185], v149
	ds_read_b128 v[186:189], v149 offset:1024
	ds_read_b128 v[190:193], v149 offset:2048
	ds_read_b128 v[194:197], v149 offset:3072
	ds_read_b128 v[198:201], v149 offset:4096
	ds_read_b128 v[202:205], v149 offset:5120
	ds_read_b128 v[206:209], v149 offset:6144
	ds_read_b128 v[210:213], v149 offset:7168
	global_load_lds_dwordx4 v[214:215], off
	v_lshl_add_u64 v[214:215], s[40:41], 0, v[138:139]
	s_add_i32 m0, s9, 0xe000
	s_nop 0
	global_load_lds_dwordx4 v[214:215], off
	s_waitcnt vmcnt(8)
	s_waitcnt lgkmcnt(0)
	s_barrier
	s_waitcnt lgkmcnt(0)
	v_mfma_f32_16x16x32_bf16 v[124:127], v[150:153], v[182:185], v[124:127]
	v_mfma_f32_16x16x32_bf16 v[120:123], v[158:161], v[182:185], v[120:123]
	v_mfma_f32_16x16x32_bf16 v[108:111], v[150:153], v[190:193], v[108:111]
	v_mfma_f32_16x16x32_bf16 v[104:107], v[158:161], v[190:193], v[104:107]
	v_mfma_f32_16x16x32_bf16 v[92:95], v[150:153], v[198:201], v[92:95]
	v_mfma_f32_16x16x32_bf16 v[88:91], v[158:161], v[198:201], v[88:91]
	v_mfma_f32_16x16x32_bf16 v[76:79], v[150:153], v[206:209], v[76:79]
	v_mfma_f32_16x16x32_bf16 v[72:75], v[158:161], v[206:209], v[72:75]
	v_mfma_f32_16x16x32_bf16 v[124:127], v[154:157], v[186:189], v[124:127]
	v_mfma_f32_16x16x32_bf16 v[120:123], v[162:165], v[186:189], v[120:123]
	v_mfma_f32_16x16x32_bf16 v[108:111], v[154:157], v[194:197], v[108:111]
	v_mfma_f32_16x16x32_bf16 v[104:107], v[162:165], v[194:197], v[104:107]
	v_mfma_f32_16x16x32_bf16 v[92:95], v[154:157], v[202:205], v[92:95]
	v_mfma_f32_16x16x32_bf16 v[88:91], v[162:165], v[202:205], v[88:91]
	v_mfma_f32_16x16x32_bf16 v[76:79], v[154:157], v[210:213], v[76:79]
	v_mfma_f32_16x16x32_bf16 v[72:75], v[162:165], v[210:213], v[72:75]
	v_mfma_f32_16x16x32_bf16 v[116:119], v[166:169], v[182:185], v[116:119]
	v_mfma_f32_16x16x32_bf16 v[112:115], v[174:177], v[182:185], v[112:115]
	v_mfma_f32_16x16x32_bf16 v[100:103], v[166:169], v[190:193], v[100:103]
	v_mfma_f32_16x16x32_bf16 v[96:99], v[174:177], v[190:193], v[96:99]
	v_mfma_f32_16x16x32_bf16 v[84:87], v[166:169], v[198:201], v[84:87]
	v_mfma_f32_16x16x32_bf16 v[80:83], v[174:177], v[198:201], v[80:83]
	v_mfma_f32_16x16x32_bf16 v[68:71], v[166:169], v[206:209], v[68:71]
	v_mfma_f32_16x16x32_bf16 v[64:67], v[174:177], v[206:209], v[64:67]
	v_mfma_f32_16x16x32_bf16 v[116:119], v[170:173], v[186:189], v[116:119]
	v_mfma_f32_16x16x32_bf16 v[112:115], v[178:181], v[186:189], v[112:115]
	v_mfma_f32_16x16x32_bf16 v[100:103], v[170:173], v[194:197], v[100:103]
	v_mfma_f32_16x16x32_bf16 v[96:99], v[178:181], v[194:197], v[96:99]
	v_mfma_f32_16x16x32_bf16 v[84:87], v[170:173], v[202:205], v[84:87]
	v_mfma_f32_16x16x32_bf16 v[80:83], v[178:181], v[202:205], v[80:83]
	v_mfma_f32_16x16x32_bf16 v[68:71], v[170:173], v[210:213], v[68:71]
	v_mfma_f32_16x16x32_bf16 v[64:67], v[178:181], v[210:213], v[64:67]
	s_barrier
	s_add_i32 s76, s64, s49
	v_lshl_add_u64 v[214:215], s[74:75], 0, v[132:133]
	s_mov_b32 m0, s76
	ds_read_b128 v[182:185], v149 offset:16384
	ds_read_b128 v[186:189], v149 offset:17408
	ds_read_b128 v[190:193], v149 offset:18432
	ds_read_b128 v[194:197], v149 offset:19456
	ds_read_b128 v[198:201], v149 offset:20480
	ds_read_b128 v[202:205], v149 offset:21504
	ds_read_b128 v[206:209], v149 offset:22528
	ds_read_b128 v[210:213], v149 offset:23552
	global_load_lds_dwordx4 v[214:215], off
	s_add_i32 m0, s76, 0x2000
	v_lshl_add_u64 v[216:217], s[74:75], 0, v[128:129]
	s_add_u32 s74, s74, s12
	s_addc_u32 s75, s75, s13
	s_add_i32 s76, s65, s49
	global_load_lds_dwordx4 v[216:217], off
	v_lshl_add_u64 v[218:219], s[74:75], 0, v[132:133]
	s_mov_b32 m0, s76
	v_lshl_add_u64 v[220:221], s[74:75], 0, v[128:129]
	global_load_lds_dwordx4 v[218:219], off
	s_add_i32 m0, s76, 0x2000
	v_lshl_add_u64 v[222:223], s[42:43], 0, v[134:135]
	global_load_lds_dwordx4 v[220:221], off
	s_mov_b32 m0, s9
	v_lshl_add_u64 v[224:225], s[42:43], 0, v[130:131]
	global_load_lds_dwordx4 v[222:223], off
	s_mov_b32 m0, s54
	s_nop 0
	global_load_lds_dwordx4 v[224:225], off
	s_waitcnt vmcnt(8)
	s_waitcnt lgkmcnt(0)
	s_barrier
	s_waitcnt lgkmcnt(0)
	v_mfma_f32_16x16x32_bf16 v[60:63], v[150:153], v[182:185], v[60:63]
	v_mfma_f32_16x16x32_bf16 v[56:59], v[158:161], v[182:185], v[56:59]
	v_mfma_f32_16x16x32_bf16 v[44:47], v[150:153], v[190:193], v[44:47]
	v_mfma_f32_16x16x32_bf16 v[40:43], v[158:161], v[190:193], v[40:43]
	v_mfma_f32_16x16x32_bf16 v[28:31], v[150:153], v[198:201], v[28:31]
	v_mfma_f32_16x16x32_bf16 v[24:27], v[158:161], v[198:201], v[24:27]
	v_mfma_f32_16x16x32_bf16 v[12:15], v[150:153], v[206:209], v[12:15]
	v_mfma_f32_16x16x32_bf16 v[8:11], v[158:161], v[206:209], v[8:11]
	v_mfma_f32_16x16x32_bf16 v[60:63], v[154:157], v[186:189], v[60:63]
	v_mfma_f32_16x16x32_bf16 v[56:59], v[162:165], v[186:189], v[56:59]
	v_mfma_f32_16x16x32_bf16 v[44:47], v[154:157], v[194:197], v[44:47]
	v_mfma_f32_16x16x32_bf16 v[40:43], v[162:165], v[194:197], v[40:43]
	v_mfma_f32_16x16x32_bf16 v[28:31], v[154:157], v[202:205], v[28:31]
	v_mfma_f32_16x16x32_bf16 v[24:27], v[162:165], v[202:205], v[24:27]
	v_mfma_f32_16x16x32_bf16 v[12:15], v[154:157], v[210:213], v[12:15]
	v_mfma_f32_16x16x32_bf16 v[8:11], v[162:165], v[210:213], v[8:11]
	v_mfma_f32_16x16x32_bf16 v[52:55], v[166:169], v[182:185], v[52:55]
	v_mfma_f32_16x16x32_bf16 v[48:51], v[174:177], v[182:185], v[48:51]
	v_mfma_f32_16x16x32_bf16 v[36:39], v[166:169], v[190:193], v[36:39]
	v_mfma_f32_16x16x32_bf16 v[32:35], v[174:177], v[190:193], v[32:35]
	v_mfma_f32_16x16x32_bf16 v[20:23], v[166:169], v[198:201], v[20:23]
	v_mfma_f32_16x16x32_bf16 v[16:19], v[174:177], v[198:201], v[16:19]
	v_mfma_f32_16x16x32_bf16 v[4:7], v[166:169], v[206:209], v[4:7]
	v_mfma_f32_16x16x32_bf16 v[0:3], v[174:177], v[206:209], v[0:3]
	v_mfma_f32_16x16x32_bf16 v[52:55], v[170:173], v[186:189], v[52:55]
	v_mfma_f32_16x16x32_bf16 v[48:51], v[178:181], v[186:189], v[48:51]
	v_mfma_f32_16x16x32_bf16 v[36:39], v[170:173], v[194:197], v[36:39]
	v_mfma_f32_16x16x32_bf16 v[32:35], v[178:181], v[194:197], v[32:35]
	v_mfma_f32_16x16x32_bf16 v[20:23], v[170:173], v[202:205], v[20:23]
	v_mfma_f32_16x16x32_bf16 v[16:19], v[178:181], v[202:205], v[16:19]
	v_mfma_f32_16x16x32_bf16 v[4:7], v[170:173], v[210:213], v[4:7]
	v_mfma_f32_16x16x32_bf16 v[0:3], v[178:181], v[210:213], v[0:3]
	s_barrier
	s_add_i32 s74, 0, 0x18000
	s_add_i32 s75, 0, 0x1c000
	v_add_u32_e32 v162, s74, v145
	v_add_u32_e32 v178, s75, v145
	ds_read_b128 v[150:153], v162
	ds_read_b128 v[154:157], v162 offset:1024
	ds_read_b128 v[158:161], v162 offset:2048
	ds_read_b128 v[162:165], v162 offset:3072
	ds_read_b128 v[166:169], v178
	ds_read_b128 v[170:173], v178 offset:1024
	ds_read_b128 v[174:177], v178 offset:2048
	ds_read_b128 v[178:181], v178 offset:3072
	s_add_u32 s42, s42, s12
	s_addc_u32 s43, s43, s13
	s_mov_b32 m0, s55
	v_lshl_add_u64 v[226:227], s[42:43], 0, v[134:135]
	ds_read_b128 v[182:185], v149 offset:32768
	ds_read_b128 v[186:189], v149 offset:33792
	ds_read_b128 v[190:193], v149 offset:34816
	ds_read_b128 v[194:197], v149 offset:35840
	ds_read_b128 v[198:201], v149 offset:36864
	ds_read_b128 v[202:205], v149 offset:37888
	ds_read_b128 v[206:209], v149 offset:38912
	ds_read_b128 v[210:213], v149 offset:39936
	global_load_lds_dwordx4 v[226:227], off
	v_lshl_add_u64 v[226:227], s[42:43], 0, v[130:131]
	s_mov_b32 m0, s56
	s_nop 0
	global_load_lds_dwordx4 v[226:227], off
	s_waitcnt vmcnt(8)
	s_waitcnt lgkmcnt(0)
	s_barrier
	s_waitcnt lgkmcnt(0)
	v_mfma_f32_16x16x32_bf16 v[124:127], v[150:153], v[182:185], v[124:127]
	v_mfma_f32_16x16x32_bf16 v[120:123], v[158:161], v[182:185], v[120:123]
	v_mfma_f32_16x16x32_bf16 v[108:111], v[150:153], v[190:193], v[108:111]
	v_mfma_f32_16x16x32_bf16 v[104:107], v[158:161], v[190:193], v[104:107]
	v_mfma_f32_16x16x32_bf16 v[92:95], v[150:153], v[198:201], v[92:95]
	v_mfma_f32_16x16x32_bf16 v[88:91], v[158:161], v[198:201], v[88:91]
	v_mfma_f32_16x16x32_bf16 v[76:79], v[150:153], v[206:209], v[76:79]
	v_mfma_f32_16x16x32_bf16 v[72:75], v[158:161], v[206:209], v[72:75]
	v_mfma_f32_16x16x32_bf16 v[124:127], v[154:157], v[186:189], v[124:127]
	v_mfma_f32_16x16x32_bf16 v[120:123], v[162:165], v[186:189], v[120:123]
	v_mfma_f32_16x16x32_bf16 v[108:111], v[154:157], v[194:197], v[108:111]
	v_mfma_f32_16x16x32_bf16 v[104:107], v[162:165], v[194:197], v[104:107]
	v_mfma_f32_16x16x32_bf16 v[92:95], v[154:157], v[202:205], v[92:95]
	v_mfma_f32_16x16x32_bf16 v[88:91], v[162:165], v[202:205], v[88:91]
	v_mfma_f32_16x16x32_bf16 v[76:79], v[154:157], v[210:213], v[76:79]
	v_mfma_f32_16x16x32_bf16 v[72:75], v[162:165], v[210:213], v[72:75]
	v_mfma_f32_16x16x32_bf16 v[116:119], v[166:169], v[182:185], v[116:119]
	v_mfma_f32_16x16x32_bf16 v[112:115], v[174:177], v[182:185], v[112:115]
	v_mfma_f32_16x16x32_bf16 v[100:103], v[166:169], v[190:193], v[100:103]
	v_mfma_f32_16x16x32_bf16 v[96:99], v[174:177], v[190:193], v[96:99]
	v_mfma_f32_16x16x32_bf16 v[84:87], v[166:169], v[198:201], v[84:87]
	v_mfma_f32_16x16x32_bf16 v[80:83], v[174:177], v[198:201], v[80:83]
	v_mfma_f32_16x16x32_bf16 v[68:71], v[166:169], v[206:209], v[68:71]
	v_mfma_f32_16x16x32_bf16 v[64:67], v[174:177], v[206:209], v[64:67]
	v_mfma_f32_16x16x32_bf16 v[116:119], v[170:173], v[186:189], v[116:119]
	v_mfma_f32_16x16x32_bf16 v[112:115], v[178:181], v[186:189], v[112:115]
	v_mfma_f32_16x16x32_bf16 v[100:103], v[170:173], v[194:197], v[100:103]
	v_mfma_f32_16x16x32_bf16 v[96:99], v[178:181], v[194:197], v[96:99]
	v_mfma_f32_16x16x32_bf16 v[84:87], v[170:173], v[202:205], v[84:87]
	v_mfma_f32_16x16x32_bf16 v[80:83], v[178:181], v[202:205], v[80:83]
	v_mfma_f32_16x16x32_bf16 v[68:71], v[170:173], v[210:213], v[68:71]
	v_mfma_f32_16x16x32_bf16 v[64:67], v[178:181], v[210:213], v[64:67]
	s_barrier
	s_add_i32 s42, s74, s49
	v_lshl_add_u64 v[214:215], v[214:215], 0, s[20:21]
	s_mov_b32 m0, s42
	ds_read_b128 v[182:185], v149 offset:49152
	ds_read_b128 v[186:189], v149 offset:50176
	ds_read_b128 v[190:193], v149 offset:51200
	ds_read_b128 v[194:197], v149 offset:52224
	ds_read_b128 v[198:201], v149 offset:53248
	ds_read_b128 v[202:205], v149 offset:54272
	ds_read_b128 v[206:209], v149 offset:55296
	ds_read_b128 v[210:213], v149 offset:56320
	global_load_lds_dwordx4 v[214:215], off
	v_lshl_add_u64 v[214:215], v[216:217], 0, s[20:21]
	s_add_i32 m0, s42, 0x2000
	s_add_i32 s42, s75, s49
	global_load_lds_dwordx4 v[214:215], off
	v_lshl_add_u64 v[214:215], v[218:219], 0, s[20:21]
	s_mov_b32 m0, s42
	s_nop 0
	global_load_lds_dwordx4 v[214:215], off
	v_lshl_add_u64 v[214:215], v[220:221], 0, s[20:21]
	s_add_i32 m0, s42, 0x2000
	s_nop 0
	global_load_lds_dwordx4 v[214:215], off
	v_lshl_add_u64 v[214:215], v[222:223], 0, s[20:21]
	s_mov_b32 m0, s58
	s_nop 0
	global_load_lds_dwordx4 v[214:215], off
	v_lshl_add_u64 v[214:215], v[224:225], 0, s[20:21]
	s_mov_b32 m0, s59
	s_nop 0
	global_load_lds_dwordx4 v[214:215], off
	s_waitcnt vmcnt(8)
	s_waitcnt lgkmcnt(0)
	s_barrier
	s_waitcnt lgkmcnt(0)
	v_mfma_f32_16x16x32_bf16 v[60:63], v[150:153], v[182:185], v[60:63]
	v_mfma_f32_16x16x32_bf16 v[56:59], v[158:161], v[182:185], v[56:59]
	v_mfma_f32_16x16x32_bf16 v[44:47], v[150:153], v[190:193], v[44:47]
	v_mfma_f32_16x16x32_bf16 v[40:43], v[158:161], v[190:193], v[40:43]
	v_mfma_f32_16x16x32_bf16 v[28:31], v[150:153], v[198:201], v[28:31]
	v_mfma_f32_16x16x32_bf16 v[24:27], v[158:161], v[198:201], v[24:27]
	v_mfma_f32_16x16x32_bf16 v[12:15], v[150:153], v[206:209], v[12:15]
	v_mfma_f32_16x16x32_bf16 v[8:11], v[158:161], v[206:209], v[8:11]
	v_mfma_f32_16x16x32_bf16 v[60:63], v[154:157], v[186:189], v[60:63]
	v_mfma_f32_16x16x32_bf16 v[56:59], v[162:165], v[186:189], v[56:59]
	v_mfma_f32_16x16x32_bf16 v[44:47], v[154:157], v[194:197], v[44:47]
	v_mfma_f32_16x16x32_bf16 v[40:43], v[162:165], v[194:197], v[40:43]
	v_mfma_f32_16x16x32_bf16 v[28:31], v[154:157], v[202:205], v[28:31]
	v_mfma_f32_16x16x32_bf16 v[24:27], v[162:165], v[202:205], v[24:27]
	v_mfma_f32_16x16x32_bf16 v[12:15], v[154:157], v[210:213], v[12:15]
	v_mfma_f32_16x16x32_bf16 v[8:11], v[162:165], v[210:213], v[8:11]
	v_mfma_f32_16x16x32_bf16 v[52:55], v[166:169], v[182:185], v[52:55]
	v_mfma_f32_16x16x32_bf16 v[48:51], v[174:177], v[182:185], v[48:51]
	v_mfma_f32_16x16x32_bf16 v[36:39], v[166:169], v[190:193], v[36:39]
	v_mfma_f32_16x16x32_bf16 v[32:35], v[174:177], v[190:193], v[32:35]
	v_mfma_f32_16x16x32_bf16 v[20:23], v[166:169], v[198:201], v[20:23]
	v_mfma_f32_16x16x32_bf16 v[16:19], v[174:177], v[198:201], v[16:19]
	v_mfma_f32_16x16x32_bf16 v[4:7], v[166:169], v[206:209], v[4:7]
	v_mfma_f32_16x16x32_bf16 v[0:3], v[174:177], v[206:209], v[0:3]
	v_mfma_f32_16x16x32_bf16 v[52:55], v[170:173], v[186:189], v[52:55]
	v_mfma_f32_16x16x32_bf16 v[48:51], v[178:181], v[186:189], v[48:51]
	v_mfma_f32_16x16x32_bf16 v[36:39], v[170:173], v[194:197], v[36:39]
	v_mfma_f32_16x16x32_bf16 v[32:35], v[178:181], v[194:197], v[32:35]
	v_mfma_f32_16x16x32_bf16 v[20:23], v[170:173], v[202:205], v[20:23]
	v_mfma_f32_16x16x32_bf16 v[16:19], v[178:181], v[202:205], v[16:19]
	v_mfma_f32_16x16x32_bf16 v[4:7], v[170:173], v[210:213], v[4:7]
	v_mfma_f32_16x16x32_bf16 v[0:3], v[178:181], v[210:213], v[0:3]
	s_barrier
	s_add_u32 s40, s40, 0x100
	s_addc_u32 s41, s41, 0
	s_add_u32 s71, s71, 0x100
	s_addc_u32 s72, s72, 0
	s_cmp_ge_i32 s73, s60
	s_mov_b32 s42, s73
	s_cbranch_scc0 .LBB0_445

.LBB0_474:
	ds_read_b128 v[150:153], v147
	ds_read_b128 v[154:157], v147 offset:1024
	ds_read_b128 v[158:161], v147 offset:2048
	ds_read_b128 v[162:165], v147 offset:3072
	ds_read_b128 v[166:169], v148
	ds_read_b128 v[170:173], v148 offset:1024
	ds_read_b128 v[174:177], v148 offset:2048
	ds_read_b128 v[178:181], v148 offset:3072
	s_add_i32 s93, s64, 2
	s_add_u32 s94, s62, 0x80
	s_addc_u32 s65, s63, 0
	s_cmp_eq_u32 s75, s64
	s_cselect_b32 s64, s4, s94
	s_cselect_b32 s65, s5, s65
	s_cselect_b32 s95, s61, s92
	s_cselect_b32 s94, s60, s91
	v_lshl_add_u64 v[214:215], s[62:63], 0, v[136:137]
	s_add_i32 m0, s69, 0xc000
	ds_read_b128 v[182:185], v149
	ds_read_b128 v[186:189], v149 offset:1024
	ds_read_b128 v[190:193], v149 offset:2048
	ds_read_b128 v[194:197], v149 offset:3072
	ds_read_b128 v[198:201], v149 offset:4096
	ds_read_b128 v[202:205], v149 offset:5120
	ds_read_b128 v[206:209], v149 offset:6144
	ds_read_b128 v[210:213], v149 offset:7168
	global_load_lds_dwordx4 v[214:215], off
	v_lshl_add_u64 v[214:215], s[62:63], 0, v[138:139]
	s_add_i32 m0, s69, 0xe000
	s_nop 0
	global_load_lds_dwordx4 v[214:215], off
	s_waitcnt vmcnt(8)
	s_waitcnt lgkmcnt(0)
	s_barrier
	s_waitcnt lgkmcnt(0)
	v_mfma_f32_16x16x32_bf16 v[120:123], v[150:153], v[182:185], v[120:123]
	v_mfma_f32_16x16x32_bf16 v[124:127], v[158:161], v[182:185], v[124:127]
	v_mfma_f32_16x16x32_bf16 v[108:111], v[150:153], v[190:193], v[108:111]
	v_mfma_f32_16x16x32_bf16 v[104:107], v[158:161], v[190:193], v[104:107]
	v_mfma_f32_16x16x32_bf16 v[92:95], v[150:153], v[198:201], v[92:95]
	v_mfma_f32_16x16x32_bf16 v[88:91], v[158:161], v[198:201], v[88:91]
	v_mfma_f32_16x16x32_bf16 v[76:79], v[150:153], v[206:209], v[76:79]
	v_mfma_f32_16x16x32_bf16 v[72:75], v[158:161], v[206:209], v[72:75]
	v_mfma_f32_16x16x32_bf16 v[120:123], v[154:157], v[186:189], v[120:123]
	v_mfma_f32_16x16x32_bf16 v[124:127], v[162:165], v[186:189], v[124:127]
	v_mfma_f32_16x16x32_bf16 v[108:111], v[154:157], v[194:197], v[108:111]
	v_mfma_f32_16x16x32_bf16 v[104:107], v[162:165], v[194:197], v[104:107]
	v_mfma_f32_16x16x32_bf16 v[92:95], v[154:157], v[202:205], v[92:95]
	v_mfma_f32_16x16x32_bf16 v[88:91], v[162:165], v[202:205], v[88:91]
	v_mfma_f32_16x16x32_bf16 v[76:79], v[154:157], v[210:213], v[76:79]
	v_mfma_f32_16x16x32_bf16 v[72:75], v[162:165], v[210:213], v[72:75]
	v_mfma_f32_16x16x32_bf16 v[116:119], v[166:169], v[182:185], v[116:119]
	v_mfma_f32_16x16x32_bf16 v[112:115], v[174:177], v[182:185], v[112:115]
	v_mfma_f32_16x16x32_bf16 v[100:103], v[166:169], v[190:193], v[100:103]
	v_mfma_f32_16x16x32_bf16 v[96:99], v[174:177], v[190:193], v[96:99]
	v_mfma_f32_16x16x32_bf16 v[84:87], v[166:169], v[198:201], v[84:87]
	v_mfma_f32_16x16x32_bf16 v[80:83], v[174:177], v[198:201], v[80:83]
	v_mfma_f32_16x16x32_bf16 v[68:71], v[166:169], v[206:209], v[68:71]
	v_mfma_f32_16x16x32_bf16 v[64:67], v[174:177], v[206:209], v[64:67]
	v_mfma_f32_16x16x32_bf16 v[116:119], v[170:173], v[186:189], v[116:119]
	v_mfma_f32_16x16x32_bf16 v[112:115], v[178:181], v[186:189], v[112:115]
	v_mfma_f32_16x16x32_bf16 v[100:103], v[170:173], v[194:197], v[100:103]
	v_mfma_f32_16x16x32_bf16 v[96:99], v[178:181], v[194:197], v[96:99]
	v_mfma_f32_16x16x32_bf16 v[84:87], v[170:173], v[202:205], v[84:87]
	v_mfma_f32_16x16x32_bf16 v[80:83], v[178:181], v[202:205], v[80:83]
	v_mfma_f32_16x16x32_bf16 v[68:71], v[170:173], v[210:213], v[68:71]
	v_mfma_f32_16x16x32_bf16 v[64:67], v[178:181], v[210:213], v[64:67]
	s_barrier
	s_add_i32 s96, s80, s68
	v_lshl_add_u64 v[214:215], s[94:95], 0, v[130:131]
	s_mov_b32 m0, s96
	ds_read_b128 v[182:185], v149 offset:16384
	ds_read_b128 v[186:189], v149 offset:17408
	ds_read_b128 v[190:193], v149 offset:18432
	ds_read_b128 v[194:197], v149 offset:19456
	ds_read_b128 v[198:201], v149 offset:20480
	ds_read_b128 v[202:205], v149 offset:21504
	ds_read_b128 v[206:209], v149 offset:22528
	ds_read_b128 v[210:213], v149 offset:23552
	global_load_lds_dwordx4 v[214:215], off
	s_add_i32 m0, s96, 0x2000
	v_lshl_add_u64 v[216:217], s[94:95], 0, v[134:135]
	s_add_u32 s94, s94, s6
	s_addc_u32 s95, s95, s7
	s_add_i32 s96, s81, s68
	global_load_lds_dwordx4 v[216:217], off
	v_lshl_add_u64 v[218:219], s[94:95], 0, v[130:131]
	s_mov_b32 m0, s96
	v_lshl_add_u64 v[220:221], s[94:95], 0, v[134:135]
	global_load_lds_dwordx4 v[218:219], off
	s_add_i32 m0, s96, 0x2000
	v_lshl_add_u64 v[222:223], s[64:65], 0, v[128:129]
	global_load_lds_dwordx4 v[220:221], off
	s_mov_b32 m0, s69
	v_lshl_add_u64 v[224:225], s[64:65], 0, v[132:133]
	global_load_lds_dwordx4 v[222:223], off
	s_mov_b32 m0, s8
	s_nop 0
	global_load_lds_dwordx4 v[224:225], off
	s_waitcnt vmcnt(8)
	s_waitcnt lgkmcnt(0)
	s_barrier
	s_waitcnt lgkmcnt(0)
	v_mfma_f32_16x16x32_bf16 v[60:63], v[150:153], v[182:185], v[60:63]
	v_mfma_f32_16x16x32_bf16 v[56:59], v[158:161], v[182:185], v[56:59]
	v_mfma_f32_16x16x32_bf16 v[44:47], v[150:153], v[190:193], v[44:47]
	v_mfma_f32_16x16x32_bf16 v[40:43], v[158:161], v[190:193], v[40:43]
	v_mfma_f32_16x16x32_bf16 v[28:31], v[150:153], v[198:201], v[28:31]
	v_mfma_f32_16x16x32_bf16 v[24:27], v[158:161], v[198:201], v[24:27]
	v_mfma_f32_16x16x32_bf16 v[12:15], v[150:153], v[206:209], v[12:15]
	v_mfma_f32_16x16x32_bf16 v[8:11], v[158:161], v[206:209], v[8:11]
	v_mfma_f32_16x16x32_bf16 v[60:63], v[154:157], v[186:189], v[60:63]
	v_mfma_f32_16x16x32_bf16 v[56:59], v[162:165], v[186:189], v[56:59]
	v_mfma_f32_16x16x32_bf16 v[44:47], v[154:157], v[194:197], v[44:47]
	v_mfma_f32_16x16x32_bf16 v[40:43], v[162:165], v[194:197], v[40:43]
	v_mfma_f32_16x16x32_bf16 v[28:31], v[154:157], v[202:205], v[28:31]
	v_mfma_f32_16x16x32_bf16 v[24:27], v[162:165], v[202:205], v[24:27]
	v_mfma_f32_16x16x32_bf16 v[12:15], v[154:157], v[210:213], v[12:15]
	v_mfma_f32_16x16x32_bf16 v[8:11], v[162:165], v[210:213], v[8:11]
	v_mfma_f32_16x16x32_bf16 v[52:55], v[166:169], v[182:185], v[52:55]
	v_mfma_f32_16x16x32_bf16 v[48:51], v[174:177], v[182:185], v[48:51]
	v_mfma_f32_16x16x32_bf16 v[36:39], v[166:169], v[190:193], v[36:39]
	v_mfma_f32_16x16x32_bf16 v[32:35], v[174:177], v[190:193], v[32:35]
	v_mfma_f32_16x16x32_bf16 v[20:23], v[166:169], v[198:201], v[20:23]
	v_mfma_f32_16x16x32_bf16 v[16:19], v[174:177], v[198:201], v[16:19]
	v_mfma_f32_16x16x32_bf16 v[4:7], v[166:169], v[206:209], v[4:7]
	v_mfma_f32_16x16x32_bf16 v[0:3], v[174:177], v[206:209], v[0:3]
	v_mfma_f32_16x16x32_bf16 v[52:55], v[170:173], v[186:189], v[52:55]
	v_mfma_f32_16x16x32_bf16 v[48:51], v[178:181], v[186:189], v[48:51]
	v_mfma_f32_16x16x32_bf16 v[36:39], v[170:173], v[194:197], v[36:39]
	v_mfma_f32_16x16x32_bf16 v[32:35], v[178:181], v[194:197], v[32:35]
	v_mfma_f32_16x16x32_bf16 v[20:23], v[170:173], v[202:205], v[20:23]
	v_mfma_f32_16x16x32_bf16 v[16:19], v[178:181], v[202:205], v[16:19]
	v_mfma_f32_16x16x32_bf16 v[4:7], v[170:173], v[210:213], v[4:7]
	v_mfma_f32_16x16x32_bf16 v[0:3], v[178:181], v[210:213], v[0:3]
	s_barrier
	s_add_i32 s94, 0, 0x18000
	s_add_i32 s95, 0, 0x1c000
	v_add_u32_e32 v162, s94, v145
	v_add_u32_e32 v178, s95, v145
	ds_read_b128 v[150:153], v162
	ds_read_b128 v[154:157], v162 offset:1024
	ds_read_b128 v[158:161], v162 offset:2048
	ds_read_b128 v[162:165], v162 offset:3072
	ds_read_b128 v[166:169], v178
	ds_read_b128 v[170:173], v178 offset:1024
	ds_read_b128 v[174:177], v178 offset:2048
	ds_read_b128 v[178:181], v178 offset:3072
	s_add_u32 s64, s64, s6
	s_addc_u32 s65, s65, s7
	s_mov_b32 m0, s9
	v_lshl_add_u64 v[226:227], s[64:65], 0, v[128:129]
	ds_read_b128 v[182:185], v149 offset:32768
	ds_read_b128 v[186:189], v149 offset:33792
	ds_read_b128 v[190:193], v149 offset:34816
	ds_read_b128 v[194:197], v149 offset:35840
	ds_read_b128 v[198:201], v149 offset:36864
	ds_read_b128 v[202:205], v149 offset:37888
	ds_read_b128 v[206:209], v149 offset:38912
	ds_read_b128 v[210:213], v149 offset:39936
	global_load_lds_dwordx4 v[226:227], off
	v_lshl_add_u64 v[226:227], s[64:65], 0, v[132:133]
	s_mov_b32 m0, s70
	s_nop 0
	global_load_lds_dwordx4 v[226:227], off
	s_waitcnt vmcnt(8)
	s_waitcnt lgkmcnt(0)
	s_barrier
	s_waitcnt lgkmcnt(0)
	v_mfma_f32_16x16x32_bf16 v[120:123], v[150:153], v[182:185], v[120:123]
	v_mfma_f32_16x16x32_bf16 v[124:127], v[158:161], v[182:185], v[124:127]
	v_mfma_f32_16x16x32_bf16 v[108:111], v[150:153], v[190:193], v[108:111]
	v_mfma_f32_16x16x32_bf16 v[104:107], v[158:161], v[190:193], v[104:107]
	v_mfma_f32_16x16x32_bf16 v[92:95], v[150:153], v[198:201], v[92:95]
	v_mfma_f32_16x16x32_bf16 v[88:91], v[158:161], v[198:201], v[88:91]
	v_mfma_f32_16x16x32_bf16 v[76:79], v[150:153], v[206:209], v[76:79]
	v_mfma_f32_16x16x32_bf16 v[72:75], v[158:161], v[206:209], v[72:75]
	v_mfma_f32_16x16x32_bf16 v[120:123], v[154:157], v[186:189], v[120:123]
	v_mfma_f32_16x16x32_bf16 v[124:127], v[162:165], v[186:189], v[124:127]
	v_mfma_f32_16x16x32_bf16 v[108:111], v[154:157], v[194:197], v[108:111]
	v_mfma_f32_16x16x32_bf16 v[104:107], v[162:165], v[194:197], v[104:107]
	v_mfma_f32_16x16x32_bf16 v[92:95], v[154:157], v[202:205], v[92:95]
	v_mfma_f32_16x16x32_bf16 v[88:91], v[162:165], v[202:205], v[88:91]
	v_mfma_f32_16x16x32_bf16 v[76:79], v[154:157], v[210:213], v[76:79]
	v_mfma_f32_16x16x32_bf16 v[72:75], v[162:165], v[210:213], v[72:75]
	v_mfma_f32_16x16x32_bf16 v[116:119], v[166:169], v[182:185], v[116:119]
	v_mfma_f32_16x16x32_bf16 v[112:115], v[174:177], v[182:185], v[112:115]
	v_mfma_f32_16x16x32_bf16 v[100:103], v[166:169], v[190:193], v[100:103]
	v_mfma_f32_16x16x32_bf16 v[96:99], v[174:177], v[190:193], v[96:99]
	v_mfma_f32_16x16x32_bf16 v[84:87], v[166:169], v[198:201], v[84:87]
	v_mfma_f32_16x16x32_bf16 v[80:83], v[174:177], v[198:201], v[80:83]
	v_mfma_f32_16x16x32_bf16 v[68:71], v[166:169], v[206:209], v[68:71]
	v_mfma_f32_16x16x32_bf16 v[64:67], v[174:177], v[206:209], v[64:67]
	v_mfma_f32_16x16x32_bf16 v[116:119], v[170:173], v[186:189], v[116:119]
	v_mfma_f32_16x16x32_bf16 v[112:115], v[178:181], v[186:189], v[112:115]
	v_mfma_f32_16x16x32_bf16 v[100:103], v[170:173], v[194:197], v[100:103]
	v_mfma_f32_16x16x32_bf16 v[96:99], v[178:181], v[194:197], v[96:99]
	v_mfma_f32_16x16x32_bf16 v[84:87], v[170:173], v[202:205], v[84:87]
	v_mfma_f32_16x16x32_bf16 v[80:83], v[178:181], v[202:205], v[80:83]
	v_mfma_f32_16x16x32_bf16 v[68:71], v[170:173], v[210:213], v[68:71]
	v_mfma_f32_16x16x32_bf16 v[64:67], v[178:181], v[210:213], v[64:67]
	s_barrier
	s_add_i32 s64, s94, s68
	v_lshl_add_u64 v[214:215], v[214:215], 0, s[38:39]
	s_mov_b32 m0, s64
	ds_read_b128 v[182:185], v149 offset:49152
	ds_read_b128 v[186:189], v149 offset:50176
	ds_read_b128 v[190:193], v149 offset:51200
	ds_read_b128 v[194:197], v149 offset:52224
	ds_read_b128 v[198:201], v149 offset:53248
	ds_read_b128 v[202:205], v149 offset:54272
	ds_read_b128 v[206:209], v149 offset:55296
	ds_read_b128 v[210:213], v149 offset:56320
	global_load_lds_dwordx4 v[214:215], off
	v_lshl_add_u64 v[214:215], v[216:217], 0, s[38:39]
	s_add_i32 m0, s64, 0x2000
	s_add_i32 s64, s95, s68
	global_load_lds_dwordx4 v[214:215], off
	v_lshl_add_u64 v[214:215], v[218:219], 0, s[38:39]
	s_mov_b32 m0, s64
	s_nop 0
	global_load_lds_dwordx4 v[214:215], off
	v_lshl_add_u64 v[214:215], v[220:221], 0, s[38:39]
	s_add_i32 m0, s64, 0x2000
	s_nop 0
	global_load_lds_dwordx4 v[214:215], off
	v_lshl_add_u64 v[214:215], v[222:223], 0, s[38:39]
	s_mov_b32 m0, s72
	s_nop 0
	global_load_lds_dwordx4 v[214:215], off
	v_lshl_add_u64 v[214:215], v[224:225], 0, s[38:39]
	s_mov_b32 m0, s73
	s_nop 0
	global_load_lds_dwordx4 v[214:215], off
	s_waitcnt vmcnt(8)
	s_waitcnt lgkmcnt(0)
	s_barrier
	s_waitcnt lgkmcnt(0)
	v_mfma_f32_16x16x32_bf16 v[60:63], v[150:153], v[182:185], v[60:63]
	v_mfma_f32_16x16x32_bf16 v[56:59], v[158:161], v[182:185], v[56:59]
	v_mfma_f32_16x16x32_bf16 v[44:47], v[150:153], v[190:193], v[44:47]
	v_mfma_f32_16x16x32_bf16 v[40:43], v[158:161], v[190:193], v[40:43]
	v_mfma_f32_16x16x32_bf16 v[28:31], v[150:153], v[198:201], v[28:31]
	v_mfma_f32_16x16x32_bf16 v[24:27], v[158:161], v[198:201], v[24:27]
	v_mfma_f32_16x16x32_bf16 v[12:15], v[150:153], v[206:209], v[12:15]
	v_mfma_f32_16x16x32_bf16 v[8:11], v[158:161], v[206:209], v[8:11]
	v_mfma_f32_16x16x32_bf16 v[60:63], v[154:157], v[186:189], v[60:63]
	v_mfma_f32_16x16x32_bf16 v[56:59], v[162:165], v[186:189], v[56:59]
	v_mfma_f32_16x16x32_bf16 v[44:47], v[154:157], v[194:197], v[44:47]
	v_mfma_f32_16x16x32_bf16 v[40:43], v[162:165], v[194:197], v[40:43]
	v_mfma_f32_16x16x32_bf16 v[28:31], v[154:157], v[202:205], v[28:31]
	v_mfma_f32_16x16x32_bf16 v[24:27], v[162:165], v[202:205], v[24:27]
	v_mfma_f32_16x16x32_bf16 v[12:15], v[154:157], v[210:213], v[12:15]
	v_mfma_f32_16x16x32_bf16 v[8:11], v[162:165], v[210:213], v[8:11]
	v_mfma_f32_16x16x32_bf16 v[52:55], v[166:169], v[182:185], v[52:55]
	v_mfma_f32_16x16x32_bf16 v[48:51], v[174:177], v[182:185], v[48:51]
	v_mfma_f32_16x16x32_bf16 v[36:39], v[166:169], v[190:193], v[36:39]
	v_mfma_f32_16x16x32_bf16 v[32:35], v[174:177], v[190:193], v[32:35]
	v_mfma_f32_16x16x32_bf16 v[20:23], v[166:169], v[198:201], v[20:23]
	v_mfma_f32_16x16x32_bf16 v[16:19], v[174:177], v[198:201], v[16:19]
	v_mfma_f32_16x16x32_bf16 v[4:7], v[166:169], v[206:209], v[4:7]
	v_mfma_f32_16x16x32_bf16 v[0:3], v[174:177], v[206:209], v[0:3]
	v_mfma_f32_16x16x32_bf16 v[52:55], v[170:173], v[186:189], v[52:55]
	v_mfma_f32_16x16x32_bf16 v[48:51], v[178:181], v[186:189], v[48:51]
	v_mfma_f32_16x16x32_bf16 v[36:39], v[170:173], v[194:197], v[36:39]
	v_mfma_f32_16x16x32_bf16 v[32:35], v[178:181], v[194:197], v[32:35]
	v_mfma_f32_16x16x32_bf16 v[20:23], v[170:173], v[202:205], v[20:23]
	v_mfma_f32_16x16x32_bf16 v[16:19], v[178:181], v[202:205], v[16:19]
	v_mfma_f32_16x16x32_bf16 v[4:7], v[170:173], v[210:213], v[4:7]
	v_mfma_f32_16x16x32_bf16 v[0:3], v[178:181], v[210:213], v[0:3]
	s_barrier
	s_add_u32 s62, s62, 0x100
	s_addc_u32 s63, s63, 0
	s_add_u32 s91, s91, 0x100
	s_addc_u32 s92, s92, 0
	s_cmp_ge_i32 s93, s74
	s_mov_b32 s64, s93
	s_cbranch_scc0 .LBB0_474

.LBB0_657:
	ds_read_b128 v[128:131], v185
	ds_read_b128 v[132:135], v185 offset:1024
	ds_read_b128 v[136:139], v185 offset:2048
	ds_read_b128 v[140:143], v185 offset:3072
	ds_read_b128 v[144:147], v186
	ds_read_b128 v[148:151], v186 offset:1024
	ds_read_b128 v[172:175], v186 offset:2048
	ds_read_b128 v[176:179], v186 offset:3072
	s_add_u32 s60, s58, 0xfffc0080
	s_addc_u32 s61, s59, -1
	s_cmp_eq_u32 s65, 12
	s_cselect_b32 s63, s8, s61
	s_cselect_b32 s62, s9, s60
	s_cselect_b32 s61, s45, s64
	s_cselect_b32 s60, s47, s57
	v_lshl_add_u64 v[180:181], s[58:59], 0, v[164:165]
	s_add_i32 m0, s70, 0xc000
	ds_read_b128 v[190:193], v187
	ds_read_b128 v[194:197], v187 offset:1024
	ds_read_b128 v[198:201], v187 offset:2048
	ds_read_b128 v[202:205], v187 offset:3072
	ds_read_b128 v[206:209], v187 offset:4096
	ds_read_b128 v[210:213], v187 offset:5120
	ds_read_b128 v[214:217], v187 offset:6144
	ds_read_b128 v[218:221], v187 offset:7168
	global_load_lds_dwordx4 v[180:181], off
	v_lshl_add_u64 v[180:181], s[58:59], 0, v[166:167]
	s_add_i32 m0, s70, 0xe000
	s_nop 0
	global_load_lds_dwordx4 v[180:181], off
	s_waitcnt vmcnt(8)
	s_waitcnt lgkmcnt(0)
	s_barrier
	s_waitcnt lgkmcnt(0)
	v_mfma_f32_16x16x32_bf16 v[124:127], v[128:131], v[190:193], v[124:127]
	v_mfma_f32_16x16x32_bf16 v[120:123], v[136:139], v[190:193], v[120:123]
	v_mfma_f32_16x16x32_bf16 v[108:111], v[128:131], v[198:201], v[108:111]
	v_mfma_f32_16x16x32_bf16 v[104:107], v[136:139], v[198:201], v[104:107]
	v_mfma_f32_16x16x32_bf16 v[92:95], v[128:131], v[206:209], v[92:95]
	v_mfma_f32_16x16x32_bf16 v[88:91], v[136:139], v[206:209], v[88:91]
	v_mfma_f32_16x16x32_bf16 v[76:79], v[128:131], v[214:217], v[76:79]
	v_mfma_f32_16x16x32_bf16 v[72:75], v[136:139], v[214:217], v[72:75]
	v_mfma_f32_16x16x32_bf16 v[124:127], v[132:135], v[194:197], v[124:127]
	v_mfma_f32_16x16x32_bf16 v[120:123], v[140:143], v[194:197], v[120:123]
	v_mfma_f32_16x16x32_bf16 v[108:111], v[132:135], v[202:205], v[108:111]
	v_mfma_f32_16x16x32_bf16 v[104:107], v[140:143], v[202:205], v[104:107]
	v_mfma_f32_16x16x32_bf16 v[92:95], v[132:135], v[210:213], v[92:95]
	v_mfma_f32_16x16x32_bf16 v[88:91], v[140:143], v[210:213], v[88:91]
	v_mfma_f32_16x16x32_bf16 v[76:79], v[132:135], v[218:221], v[76:79]
	v_mfma_f32_16x16x32_bf16 v[72:75], v[140:143], v[218:221], v[72:75]
	v_mfma_f32_16x16x32_bf16 v[116:119], v[144:147], v[190:193], v[116:119]
	v_mfma_f32_16x16x32_bf16 v[112:115], v[172:175], v[190:193], v[112:115]
	v_mfma_f32_16x16x32_bf16 v[100:103], v[144:147], v[198:201], v[100:103]
	v_mfma_f32_16x16x32_bf16 v[96:99], v[172:175], v[198:201], v[96:99]
	v_mfma_f32_16x16x32_bf16 v[84:87], v[144:147], v[206:209], v[84:87]
	v_mfma_f32_16x16x32_bf16 v[80:83], v[172:175], v[206:209], v[80:83]
	v_mfma_f32_16x16x32_bf16 v[68:71], v[144:147], v[214:217], v[68:71]
	v_mfma_f32_16x16x32_bf16 v[64:67], v[172:175], v[214:217], v[64:67]
	v_mfma_f32_16x16x32_bf16 v[116:119], v[148:151], v[194:197], v[116:119]
	v_mfma_f32_16x16x32_bf16 v[112:115], v[176:179], v[194:197], v[112:115]
	v_mfma_f32_16x16x32_bf16 v[100:103], v[148:151], v[202:205], v[100:103]
	v_mfma_f32_16x16x32_bf16 v[96:99], v[176:179], v[202:205], v[96:99]
	v_mfma_f32_16x16x32_bf16 v[84:87], v[148:151], v[210:213], v[84:87]
	v_mfma_f32_16x16x32_bf16 v[80:83], v[176:179], v[210:213], v[80:83]
	v_mfma_f32_16x16x32_bf16 v[68:71], v[148:151], v[218:221], v[68:71]
	v_mfma_f32_16x16x32_bf16 v[64:67], v[176:179], v[218:221], v[64:67]
	s_barrier
	s_add_i32 s66, s83, s69
	v_lshl_add_u64 v[180:181], s[60:61], 0, v[154:155]
	s_mov_b32 m0, s66
	ds_read_b128 v[190:193], v187 offset:16384
	ds_read_b128 v[194:197], v187 offset:17408
	ds_read_b128 v[198:201], v187 offset:18432
	ds_read_b128 v[202:205], v187 offset:19456
	ds_read_b128 v[206:209], v187 offset:20480
	ds_read_b128 v[210:213], v187 offset:21504
	ds_read_b128 v[214:217], v187 offset:22528
	ds_read_b128 v[218:221], v187 offset:23552
	global_load_lds_dwordx4 v[180:181], off
	s_add_i32 m0, s66, 0x2000
	s_add_u32 s66, s60, 0x40000
	v_lshl_add_u64 v[222:223], s[60:61], 0, v[158:159]
	s_addc_u32 s67, s61, 0
	s_add_i32 s85, s86, s69
	global_load_lds_dwordx4 v[222:223], off
	v_lshl_add_u64 v[224:225], s[66:67], 0, v[154:155]
	s_mov_b32 m0, s85
	v_lshl_add_u64 v[226:227], s[62:63], 0, v[156:157]
	global_load_lds_dwordx4 v[224:225], off
	v_lshl_add_u64 v[224:225], s[66:67], 0, v[158:159]
	s_add_i32 m0, s85, 0x2000
	s_nop 0
	global_load_lds_dwordx4 v[224:225], off
	v_lshl_add_u64 v[224:225], s[62:63], 0, v[152:153]
	s_mov_b32 m0, s70
	s_nop 0
	global_load_lds_dwordx4 v[224:225], off
	s_mov_b32 m0, s71
	s_nop 0
	global_load_lds_dwordx4 v[226:227], off
	s_waitcnt vmcnt(8)
	s_waitcnt lgkmcnt(0)
	s_barrier
	s_waitcnt lgkmcnt(0)
	v_mfma_f32_16x16x32_bf16 v[60:63], v[128:131], v[190:193], v[60:63]
	v_mfma_f32_16x16x32_bf16 v[56:59], v[136:139], v[190:193], v[56:59]
	v_mfma_f32_16x16x32_bf16 v[44:47], v[128:131], v[198:201], v[44:47]
	v_mfma_f32_16x16x32_bf16 v[40:43], v[136:139], v[198:201], v[40:43]
	v_mfma_f32_16x16x32_bf16 v[28:31], v[128:131], v[206:209], v[28:31]
	v_mfma_f32_16x16x32_bf16 v[24:27], v[136:139], v[206:209], v[24:27]
	v_mfma_f32_16x16x32_bf16 v[12:15], v[128:131], v[214:217], v[12:15]
	v_mfma_f32_16x16x32_bf16 v[8:11], v[136:139], v[214:217], v[8:11]
	v_mfma_f32_16x16x32_bf16 v[60:63], v[132:135], v[194:197], v[60:63]
	v_mfma_f32_16x16x32_bf16 v[56:59], v[140:143], v[194:197], v[56:59]
	v_mfma_f32_16x16x32_bf16 v[44:47], v[132:135], v[202:205], v[44:47]
	v_mfma_f32_16x16x32_bf16 v[40:43], v[140:143], v[202:205], v[40:43]
	v_mfma_f32_16x16x32_bf16 v[28:31], v[132:135], v[210:213], v[28:31]
	v_mfma_f32_16x16x32_bf16 v[24:27], v[140:143], v[210:213], v[24:27]
	v_mfma_f32_16x16x32_bf16 v[12:15], v[132:135], v[218:221], v[12:15]
	v_mfma_f32_16x16x32_bf16 v[8:11], v[140:143], v[218:221], v[8:11]
	v_mfma_f32_16x16x32_bf16 v[52:55], v[144:147], v[190:193], v[52:55]
	v_mfma_f32_16x16x32_bf16 v[48:51], v[172:175], v[190:193], v[48:51]
	v_mfma_f32_16x16x32_bf16 v[36:39], v[144:147], v[198:201], v[36:39]
	v_mfma_f32_16x16x32_bf16 v[32:35], v[172:175], v[198:201], v[32:35]
	v_mfma_f32_16x16x32_bf16 v[20:23], v[144:147], v[206:209], v[20:23]
	v_mfma_f32_16x16x32_bf16 v[16:19], v[172:175], v[206:209], v[16:19]
	v_mfma_f32_16x16x32_bf16 v[4:7], v[144:147], v[214:217], v[4:7]
	v_mfma_f32_16x16x32_bf16 v[0:3], v[172:175], v[214:217], v[0:3]
	v_mfma_f32_16x16x32_bf16 v[52:55], v[148:151], v[194:197], v[52:55]
	v_mfma_f32_16x16x32_bf16 v[48:51], v[176:179], v[194:197], v[48:51]
	v_mfma_f32_16x16x32_bf16 v[36:39], v[148:151], v[202:205], v[36:39]
	v_mfma_f32_16x16x32_bf16 v[32:35], v[176:179], v[202:205], v[32:35]
	v_mfma_f32_16x16x32_bf16 v[20:23], v[148:151], v[210:213], v[20:23]
	v_mfma_f32_16x16x32_bf16 v[16:19], v[176:179], v[210:213], v[16:19]
	v_mfma_f32_16x16x32_bf16 v[4:7], v[148:151], v[218:221], v[4:7]
	v_mfma_f32_16x16x32_bf16 v[0:3], v[176:179], v[218:221], v[0:3]
	s_barrier
	s_add_i32 s66, 0, 0x18000
	s_add_i32 s67, 0, 0x1c000
	v_add_u32_e32 v140, s66, v182
	v_add_u32_e32 v160, s67, v182
	ds_read_b128 v[128:131], v140
	ds_read_b128 v[132:135], v140 offset:1024
	ds_read_b128 v[136:139], v140 offset:2048
	ds_read_b128 v[140:143], v140 offset:3072
	ds_read_b128 v[144:147], v160
	ds_read_b128 v[148:151], v160 offset:1024
	ds_read_b128 v[172:175], v160 offset:2048
	ds_read_b128 v[176:179], v160 offset:3072
	s_add_u32 s62, s62, 0x40000
	s_addc_u32 s63, s63, 0
	s_mov_b32 m0, s72
	v_lshl_add_u64 v[228:229], s[62:63], 0, v[152:153]
	ds_read_b128 v[190:193], v187 offset:32768
	ds_read_b128 v[194:197], v187 offset:33792
	ds_read_b128 v[198:201], v187 offset:34816
	ds_read_b128 v[202:205], v187 offset:35840
	ds_read_b128 v[206:209], v187 offset:36864
	ds_read_b128 v[210:213], v187 offset:37888
	ds_read_b128 v[214:217], v187 offset:38912
	ds_read_b128 v[218:221], v187 offset:39936
	global_load_lds_dwordx4 v[228:229], off
	v_lshl_add_u64 v[228:229], s[62:63], 0, v[156:157]
	s_mov_b32 m0, s73
	s_nop 0
	global_load_lds_dwordx4 v[228:229], off
	s_waitcnt vmcnt(8)
	s_waitcnt lgkmcnt(0)
	s_barrier
	s_waitcnt lgkmcnt(0)
	v_mfma_f32_16x16x32_bf16 v[124:127], v[128:131], v[190:193], v[124:127]
	v_mfma_f32_16x16x32_bf16 v[120:123], v[136:139], v[190:193], v[120:123]
	v_mfma_f32_16x16x32_bf16 v[108:111], v[128:131], v[198:201], v[108:111]
	v_mfma_f32_16x16x32_bf16 v[104:107], v[136:139], v[198:201], v[104:107]
	v_mfma_f32_16x16x32_bf16 v[92:95], v[128:131], v[206:209], v[92:95]
	v_mfma_f32_16x16x32_bf16 v[88:91], v[136:139], v[206:209], v[88:91]
	v_mfma_f32_16x16x32_bf16 v[76:79], v[128:131], v[214:217], v[76:79]
	v_mfma_f32_16x16x32_bf16 v[72:75], v[136:139], v[214:217], v[72:75]
	v_mfma_f32_16x16x32_bf16 v[124:127], v[132:135], v[194:197], v[124:127]
	v_mfma_f32_16x16x32_bf16 v[120:123], v[140:143], v[194:197], v[120:123]
	v_mfma_f32_16x16x32_bf16 v[108:111], v[132:135], v[202:205], v[108:111]
	v_mfma_f32_16x16x32_bf16 v[104:107], v[140:143], v[202:205], v[104:107]
	v_mfma_f32_16x16x32_bf16 v[92:95], v[132:135], v[210:213], v[92:95]
	v_mfma_f32_16x16x32_bf16 v[88:91], v[140:143], v[210:213], v[88:91]
	v_mfma_f32_16x16x32_bf16 v[76:79], v[132:135], v[218:221], v[76:79]
	v_mfma_f32_16x16x32_bf16 v[72:75], v[140:143], v[218:221], v[72:75]
	v_mfma_f32_16x16x32_bf16 v[116:119], v[144:147], v[190:193], v[116:119]
	v_mfma_f32_16x16x32_bf16 v[112:115], v[172:175], v[190:193], v[112:115]
	v_mfma_f32_16x16x32_bf16 v[100:103], v[144:147], v[198:201], v[100:103]
	v_mfma_f32_16x16x32_bf16 v[96:99], v[172:175], v[198:201], v[96:99]
	v_mfma_f32_16x16x32_bf16 v[84:87], v[144:147], v[206:209], v[84:87]
	v_mfma_f32_16x16x32_bf16 v[80:83], v[172:175], v[206:209], v[80:83]
	v_mfma_f32_16x16x32_bf16 v[68:71], v[144:147], v[214:217], v[68:71]
	v_mfma_f32_16x16x32_bf16 v[64:67], v[172:175], v[214:217], v[64:67]
	v_mfma_f32_16x16x32_bf16 v[116:119], v[148:151], v[194:197], v[116:119]
	v_mfma_f32_16x16x32_bf16 v[112:115], v[176:179], v[194:197], v[112:115]
	v_mfma_f32_16x16x32_bf16 v[100:103], v[148:151], v[202:205], v[100:103]
	v_mfma_f32_16x16x32_bf16 v[96:99], v[176:179], v[202:205], v[96:99]
	v_mfma_f32_16x16x32_bf16 v[84:87], v[148:151], v[210:213], v[84:87]
	v_mfma_f32_16x16x32_bf16 v[80:83], v[176:179], v[210:213], v[80:83]
	v_mfma_f32_16x16x32_bf16 v[68:71], v[148:151], v[218:221], v[68:71]
	v_mfma_f32_16x16x32_bf16 v[64:67], v[176:179], v[218:221], v[64:67]
	s_barrier
	s_add_i32 s62, s66, s69
	v_lshl_add_u64 v[180:181], v[180:181], 0, s[16:17]
	s_mov_b32 m0, s62
	ds_read_b128 v[190:193], v187 offset:49152
	ds_read_b128 v[194:197], v187 offset:50176
	ds_read_b128 v[198:201], v187 offset:51200
	ds_read_b128 v[202:205], v187 offset:52224
	ds_read_b128 v[206:209], v187 offset:53248
	ds_read_b128 v[210:213], v187 offset:54272
	ds_read_b128 v[214:217], v187 offset:55296
	ds_read_b128 v[218:221], v187 offset:56320
	global_load_lds_dwordx4 v[180:181], off
	s_add_i32 m0, s62, 0x2000
	s_add_u32 s60, s60, 0x40080
	v_lshl_add_u64 v[180:181], v[222:223], 0, s[16:17]
	s_addc_u32 s61, s61, 0
	s_add_i32 s62, s67, s69
	global_load_lds_dwordx4 v[180:181], off
	v_lshl_add_u64 v[180:181], s[60:61], 0, v[154:155]
	s_mov_b32 m0, s62
	s_nop 0
	global_load_lds_dwordx4 v[180:181], off
	v_lshl_add_u64 v[180:181], s[60:61], 0, v[158:159]
	s_add_i32 m0, s62, 0x2000
	s_nop 0
	global_load_lds_dwordx4 v[180:181], off
	v_lshl_add_u64 v[180:181], v[224:225], 0, s[16:17]
	s_mov_b32 m0, s75
	s_nop 0
	global_load_lds_dwordx4 v[180:181], off
	v_lshl_add_u64 v[180:181], v[226:227], 0, s[16:17]
	s_mov_b32 m0, s76
	s_nop 0
	global_load_lds_dwordx4 v[180:181], off
	s_waitcnt vmcnt(8)
	s_waitcnt lgkmcnt(0)
	s_barrier
	s_waitcnt lgkmcnt(0)
	v_mfma_f32_16x16x32_bf16 v[60:63], v[128:131], v[190:193], v[60:63]
	v_mfma_f32_16x16x32_bf16 v[56:59], v[136:139], v[190:193], v[56:59]
	v_mfma_f32_16x16x32_bf16 v[44:47], v[128:131], v[198:201], v[44:47]
	v_mfma_f32_16x16x32_bf16 v[40:43], v[136:139], v[198:201], v[40:43]
	v_mfma_f32_16x16x32_bf16 v[28:31], v[128:131], v[206:209], v[28:31]
	v_mfma_f32_16x16x32_bf16 v[24:27], v[136:139], v[206:209], v[24:27]
	v_mfma_f32_16x16x32_bf16 v[12:15], v[128:131], v[214:217], v[12:15]
	v_mfma_f32_16x16x32_bf16 v[8:11], v[136:139], v[214:217], v[8:11]
	v_mfma_f32_16x16x32_bf16 v[60:63], v[132:135], v[194:197], v[60:63]
	v_mfma_f32_16x16x32_bf16 v[56:59], v[140:143], v[194:197], v[56:59]
	v_mfma_f32_16x16x32_bf16 v[44:47], v[132:135], v[202:205], v[44:47]
	v_mfma_f32_16x16x32_bf16 v[40:43], v[140:143], v[202:205], v[40:43]
	v_mfma_f32_16x16x32_bf16 v[28:31], v[132:135], v[210:213], v[28:31]
	v_mfma_f32_16x16x32_bf16 v[24:27], v[140:143], v[210:213], v[24:27]
	v_mfma_f32_16x16x32_bf16 v[12:15], v[132:135], v[218:221], v[12:15]
	v_mfma_f32_16x16x32_bf16 v[8:11], v[140:143], v[218:221], v[8:11]
	v_mfma_f32_16x16x32_bf16 v[52:55], v[144:147], v[190:193], v[52:55]
	v_mfma_f32_16x16x32_bf16 v[48:51], v[172:175], v[190:193], v[48:51]
	v_mfma_f32_16x16x32_bf16 v[36:39], v[144:147], v[198:201], v[36:39]
	v_mfma_f32_16x16x32_bf16 v[32:35], v[172:175], v[198:201], v[32:35]
	v_mfma_f32_16x16x32_bf16 v[20:23], v[144:147], v[206:209], v[20:23]
	v_mfma_f32_16x16x32_bf16 v[16:19], v[172:175], v[206:209], v[16:19]
	v_mfma_f32_16x16x32_bf16 v[4:7], v[144:147], v[214:217], v[4:7]
	v_mfma_f32_16x16x32_bf16 v[0:3], v[172:175], v[214:217], v[0:3]
	v_mfma_f32_16x16x32_bf16 v[52:55], v[148:151], v[194:197], v[52:55]
	v_mfma_f32_16x16x32_bf16 v[48:51], v[176:179], v[194:197], v[48:51]
	v_mfma_f32_16x16x32_bf16 v[36:39], v[148:151], v[202:205], v[36:39]
	v_mfma_f32_16x16x32_bf16 v[32:35], v[176:179], v[202:205], v[32:35]
	v_mfma_f32_16x16x32_bf16 v[20:23], v[148:151], v[210:213], v[20:23]
	v_mfma_f32_16x16x32_bf16 v[16:19], v[176:179], v[210:213], v[16:19]
	v_mfma_f32_16x16x32_bf16 v[4:7], v[148:151], v[218:221], v[4:7]
	v_mfma_f32_16x16x32_bf16 v[0:3], v[176:179], v[218:221], v[0:3]
	s_barrier
	s_add_i32 s65, s65, 2
	s_add_u32 s58, s58, 0x100
	s_addc_u32 s59, s59, 0
	s_add_u32 s57, s57, 0x100
	s_addc_u32 s64, s64, 0
	s_cmp_gt_u32 s65, 13
	s_cbranch_scc0 .LBB0_657
	s_and_b64 vcc, exec, s[18:19]
	s_cbranch_vccz .LBB0_660
	s_barrier

.LBB0_940:
	ds_read_b128 v[150:153], v147
	ds_read_b128 v[154:157], v147 offset:1024
	ds_read_b128 v[158:161], v147 offset:2048
	ds_read_b128 v[162:165], v147 offset:3072
	ds_read_b128 v[166:169], v148
	ds_read_b128 v[170:173], v148 offset:1024
	ds_read_b128 v[174:177], v148 offset:2048
	ds_read_b128 v[178:181], v148 offset:3072
	s_add_u32 s58, s56, 0xfffe0080
	s_addc_u32 s59, s57, -1
	s_cmp_eq_u32 s87, 4
	s_cselect_b32 s61, s51, s59
	s_cselect_b32 s60, s82, s58
	s_cselect_b32 s59, s49, s86
	s_cselect_b32 s58, s83, s85
	v_lshl_add_u64 v[214:215], s[56:57], 0, v[136:137]
	s_add_i32 m0, s47, 0xc000
	ds_read_b128 v[182:185], v149
	ds_read_b128 v[186:189], v149 offset:1024
	ds_read_b128 v[190:193], v149 offset:2048
	ds_read_b128 v[194:197], v149 offset:3072
	ds_read_b128 v[198:201], v149 offset:4096
	ds_read_b128 v[202:205], v149 offset:5120
	ds_read_b128 v[206:209], v149 offset:6144
	ds_read_b128 v[210:213], v149 offset:7168
	global_load_lds_dwordx4 v[214:215], off
	v_lshl_add_u64 v[214:215], s[56:57], 0, v[138:139]
	s_add_i32 m0, s47, 0xe000
	s_nop 0
	global_load_lds_dwordx4 v[214:215], off
	s_waitcnt vmcnt(8)
	s_waitcnt lgkmcnt(0)
	s_barrier
	s_waitcnt lgkmcnt(0)
	v_mfma_f32_16x16x32_bf16 v[124:127], v[150:153], v[182:185], v[124:127]
	v_mfma_f32_16x16x32_bf16 v[120:123], v[158:161], v[182:185], v[120:123]
	v_mfma_f32_16x16x32_bf16 v[116:119], v[150:153], v[190:193], v[116:119]
	v_mfma_f32_16x16x32_bf16 v[112:115], v[158:161], v[190:193], v[112:115]
	v_mfma_f32_16x16x32_bf16 v[100:103], v[150:153], v[198:201], v[100:103]
	v_mfma_f32_16x16x32_bf16 v[96:99], v[158:161], v[198:201], v[96:99]
	v_mfma_f32_16x16x32_bf16 v[84:87], v[150:153], v[206:209], v[84:87]
	v_mfma_f32_16x16x32_bf16 v[80:83], v[158:161], v[206:209], v[80:83]
	v_mfma_f32_16x16x32_bf16 v[124:127], v[154:157], v[186:189], v[124:127]
	v_mfma_f32_16x16x32_bf16 v[120:123], v[162:165], v[186:189], v[120:123]
	v_mfma_f32_16x16x32_bf16 v[116:119], v[154:157], v[194:197], v[116:119]
	v_mfma_f32_16x16x32_bf16 v[112:115], v[162:165], v[194:197], v[112:115]
	v_mfma_f32_16x16x32_bf16 v[100:103], v[154:157], v[202:205], v[100:103]
	v_mfma_f32_16x16x32_bf16 v[96:99], v[162:165], v[202:205], v[96:99]
	v_mfma_f32_16x16x32_bf16 v[84:87], v[154:157], v[210:213], v[84:87]
	v_mfma_f32_16x16x32_bf16 v[80:83], v[162:165], v[210:213], v[80:83]
	v_mfma_f32_16x16x32_bf16 v[108:111], v[166:169], v[182:185], v[108:111]
	v_mfma_f32_16x16x32_bf16 v[104:107], v[174:177], v[182:185], v[104:107]
	v_mfma_f32_16x16x32_bf16 v[92:95], v[166:169], v[190:193], v[92:95]
	v_mfma_f32_16x16x32_bf16 v[88:91], v[174:177], v[190:193], v[88:91]
	v_mfma_f32_16x16x32_bf16 v[76:79], v[166:169], v[198:201], v[76:79]
	v_mfma_f32_16x16x32_bf16 v[72:75], v[174:177], v[198:201], v[72:75]
	v_mfma_f32_16x16x32_bf16 v[68:71], v[166:169], v[206:209], v[68:71]
	v_mfma_f32_16x16x32_bf16 v[64:67], v[174:177], v[206:209], v[64:67]
	v_mfma_f32_16x16x32_bf16 v[108:111], v[170:173], v[186:189], v[108:111]
	v_mfma_f32_16x16x32_bf16 v[104:107], v[178:181], v[186:189], v[104:107]
	v_mfma_f32_16x16x32_bf16 v[92:95], v[170:173], v[194:197], v[92:95]
	v_mfma_f32_16x16x32_bf16 v[88:91], v[178:181], v[194:197], v[88:91]
	v_mfma_f32_16x16x32_bf16 v[76:79], v[170:173], v[202:205], v[76:79]
	v_mfma_f32_16x16x32_bf16 v[72:75], v[178:181], v[202:205], v[72:75]
	v_mfma_f32_16x16x32_bf16 v[68:71], v[170:173], v[210:213], v[68:71]
	v_mfma_f32_16x16x32_bf16 v[64:67], v[178:181], v[210:213], v[64:67]
	s_barrier
	s_add_i32 s88, s73, s64
	v_lshl_add_u64 v[214:215], s[58:59], 0, v[130:131]
	s_mov_b32 m0, s88
	ds_read_b128 v[182:185], v149 offset:16384
	ds_read_b128 v[186:189], v149 offset:17408
	ds_read_b128 v[190:193], v149 offset:18432
	ds_read_b128 v[194:197], v149 offset:19456
	ds_read_b128 v[198:201], v149 offset:20480
	ds_read_b128 v[202:205], v149 offset:21504
	ds_read_b128 v[206:209], v149 offset:22528
	ds_read_b128 v[210:213], v149 offset:23552
	global_load_lds_dwordx4 v[214:215], off
	s_add_i32 m0, s88, 0x2000
	s_add_u32 s88, s58, 0x20000
	v_lshl_add_u64 v[216:217], s[58:59], 0, v[134:135]
	s_addc_u32 s89, s59, 0
	s_add_i32 s90, s74, s64
	global_load_lds_dwordx4 v[216:217], off
	v_lshl_add_u64 v[218:219], s[88:89], 0, v[130:131]
	s_mov_b32 m0, s90
	v_lshl_add_u64 v[220:221], s[60:61], 0, v[132:133]
	global_load_lds_dwordx4 v[218:219], off
	v_lshl_add_u64 v[218:219], s[88:89], 0, v[134:135]
	s_add_i32 m0, s90, 0x2000
	s_nop 0
	global_load_lds_dwordx4 v[218:219], off
	v_lshl_add_u64 v[218:219], s[60:61], 0, v[128:129]
	s_mov_b32 m0, s47
	s_nop 0
	global_load_lds_dwordx4 v[218:219], off
	s_mov_b32 m0, s65
	s_nop 0
	global_load_lds_dwordx4 v[220:221], off
	s_waitcnt vmcnt(8)
	s_waitcnt lgkmcnt(0)
	s_barrier
	s_waitcnt lgkmcnt(0)
	v_mfma_f32_16x16x32_bf16 v[60:63], v[150:153], v[182:185], v[60:63]
	v_mfma_f32_16x16x32_bf16 v[56:59], v[158:161], v[182:185], v[56:59]
	v_mfma_f32_16x16x32_bf16 v[52:55], v[150:153], v[190:193], v[52:55]
	v_mfma_f32_16x16x32_bf16 v[48:51], v[158:161], v[190:193], v[48:51]
	v_mfma_f32_16x16x32_bf16 v[36:39], v[150:153], v[198:201], v[36:39]
	v_mfma_f32_16x16x32_bf16 v[32:35], v[158:161], v[198:201], v[32:35]
	v_mfma_f32_16x16x32_bf16 v[20:23], v[150:153], v[206:209], v[20:23]
	v_mfma_f32_16x16x32_bf16 v[16:19], v[158:161], v[206:209], v[16:19]
	v_mfma_f32_16x16x32_bf16 v[60:63], v[154:157], v[186:189], v[60:63]
	v_mfma_f32_16x16x32_bf16 v[56:59], v[162:165], v[186:189], v[56:59]
	v_mfma_f32_16x16x32_bf16 v[52:55], v[154:157], v[194:197], v[52:55]
	v_mfma_f32_16x16x32_bf16 v[48:51], v[162:165], v[194:197], v[48:51]
	v_mfma_f32_16x16x32_bf16 v[36:39], v[154:157], v[202:205], v[36:39]
	v_mfma_f32_16x16x32_bf16 v[32:35], v[162:165], v[202:205], v[32:35]
	v_mfma_f32_16x16x32_bf16 v[20:23], v[154:157], v[210:213], v[20:23]
	v_mfma_f32_16x16x32_bf16 v[16:19], v[162:165], v[210:213], v[16:19]
	v_mfma_f32_16x16x32_bf16 v[44:47], v[166:169], v[182:185], v[44:47]
	v_mfma_f32_16x16x32_bf16 v[40:43], v[174:177], v[182:185], v[40:43]
	v_mfma_f32_16x16x32_bf16 v[28:31], v[166:169], v[190:193], v[28:31]
	v_mfma_f32_16x16x32_bf16 v[24:27], v[174:177], v[190:193], v[24:27]
	v_mfma_f32_16x16x32_bf16 v[12:15], v[166:169], v[198:201], v[12:15]
	v_mfma_f32_16x16x32_bf16 v[8:11], v[174:177], v[198:201], v[8:11]
	v_mfma_f32_16x16x32_bf16 v[4:7], v[166:169], v[206:209], v[4:7]
	v_mfma_f32_16x16x32_bf16 v[0:3], v[174:177], v[206:209], v[0:3]
	v_mfma_f32_16x16x32_bf16 v[44:47], v[170:173], v[186:189], v[44:47]
	v_mfma_f32_16x16x32_bf16 v[40:43], v[178:181], v[186:189], v[40:43]
	v_mfma_f32_16x16x32_bf16 v[28:31], v[170:173], v[194:197], v[28:31]
	v_mfma_f32_16x16x32_bf16 v[24:27], v[178:181], v[194:197], v[24:27]
	v_mfma_f32_16x16x32_bf16 v[12:15], v[170:173], v[202:205], v[12:15]
	v_mfma_f32_16x16x32_bf16 v[8:11], v[178:181], v[202:205], v[8:11]
	v_mfma_f32_16x16x32_bf16 v[4:7], v[170:173], v[210:213], v[4:7]
	v_mfma_f32_16x16x32_bf16 v[0:3], v[178:181], v[210:213], v[0:3]
	s_barrier
	s_add_i32 s88, 0, 0x18000
	s_add_i32 s89, 0, 0x1c000
	v_add_u32_e32 v162, s88, v145
	v_add_u32_e32 v178, s89, v145
	ds_read_b128 v[150:153], v162
	ds_read_b128 v[154:157], v162 offset:1024
	ds_read_b128 v[158:161], v162 offset:2048
	ds_read_b128 v[162:165], v162 offset:3072
	ds_read_b128 v[166:169], v178
	ds_read_b128 v[170:173], v178 offset:1024
	ds_read_b128 v[174:177], v178 offset:2048
	ds_read_b128 v[178:181], v178 offset:3072
	s_add_u32 s60, s60, 0x20000
	s_addc_u32 s61, s61, 0
	s_mov_b32 m0, s66
	v_lshl_add_u64 v[222:223], s[60:61], 0, v[128:129]
	ds_read_b128 v[182:185], v149 offset:32768
	ds_read_b128 v[186:189], v149 offset:33792
	ds_read_b128 v[190:193], v149 offset:34816
	ds_read_b128 v[194:197], v149 offset:35840
	ds_read_b128 v[198:201], v149 offset:36864
	ds_read_b128 v[202:205], v149 offset:37888
	ds_read_b128 v[206:209], v149 offset:38912
	ds_read_b128 v[210:213], v149 offset:39936
	global_load_lds_dwordx4 v[222:223], off
	v_lshl_add_u64 v[222:223], s[60:61], 0, v[132:133]
	s_mov_b32 m0, s67
	s_nop 0
	global_load_lds_dwordx4 v[222:223], off
	s_waitcnt vmcnt(8)
	s_waitcnt lgkmcnt(0)
	s_barrier
	s_waitcnt lgkmcnt(0)
	v_mfma_f32_16x16x32_bf16 v[124:127], v[150:153], v[182:185], v[124:127]
	v_mfma_f32_16x16x32_bf16 v[120:123], v[158:161], v[182:185], v[120:123]
	v_mfma_f32_16x16x32_bf16 v[116:119], v[150:153], v[190:193], v[116:119]
	v_mfma_f32_16x16x32_bf16 v[112:115], v[158:161], v[190:193], v[112:115]
	v_mfma_f32_16x16x32_bf16 v[100:103], v[150:153], v[198:201], v[100:103]
	v_mfma_f32_16x16x32_bf16 v[96:99], v[158:161], v[198:201], v[96:99]
	v_mfma_f32_16x16x32_bf16 v[84:87], v[150:153], v[206:209], v[84:87]
	v_mfma_f32_16x16x32_bf16 v[80:83], v[158:161], v[206:209], v[80:83]
	v_mfma_f32_16x16x32_bf16 v[124:127], v[154:157], v[186:189], v[124:127]
	v_mfma_f32_16x16x32_bf16 v[120:123], v[162:165], v[186:189], v[120:123]
	v_mfma_f32_16x16x32_bf16 v[116:119], v[154:157], v[194:197], v[116:119]
	v_mfma_f32_16x16x32_bf16 v[112:115], v[162:165], v[194:197], v[112:115]
	v_mfma_f32_16x16x32_bf16 v[100:103], v[154:157], v[202:205], v[100:103]
	v_mfma_f32_16x16x32_bf16 v[96:99], v[162:165], v[202:205], v[96:99]
	v_mfma_f32_16x16x32_bf16 v[84:87], v[154:157], v[210:213], v[84:87]
	v_mfma_f32_16x16x32_bf16 v[80:83], v[162:165], v[210:213], v[80:83]
	v_mfma_f32_16x16x32_bf16 v[108:111], v[166:169], v[182:185], v[108:111]
	v_mfma_f32_16x16x32_bf16 v[104:107], v[174:177], v[182:185], v[104:107]
	v_mfma_f32_16x16x32_bf16 v[92:95], v[166:169], v[190:193], v[92:95]
	v_mfma_f32_16x16x32_bf16 v[88:91], v[174:177], v[190:193], v[88:91]
	v_mfma_f32_16x16x32_bf16 v[76:79], v[166:169], v[198:201], v[76:79]
	v_mfma_f32_16x16x32_bf16 v[72:75], v[174:177], v[198:201], v[72:75]
	v_mfma_f32_16x16x32_bf16 v[68:71], v[166:169], v[206:209], v[68:71]
	v_mfma_f32_16x16x32_bf16 v[64:67], v[174:177], v[206:209], v[64:67]
	v_mfma_f32_16x16x32_bf16 v[108:111], v[170:173], v[186:189], v[108:111]
	v_mfma_f32_16x16x32_bf16 v[104:107], v[178:181], v[186:189], v[104:107]
	v_mfma_f32_16x16x32_bf16 v[92:95], v[170:173], v[194:197], v[92:95]
	v_mfma_f32_16x16x32_bf16 v[88:91], v[178:181], v[194:197], v[88:91]
	v_mfma_f32_16x16x32_bf16 v[76:79], v[170:173], v[202:205], v[76:79]
	v_mfma_f32_16x16x32_bf16 v[72:75], v[178:181], v[202:205], v[72:75]
	v_mfma_f32_16x16x32_bf16 v[68:71], v[170:173], v[210:213], v[68:71]
	v_mfma_f32_16x16x32_bf16 v[64:67], v[178:181], v[210:213], v[64:67]
	s_barrier
	s_add_i32 s60, s88, s64
	v_lshl_add_u64 v[214:215], v[214:215], 0, s[22:23]
	s_mov_b32 m0, s60
	ds_read_b128 v[182:185], v149 offset:49152
	ds_read_b128 v[186:189], v149 offset:50176
	ds_read_b128 v[190:193], v149 offset:51200
	ds_read_b128 v[194:197], v149 offset:52224
	ds_read_b128 v[198:201], v149 offset:53248
	ds_read_b128 v[202:205], v149 offset:54272
	ds_read_b128 v[206:209], v149 offset:55296
	ds_read_b128 v[210:213], v149 offset:56320
	global_load_lds_dwordx4 v[214:215], off
	s_add_i32 m0, s60, 0x2000
	s_add_u32 s58, s58, 0x20080
	v_lshl_add_u64 v[214:215], v[216:217], 0, s[22:23]
	s_addc_u32 s59, s59, 0
	s_add_i32 s60, s89, s64
	global_load_lds_dwordx4 v[214:215], off
	v_lshl_add_u64 v[214:215], s[58:59], 0, v[130:131]
	s_mov_b32 m0, s60
	s_nop 0
	global_load_lds_dwordx4 v[214:215], off
	v_lshl_add_u64 v[214:215], s[58:59], 0, v[134:135]
	s_add_i32 m0, s60, 0x2000
	s_nop 0
	global_load_lds_dwordx4 v[214:215], off
	v_lshl_add_u64 v[214:215], v[218:219], 0, s[22:23]
	s_mov_b32 m0, s69
	s_nop 0
	global_load_lds_dwordx4 v[214:215], off
	v_lshl_add_u64 v[214:215], v[220:221], 0, s[22:23]
	s_mov_b32 m0, s70
	s_nop 0
	global_load_lds_dwordx4 v[214:215], off
	s_waitcnt vmcnt(8)
	s_waitcnt lgkmcnt(0)
	s_barrier
	s_waitcnt lgkmcnt(0)
	v_mfma_f32_16x16x32_bf16 v[60:63], v[150:153], v[182:185], v[60:63]
	v_mfma_f32_16x16x32_bf16 v[56:59], v[158:161], v[182:185], v[56:59]
	v_mfma_f32_16x16x32_bf16 v[52:55], v[150:153], v[190:193], v[52:55]
	v_mfma_f32_16x16x32_bf16 v[48:51], v[158:161], v[190:193], v[48:51]
	v_mfma_f32_16x16x32_bf16 v[36:39], v[150:153], v[198:201], v[36:39]
	v_mfma_f32_16x16x32_bf16 v[32:35], v[158:161], v[198:201], v[32:35]
	v_mfma_f32_16x16x32_bf16 v[20:23], v[150:153], v[206:209], v[20:23]
	v_mfma_f32_16x16x32_bf16 v[16:19], v[158:161], v[206:209], v[16:19]
	v_mfma_f32_16x16x32_bf16 v[60:63], v[154:157], v[186:189], v[60:63]
	v_mfma_f32_16x16x32_bf16 v[56:59], v[162:165], v[186:189], v[56:59]
	v_mfma_f32_16x16x32_bf16 v[52:55], v[154:157], v[194:197], v[52:55]
	v_mfma_f32_16x16x32_bf16 v[48:51], v[162:165], v[194:197], v[48:51]
	v_mfma_f32_16x16x32_bf16 v[36:39], v[154:157], v[202:205], v[36:39]
	v_mfma_f32_16x16x32_bf16 v[32:35], v[162:165], v[202:205], v[32:35]
	v_mfma_f32_16x16x32_bf16 v[20:23], v[154:157], v[210:213], v[20:23]
	v_mfma_f32_16x16x32_bf16 v[16:19], v[162:165], v[210:213], v[16:19]
	v_mfma_f32_16x16x32_bf16 v[44:47], v[166:169], v[182:185], v[44:47]
	v_mfma_f32_16x16x32_bf16 v[40:43], v[174:177], v[182:185], v[40:43]
	v_mfma_f32_16x16x32_bf16 v[28:31], v[166:169], v[190:193], v[28:31]
	v_mfma_f32_16x16x32_bf16 v[24:27], v[174:177], v[190:193], v[24:27]
	v_mfma_f32_16x16x32_bf16 v[12:15], v[166:169], v[198:201], v[12:15]
	v_mfma_f32_16x16x32_bf16 v[8:11], v[174:177], v[198:201], v[8:11]
	v_mfma_f32_16x16x32_bf16 v[4:7], v[166:169], v[206:209], v[4:7]
	v_mfma_f32_16x16x32_bf16 v[0:3], v[174:177], v[206:209], v[0:3]
	v_mfma_f32_16x16x32_bf16 v[44:47], v[170:173], v[186:189], v[44:47]
	v_mfma_f32_16x16x32_bf16 v[40:43], v[178:181], v[186:189], v[40:43]
	v_mfma_f32_16x16x32_bf16 v[28:31], v[170:173], v[194:197], v[28:31]
	v_mfma_f32_16x16x32_bf16 v[24:27], v[178:181], v[194:197], v[24:27]
	v_mfma_f32_16x16x32_bf16 v[12:15], v[170:173], v[202:205], v[12:15]
	v_mfma_f32_16x16x32_bf16 v[8:11], v[178:181], v[202:205], v[8:11]
	v_mfma_f32_16x16x32_bf16 v[4:7], v[170:173], v[210:213], v[4:7]
	v_mfma_f32_16x16x32_bf16 v[0:3], v[178:181], v[210:213], v[0:3]
	s_barrier
	s_add_i32 s87, s87, 2
	s_add_u32 s56, s56, 0x100
	s_addc_u32 s57, s57, 0
	s_add_u32 s85, s85, 0x100
	s_addc_u32 s86, s86, 0
	s_cmp_gt_u32 s87, 5
	s_cbranch_scc0 .LBB0_940
	s_and_b64 vcc, exec, s[34:35]
	s_cbranch_vccz .LBB0_943
	s_barrier

.LBB0_964:
	ds_read_b128 v[150:153], v147
	ds_read_b128 v[154:157], v147 offset:1024
	ds_read_b128 v[158:161], v147 offset:2048
	ds_read_b128 v[162:165], v147 offset:3072
	ds_read_b128 v[166:169], v148
	ds_read_b128 v[170:173], v148 offset:1024
	ds_read_b128 v[174:177], v148 offset:2048
	ds_read_b128 v[178:181], v148 offset:3072
	s_add_u32 s58, s56, 0xfffc0080
	s_addc_u32 s59, s57, -1
	s_cmp_eq_u32 s85, 12
	s_cselect_b32 s61, s51, s59
	s_cselect_b32 s60, s80, s58
	s_cselect_b32 s59, s49, s83
	s_cselect_b32 s58, s81, s82
	v_lshl_add_u64 v[214:215], s[56:57], 0, v[136:137]
	s_add_i32 m0, s47, 0xc000
	ds_read_b128 v[182:185], v149
	ds_read_b128 v[186:189], v149 offset:1024
	ds_read_b128 v[190:193], v149 offset:2048
	ds_read_b128 v[194:197], v149 offset:3072
	ds_read_b128 v[198:201], v149 offset:4096
	ds_read_b128 v[202:205], v149 offset:5120
	ds_read_b128 v[206:209], v149 offset:6144
	ds_read_b128 v[210:213], v149 offset:7168
	global_load_lds_dwordx4 v[214:215], off
	v_lshl_add_u64 v[214:215], s[56:57], 0, v[138:139]
	s_add_i32 m0, s47, 0xe000
	s_nop 0
	global_load_lds_dwordx4 v[214:215], off
	s_waitcnt vmcnt(8)
	s_waitcnt lgkmcnt(0)
	s_barrier
	s_waitcnt lgkmcnt(0)
	v_mfma_f32_16x16x32_bf16 v[124:127], v[150:153], v[182:185], v[124:127]
	v_mfma_f32_16x16x32_bf16 v[120:123], v[158:161], v[182:185], v[120:123]
	v_mfma_f32_16x16x32_bf16 v[116:119], v[150:153], v[190:193], v[116:119]
	v_mfma_f32_16x16x32_bf16 v[112:115], v[158:161], v[190:193], v[112:115]
	v_mfma_f32_16x16x32_bf16 v[100:103], v[150:153], v[198:201], v[100:103]
	v_mfma_f32_16x16x32_bf16 v[96:99], v[158:161], v[198:201], v[96:99]
	v_mfma_f32_16x16x32_bf16 v[84:87], v[150:153], v[206:209], v[84:87]
	v_mfma_f32_16x16x32_bf16 v[80:83], v[158:161], v[206:209], v[80:83]
	v_mfma_f32_16x16x32_bf16 v[124:127], v[154:157], v[186:189], v[124:127]
	v_mfma_f32_16x16x32_bf16 v[120:123], v[162:165], v[186:189], v[120:123]
	v_mfma_f32_16x16x32_bf16 v[116:119], v[154:157], v[194:197], v[116:119]
	v_mfma_f32_16x16x32_bf16 v[112:115], v[162:165], v[194:197], v[112:115]
	v_mfma_f32_16x16x32_bf16 v[100:103], v[154:157], v[202:205], v[100:103]
	v_mfma_f32_16x16x32_bf16 v[96:99], v[162:165], v[202:205], v[96:99]
	v_mfma_f32_16x16x32_bf16 v[84:87], v[154:157], v[210:213], v[84:87]
	v_mfma_f32_16x16x32_bf16 v[80:83], v[162:165], v[210:213], v[80:83]
	v_mfma_f32_16x16x32_bf16 v[108:111], v[166:169], v[182:185], v[108:111]
	v_mfma_f32_16x16x32_bf16 v[104:107], v[174:177], v[182:185], v[104:107]
	v_mfma_f32_16x16x32_bf16 v[92:95], v[166:169], v[190:193], v[92:95]
	v_mfma_f32_16x16x32_bf16 v[88:91], v[174:177], v[190:193], v[88:91]
	v_mfma_f32_16x16x32_bf16 v[76:79], v[166:169], v[198:201], v[76:79]
	v_mfma_f32_16x16x32_bf16 v[72:75], v[174:177], v[198:201], v[72:75]
	v_mfma_f32_16x16x32_bf16 v[68:71], v[166:169], v[206:209], v[68:71]
	v_mfma_f32_16x16x32_bf16 v[64:67], v[174:177], v[206:209], v[64:67]
	v_mfma_f32_16x16x32_bf16 v[108:111], v[170:173], v[186:189], v[108:111]
	v_mfma_f32_16x16x32_bf16 v[104:107], v[178:181], v[186:189], v[104:107]
	v_mfma_f32_16x16x32_bf16 v[92:95], v[170:173], v[194:197], v[92:95]
	v_mfma_f32_16x16x32_bf16 v[88:91], v[178:181], v[194:197], v[88:91]
	v_mfma_f32_16x16x32_bf16 v[76:79], v[170:173], v[202:205], v[76:79]
	v_mfma_f32_16x16x32_bf16 v[72:75], v[178:181], v[202:205], v[72:75]
	v_mfma_f32_16x16x32_bf16 v[68:71], v[170:173], v[210:213], v[68:71]
	v_mfma_f32_16x16x32_bf16 v[64:67], v[178:181], v[210:213], v[64:67]
	s_barrier
	s_add_i32 s86, s71, s62
	v_lshl_add_u64 v[214:215], s[58:59], 0, v[130:131]
	s_mov_b32 m0, s86
	ds_read_b128 v[182:185], v149 offset:16384
	ds_read_b128 v[186:189], v149 offset:17408
	ds_read_b128 v[190:193], v149 offset:18432
	ds_read_b128 v[194:197], v149 offset:19456
	ds_read_b128 v[198:201], v149 offset:20480
	ds_read_b128 v[202:205], v149 offset:21504
	ds_read_b128 v[206:209], v149 offset:22528
	ds_read_b128 v[210:213], v149 offset:23552
	global_load_lds_dwordx4 v[214:215], off
	s_add_i32 m0, s86, 0x2000
	s_add_u32 s86, s58, 0x40000
	v_lshl_add_u64 v[216:217], s[58:59], 0, v[134:135]
	s_addc_u32 s87, s59, 0
	s_add_i32 s88, s72, s62
	global_load_lds_dwordx4 v[216:217], off
	v_lshl_add_u64 v[218:219], s[86:87], 0, v[130:131]
	s_mov_b32 m0, s88
	v_lshl_add_u64 v[220:221], s[60:61], 0, v[132:133]
	global_load_lds_dwordx4 v[218:219], off
	v_lshl_add_u64 v[218:219], s[86:87], 0, v[134:135]
	s_add_i32 m0, s88, 0x2000
	s_nop 0
	global_load_lds_dwordx4 v[218:219], off
	v_lshl_add_u64 v[218:219], s[60:61], 0, v[128:129]
	s_mov_b32 m0, s47
	s_nop 0
	global_load_lds_dwordx4 v[218:219], off
	s_mov_b32 m0, s63
	s_nop 0
	global_load_lds_dwordx4 v[220:221], off
	s_waitcnt vmcnt(8)
	s_waitcnt lgkmcnt(0)
	s_barrier
	s_waitcnt lgkmcnt(0)
	v_mfma_f32_16x16x32_bf16 v[60:63], v[150:153], v[182:185], v[60:63]
	v_mfma_f32_16x16x32_bf16 v[56:59], v[158:161], v[182:185], v[56:59]
	v_mfma_f32_16x16x32_bf16 v[52:55], v[150:153], v[190:193], v[52:55]
	v_mfma_f32_16x16x32_bf16 v[48:51], v[158:161], v[190:193], v[48:51]
	v_mfma_f32_16x16x32_bf16 v[36:39], v[150:153], v[198:201], v[36:39]
	v_mfma_f32_16x16x32_bf16 v[32:35], v[158:161], v[198:201], v[32:35]
	v_mfma_f32_16x16x32_bf16 v[20:23], v[150:153], v[206:209], v[20:23]
	v_mfma_f32_16x16x32_bf16 v[16:19], v[158:161], v[206:209], v[16:19]
	v_mfma_f32_16x16x32_bf16 v[60:63], v[154:157], v[186:189], v[60:63]
	v_mfma_f32_16x16x32_bf16 v[56:59], v[162:165], v[186:189], v[56:59]
	v_mfma_f32_16x16x32_bf16 v[52:55], v[154:157], v[194:197], v[52:55]
	v_mfma_f32_16x16x32_bf16 v[48:51], v[162:165], v[194:197], v[48:51]
	v_mfma_f32_16x16x32_bf16 v[36:39], v[154:157], v[202:205], v[36:39]
	v_mfma_f32_16x16x32_bf16 v[32:35], v[162:165], v[202:205], v[32:35]
	v_mfma_f32_16x16x32_bf16 v[20:23], v[154:157], v[210:213], v[20:23]
	v_mfma_f32_16x16x32_bf16 v[16:19], v[162:165], v[210:213], v[16:19]
	v_mfma_f32_16x16x32_bf16 v[44:47], v[166:169], v[182:185], v[44:47]
	v_mfma_f32_16x16x32_bf16 v[40:43], v[174:177], v[182:185], v[40:43]
	v_mfma_f32_16x16x32_bf16 v[28:31], v[166:169], v[190:193], v[28:31]
	v_mfma_f32_16x16x32_bf16 v[24:27], v[174:177], v[190:193], v[24:27]
	v_mfma_f32_16x16x32_bf16 v[12:15], v[166:169], v[198:201], v[12:15]
	v_mfma_f32_16x16x32_bf16 v[8:11], v[174:177], v[198:201], v[8:11]
	v_mfma_f32_16x16x32_bf16 v[4:7], v[166:169], v[206:209], v[4:7]
	v_mfma_f32_16x16x32_bf16 v[0:3], v[174:177], v[206:209], v[0:3]
	v_mfma_f32_16x16x32_bf16 v[44:47], v[170:173], v[186:189], v[44:47]
	v_mfma_f32_16x16x32_bf16 v[40:43], v[178:181], v[186:189], v[40:43]
	v_mfma_f32_16x16x32_bf16 v[28:31], v[170:173], v[194:197], v[28:31]
	v_mfma_f32_16x16x32_bf16 v[24:27], v[178:181], v[194:197], v[24:27]
	v_mfma_f32_16x16x32_bf16 v[12:15], v[170:173], v[202:205], v[12:15]
	v_mfma_f32_16x16x32_bf16 v[8:11], v[178:181], v[202:205], v[8:11]
	v_mfma_f32_16x16x32_bf16 v[4:7], v[170:173], v[210:213], v[4:7]
	v_mfma_f32_16x16x32_bf16 v[0:3], v[178:181], v[210:213], v[0:3]
	s_barrier
	s_add_i32 s86, 0, 0x18000
	s_add_i32 s87, 0, 0x1c000
	v_add_u32_e32 v162, s86, v145
	v_add_u32_e32 v178, s87, v145
	ds_read_b128 v[150:153], v162
	ds_read_b128 v[154:157], v162 offset:1024
	ds_read_b128 v[158:161], v162 offset:2048
	ds_read_b128 v[162:165], v162 offset:3072
	ds_read_b128 v[166:169], v178
	ds_read_b128 v[170:173], v178 offset:1024
	ds_read_b128 v[174:177], v178 offset:2048
	ds_read_b128 v[178:181], v178 offset:3072
	s_add_u32 s60, s60, 0x40000
	s_addc_u32 s61, s61, 0
	s_mov_b32 m0, s64
	v_lshl_add_u64 v[222:223], s[60:61], 0, v[128:129]
	ds_read_b128 v[182:185], v149 offset:32768
	ds_read_b128 v[186:189], v149 offset:33792
	ds_read_b128 v[190:193], v149 offset:34816
	ds_read_b128 v[194:197], v149 offset:35840
	ds_read_b128 v[198:201], v149 offset:36864
	ds_read_b128 v[202:205], v149 offset:37888
	ds_read_b128 v[206:209], v149 offset:38912
	ds_read_b128 v[210:213], v149 offset:39936
	global_load_lds_dwordx4 v[222:223], off
	v_lshl_add_u64 v[222:223], s[60:61], 0, v[132:133]
	s_mov_b32 m0, s65
	s_nop 0
	global_load_lds_dwordx4 v[222:223], off
	s_waitcnt vmcnt(8)
	s_waitcnt lgkmcnt(0)
	s_barrier
	s_waitcnt lgkmcnt(0)
	v_mfma_f32_16x16x32_bf16 v[124:127], v[150:153], v[182:185], v[124:127]
	v_mfma_f32_16x16x32_bf16 v[120:123], v[158:161], v[182:185], v[120:123]
	v_mfma_f32_16x16x32_bf16 v[116:119], v[150:153], v[190:193], v[116:119]
	v_mfma_f32_16x16x32_bf16 v[112:115], v[158:161], v[190:193], v[112:115]
	v_mfma_f32_16x16x32_bf16 v[100:103], v[150:153], v[198:201], v[100:103]
	v_mfma_f32_16x16x32_bf16 v[96:99], v[158:161], v[198:201], v[96:99]
	v_mfma_f32_16x16x32_bf16 v[84:87], v[150:153], v[206:209], v[84:87]
	v_mfma_f32_16x16x32_bf16 v[80:83], v[158:161], v[206:209], v[80:83]
	v_mfma_f32_16x16x32_bf16 v[124:127], v[154:157], v[186:189], v[124:127]
	v_mfma_f32_16x16x32_bf16 v[120:123], v[162:165], v[186:189], v[120:123]
	v_mfma_f32_16x16x32_bf16 v[116:119], v[154:157], v[194:197], v[116:119]
	v_mfma_f32_16x16x32_bf16 v[112:115], v[162:165], v[194:197], v[112:115]
	v_mfma_f32_16x16x32_bf16 v[100:103], v[154:157], v[202:205], v[100:103]
	v_mfma_f32_16x16x32_bf16 v[96:99], v[162:165], v[202:205], v[96:99]
	v_mfma_f32_16x16x32_bf16 v[84:87], v[154:157], v[210:213], v[84:87]
	v_mfma_f32_16x16x32_bf16 v[80:83], v[162:165], v[210:213], v[80:83]
	v_mfma_f32_16x16x32_bf16 v[108:111], v[166:169], v[182:185], v[108:111]
	v_mfma_f32_16x16x32_bf16 v[104:107], v[174:177], v[182:185], v[104:107]
	v_mfma_f32_16x16x32_bf16 v[92:95], v[166:169], v[190:193], v[92:95]
	v_mfma_f32_16x16x32_bf16 v[88:91], v[174:177], v[190:193], v[88:91]
	v_mfma_f32_16x16x32_bf16 v[76:79], v[166:169], v[198:201], v[76:79]
	v_mfma_f32_16x16x32_bf16 v[72:75], v[174:177], v[198:201], v[72:75]
	v_mfma_f32_16x16x32_bf16 v[68:71], v[166:169], v[206:209], v[68:71]
	v_mfma_f32_16x16x32_bf16 v[64:67], v[174:177], v[206:209], v[64:67]
	v_mfma_f32_16x16x32_bf16 v[108:111], v[170:173], v[186:189], v[108:111]
	v_mfma_f32_16x16x32_bf16 v[104:107], v[178:181], v[186:189], v[104:107]
	v_mfma_f32_16x16x32_bf16 v[92:95], v[170:173], v[194:197], v[92:95]
	v_mfma_f32_16x16x32_bf16 v[88:91], v[178:181], v[194:197], v[88:91]
	v_mfma_f32_16x16x32_bf16 v[76:79], v[170:173], v[202:205], v[76:79]
	v_mfma_f32_16x16x32_bf16 v[72:75], v[178:181], v[202:205], v[72:75]
	v_mfma_f32_16x16x32_bf16 v[68:71], v[170:173], v[210:213], v[68:71]
	v_mfma_f32_16x16x32_bf16 v[64:67], v[178:181], v[210:213], v[64:67]
	s_barrier
	s_add_i32 s60, s86, s62
	v_lshl_add_u64 v[214:215], v[214:215], 0, s[34:35]
	s_mov_b32 m0, s60
	ds_read_b128 v[182:185], v149 offset:49152
	ds_read_b128 v[186:189], v149 offset:50176
	ds_read_b128 v[190:193], v149 offset:51200
	ds_read_b128 v[194:197], v149 offset:52224
	ds_read_b128 v[198:201], v149 offset:53248
	ds_read_b128 v[202:205], v149 offset:54272
	ds_read_b128 v[206:209], v149 offset:55296
	ds_read_b128 v[210:213], v149 offset:56320
	global_load_lds_dwordx4 v[214:215], off
	s_add_i32 m0, s60, 0x2000
	s_add_u32 s58, s58, 0x40080
	v_lshl_add_u64 v[214:215], v[216:217], 0, s[34:35]
	s_addc_u32 s59, s59, 0
	s_add_i32 s60, s87, s62
	global_load_lds_dwordx4 v[214:215], off
	v_lshl_add_u64 v[214:215], s[58:59], 0, v[130:131]
	s_mov_b32 m0, s60
	s_nop 0
	global_load_lds_dwordx4 v[214:215], off
	v_lshl_add_u64 v[214:215], s[58:59], 0, v[134:135]
	s_add_i32 m0, s60, 0x2000
	s_nop 0
	global_load_lds_dwordx4 v[214:215], off
	v_lshl_add_u64 v[214:215], v[218:219], 0, s[34:35]
	s_mov_b32 m0, s67
	s_nop 0
	global_load_lds_dwordx4 v[214:215], off
	v_lshl_add_u64 v[214:215], v[220:221], 0, s[34:35]
	s_mov_b32 m0, s68
	s_nop 0
	global_load_lds_dwordx4 v[214:215], off
	s_waitcnt vmcnt(8)
	s_waitcnt lgkmcnt(0)
	s_barrier
	s_waitcnt lgkmcnt(0)
	v_mfma_f32_16x16x32_bf16 v[60:63], v[150:153], v[182:185], v[60:63]
	v_mfma_f32_16x16x32_bf16 v[56:59], v[158:161], v[182:185], v[56:59]
	v_mfma_f32_16x16x32_bf16 v[52:55], v[150:153], v[190:193], v[52:55]
	v_mfma_f32_16x16x32_bf16 v[48:51], v[158:161], v[190:193], v[48:51]
	v_mfma_f32_16x16x32_bf16 v[36:39], v[150:153], v[198:201], v[36:39]
	v_mfma_f32_16x16x32_bf16 v[32:35], v[158:161], v[198:201], v[32:35]
	v_mfma_f32_16x16x32_bf16 v[20:23], v[150:153], v[206:209], v[20:23]
	v_mfma_f32_16x16x32_bf16 v[16:19], v[158:161], v[206:209], v[16:19]
	v_mfma_f32_16x16x32_bf16 v[60:63], v[154:157], v[186:189], v[60:63]
	v_mfma_f32_16x16x32_bf16 v[56:59], v[162:165], v[186:189], v[56:59]
	v_mfma_f32_16x16x32_bf16 v[52:55], v[154:157], v[194:197], v[52:55]
	v_mfma_f32_16x16x32_bf16 v[48:51], v[162:165], v[194:197], v[48:51]
	v_mfma_f32_16x16x32_bf16 v[36:39], v[154:157], v[202:205], v[36:39]
	v_mfma_f32_16x16x32_bf16 v[32:35], v[162:165], v[202:205], v[32:35]
	v_mfma_f32_16x16x32_bf16 v[20:23], v[154:157], v[210:213], v[20:23]
	v_mfma_f32_16x16x32_bf16 v[16:19], v[162:165], v[210:213], v[16:19]
	v_mfma_f32_16x16x32_bf16 v[44:47], v[166:169], v[182:185], v[44:47]
	v_mfma_f32_16x16x32_bf16 v[40:43], v[174:177], v[182:185], v[40:43]
	v_mfma_f32_16x16x32_bf16 v[28:31], v[166:169], v[190:193], v[28:31]
	v_mfma_f32_16x16x32_bf16 v[24:27], v[174:177], v[190:193], v[24:27]
	v_mfma_f32_16x16x32_bf16 v[12:15], v[166:169], v[198:201], v[12:15]
	v_mfma_f32_16x16x32_bf16 v[8:11], v[174:177], v[198:201], v[8:11]
	v_mfma_f32_16x16x32_bf16 v[4:7], v[166:169], v[206:209], v[4:7]
	v_mfma_f32_16x16x32_bf16 v[0:3], v[174:177], v[206:209], v[0:3]
	v_mfma_f32_16x16x32_bf16 v[44:47], v[170:173], v[186:189], v[44:47]
	v_mfma_f32_16x16x32_bf16 v[40:43], v[178:181], v[186:189], v[40:43]
	v_mfma_f32_16x16x32_bf16 v[28:31], v[170:173], v[194:197], v[28:31]
	v_mfma_f32_16x16x32_bf16 v[24:27], v[178:181], v[194:197], v[24:27]
	v_mfma_f32_16x16x32_bf16 v[12:15], v[170:173], v[202:205], v[12:15]
	v_mfma_f32_16x16x32_bf16 v[8:11], v[178:181], v[202:205], v[8:11]
	v_mfma_f32_16x16x32_bf16 v[4:7], v[170:173], v[210:213], v[4:7]
	v_mfma_f32_16x16x32_bf16 v[0:3], v[178:181], v[210:213], v[0:3]
	s_barrier
	s_add_i32 s85, s85, 2
	s_add_u32 s56, s56, 0x100
	s_addc_u32 s57, s57, 0
	s_add_u32 s82, s82, 0x100
	s_addc_u32 s83, s83, 0
	s_cmp_gt_u32 s85, 13
	s_cbranch_scc0 .LBB0_964
	s_and_b64 vcc, exec, s[38:39]
	s_cbranch_vccz .LBB0_967
	s_barrier

.LBB0_1042:
	ds_read_b128 v[128:131], v185
	ds_read_b128 v[132:135], v185 offset:1024
	ds_read_b128 v[136:139], v185 offset:2048
	ds_read_b128 v[140:143], v185 offset:3072
	ds_read_b128 v[144:147], v186
	ds_read_b128 v[148:151], v186 offset:1024
	ds_read_b128 v[172:175], v186 offset:2048
	ds_read_b128 v[176:179], v186 offset:3072
	s_add_u32 s56, s54, 0xfffc0080
	s_addc_u32 s57, s55, -1
	s_cmp_eq_u32 s53, 12
	s_cselect_b32 s59, s0, s57
	s_cselect_b32 s58, s8, s56
	s_cselect_b32 s57, s9, s51
	s_cselect_b32 s56, s43, s45
	v_lshl_add_u64 v[180:181], s[54:55], 0, v[164:165]
	s_add_i32 m0, s64, 0xc000
	ds_read_b128 v[190:193], v187
	ds_read_b128 v[194:197], v187 offset:1024
	ds_read_b128 v[198:201], v187 offset:2048
	ds_read_b128 v[202:205], v187 offset:3072
	ds_read_b128 v[206:209], v187 offset:4096
	ds_read_b128 v[210:213], v187 offset:5120
	ds_read_b128 v[214:217], v187 offset:6144
	ds_read_b128 v[218:221], v187 offset:7168
	global_load_lds_dwordx4 v[180:181], off
	v_lshl_add_u64 v[180:181], s[54:55], 0, v[166:167]
	s_add_i32 m0, s64, 0xe000
	s_nop 0
	global_load_lds_dwordx4 v[180:181], off
	s_waitcnt vmcnt(8)
	s_waitcnt lgkmcnt(0)
	s_barrier
	s_waitcnt lgkmcnt(0)
	v_mfma_f32_16x16x32_bf16 v[124:127], v[128:131], v[190:193], v[124:127]
	v_mfma_f32_16x16x32_bf16 v[120:123], v[136:139], v[190:193], v[120:123]
	v_mfma_f32_16x16x32_bf16 v[108:111], v[128:131], v[198:201], v[108:111]
	v_mfma_f32_16x16x32_bf16 v[104:107], v[136:139], v[198:201], v[104:107]
	v_mfma_f32_16x16x32_bf16 v[92:95], v[128:131], v[206:209], v[92:95]
	v_mfma_f32_16x16x32_bf16 v[88:91], v[136:139], v[206:209], v[88:91]
	v_mfma_f32_16x16x32_bf16 v[76:79], v[128:131], v[214:217], v[76:79]
	v_mfma_f32_16x16x32_bf16 v[72:75], v[136:139], v[214:217], v[72:75]
	v_mfma_f32_16x16x32_bf16 v[124:127], v[132:135], v[194:197], v[124:127]
	v_mfma_f32_16x16x32_bf16 v[120:123], v[140:143], v[194:197], v[120:123]
	v_mfma_f32_16x16x32_bf16 v[108:111], v[132:135], v[202:205], v[108:111]
	v_mfma_f32_16x16x32_bf16 v[104:107], v[140:143], v[202:205], v[104:107]
	v_mfma_f32_16x16x32_bf16 v[92:95], v[132:135], v[210:213], v[92:95]
	v_mfma_f32_16x16x32_bf16 v[88:91], v[140:143], v[210:213], v[88:91]
	v_mfma_f32_16x16x32_bf16 v[76:79], v[132:135], v[218:221], v[76:79]
	v_mfma_f32_16x16x32_bf16 v[72:75], v[140:143], v[218:221], v[72:75]
	v_mfma_f32_16x16x32_bf16 v[116:119], v[144:147], v[190:193], v[116:119]
	v_mfma_f32_16x16x32_bf16 v[112:115], v[172:175], v[190:193], v[112:115]
	v_mfma_f32_16x16x32_bf16 v[100:103], v[144:147], v[198:201], v[100:103]
	v_mfma_f32_16x16x32_bf16 v[96:99], v[172:175], v[198:201], v[96:99]
	v_mfma_f32_16x16x32_bf16 v[84:87], v[144:147], v[206:209], v[84:87]
	v_mfma_f32_16x16x32_bf16 v[80:83], v[172:175], v[206:209], v[80:83]
	v_mfma_f32_16x16x32_bf16 v[68:71], v[144:147], v[214:217], v[68:71]
	v_mfma_f32_16x16x32_bf16 v[64:67], v[172:175], v[214:217], v[64:67]
	v_mfma_f32_16x16x32_bf16 v[116:119], v[148:151], v[194:197], v[116:119]
	v_mfma_f32_16x16x32_bf16 v[112:115], v[176:179], v[194:197], v[112:115]
	v_mfma_f32_16x16x32_bf16 v[100:103], v[148:151], v[202:205], v[100:103]
	v_mfma_f32_16x16x32_bf16 v[96:99], v[176:179], v[202:205], v[96:99]
	v_mfma_f32_16x16x32_bf16 v[84:87], v[148:151], v[210:213], v[84:87]
	v_mfma_f32_16x16x32_bf16 v[80:83], v[176:179], v[210:213], v[80:83]
	v_mfma_f32_16x16x32_bf16 v[68:71], v[148:151], v[218:221], v[68:71]
	v_mfma_f32_16x16x32_bf16 v[64:67], v[176:179], v[218:221], v[64:67]
	s_barrier
	s_add_i32 s60, s74, s63
	v_lshl_add_u64 v[180:181], s[56:57], 0, v[154:155]
	s_mov_b32 m0, s60
	ds_read_b128 v[190:193], v187 offset:16384
	ds_read_b128 v[194:197], v187 offset:17408
	ds_read_b128 v[198:201], v187 offset:18432
	ds_read_b128 v[202:205], v187 offset:19456
	ds_read_b128 v[206:209], v187 offset:20480
	ds_read_b128 v[210:213], v187 offset:21504
	ds_read_b128 v[214:217], v187 offset:22528
	ds_read_b128 v[218:221], v187 offset:23552
	global_load_lds_dwordx4 v[180:181], off
	s_add_i32 m0, s60, 0x2000
	s_add_u32 s60, s56, 0x40000
	v_lshl_add_u64 v[222:223], s[56:57], 0, v[158:159]
	s_addc_u32 s61, s57, 0
	s_add_i32 s82, s75, s63
	global_load_lds_dwordx4 v[222:223], off
	v_lshl_add_u64 v[224:225], s[60:61], 0, v[154:155]
	s_mov_b32 m0, s82
	v_lshl_add_u64 v[226:227], s[58:59], 0, v[156:157]
	global_load_lds_dwordx4 v[224:225], off
	v_lshl_add_u64 v[224:225], s[60:61], 0, v[158:159]
	s_add_i32 m0, s82, 0x2000
	s_nop 0
	global_load_lds_dwordx4 v[224:225], off
	v_lshl_add_u64 v[224:225], s[58:59], 0, v[152:153]
	s_mov_b32 m0, s64
	s_nop 0
	global_load_lds_dwordx4 v[224:225], off
	s_mov_b32 m0, s65
	s_nop 0
	global_load_lds_dwordx4 v[226:227], off
	s_waitcnt vmcnt(8)
	s_waitcnt lgkmcnt(0)
	s_barrier
	s_waitcnt lgkmcnt(0)
	v_mfma_f32_16x16x32_bf16 v[60:63], v[128:131], v[190:193], v[60:63]
	v_mfma_f32_16x16x32_bf16 v[56:59], v[136:139], v[190:193], v[56:59]
	v_mfma_f32_16x16x32_bf16 v[44:47], v[128:131], v[198:201], v[44:47]
	v_mfma_f32_16x16x32_bf16 v[40:43], v[136:139], v[198:201], v[40:43]
	v_mfma_f32_16x16x32_bf16 v[28:31], v[128:131], v[206:209], v[28:31]
	v_mfma_f32_16x16x32_bf16 v[24:27], v[136:139], v[206:209], v[24:27]
	v_mfma_f32_16x16x32_bf16 v[12:15], v[128:131], v[214:217], v[12:15]
	v_mfma_f32_16x16x32_bf16 v[8:11], v[136:139], v[214:217], v[8:11]
	v_mfma_f32_16x16x32_bf16 v[60:63], v[132:135], v[194:197], v[60:63]
	v_mfma_f32_16x16x32_bf16 v[56:59], v[140:143], v[194:197], v[56:59]
	v_mfma_f32_16x16x32_bf16 v[44:47], v[132:135], v[202:205], v[44:47]
	v_mfma_f32_16x16x32_bf16 v[40:43], v[140:143], v[202:205], v[40:43]
	v_mfma_f32_16x16x32_bf16 v[28:31], v[132:135], v[210:213], v[28:31]
	v_mfma_f32_16x16x32_bf16 v[24:27], v[140:143], v[210:213], v[24:27]
	v_mfma_f32_16x16x32_bf16 v[12:15], v[132:135], v[218:221], v[12:15]
	v_mfma_f32_16x16x32_bf16 v[8:11], v[140:143], v[218:221], v[8:11]
	v_mfma_f32_16x16x32_bf16 v[52:55], v[144:147], v[190:193], v[52:55]
	v_mfma_f32_16x16x32_bf16 v[48:51], v[172:175], v[190:193], v[48:51]
	v_mfma_f32_16x16x32_bf16 v[36:39], v[144:147], v[198:201], v[36:39]
	v_mfma_f32_16x16x32_bf16 v[32:35], v[172:175], v[198:201], v[32:35]
	v_mfma_f32_16x16x32_bf16 v[20:23], v[144:147], v[206:209], v[20:23]
	v_mfma_f32_16x16x32_bf16 v[16:19], v[172:175], v[206:209], v[16:19]
	v_mfma_f32_16x16x32_bf16 v[4:7], v[144:147], v[214:217], v[4:7]
	v_mfma_f32_16x16x32_bf16 v[0:3], v[172:175], v[214:217], v[0:3]
	v_mfma_f32_16x16x32_bf16 v[52:55], v[148:151], v[194:197], v[52:55]
	v_mfma_f32_16x16x32_bf16 v[48:51], v[176:179], v[194:197], v[48:51]
	v_mfma_f32_16x16x32_bf16 v[36:39], v[148:151], v[202:205], v[36:39]
	v_mfma_f32_16x16x32_bf16 v[32:35], v[176:179], v[202:205], v[32:35]
	v_mfma_f32_16x16x32_bf16 v[20:23], v[148:151], v[210:213], v[20:23]
	v_mfma_f32_16x16x32_bf16 v[16:19], v[176:179], v[210:213], v[16:19]
	v_mfma_f32_16x16x32_bf16 v[4:7], v[148:151], v[218:221], v[4:7]
	v_mfma_f32_16x16x32_bf16 v[0:3], v[176:179], v[218:221], v[0:3]
	s_barrier
	s_add_i32 s60, 0, 0x18000
	s_add_i32 s61, 0, 0x1c000
	v_add_u32_e32 v140, s60, v182
	v_add_u32_e32 v160, s61, v182
	ds_read_b128 v[128:131], v140
	ds_read_b128 v[132:135], v140 offset:1024
	ds_read_b128 v[136:139], v140 offset:2048
	ds_read_b128 v[140:143], v140 offset:3072
	ds_read_b128 v[144:147], v160
	ds_read_b128 v[148:151], v160 offset:1024
	ds_read_b128 v[172:175], v160 offset:2048
	ds_read_b128 v[176:179], v160 offset:3072
	s_add_u32 s58, s58, 0x40000
	s_addc_u32 s59, s59, 0
	s_mov_b32 m0, s66
	v_lshl_add_u64 v[228:229], s[58:59], 0, v[152:153]
	ds_read_b128 v[190:193], v187 offset:32768
	ds_read_b128 v[194:197], v187 offset:33792
	ds_read_b128 v[198:201], v187 offset:34816
	ds_read_b128 v[202:205], v187 offset:35840
	ds_read_b128 v[206:209], v187 offset:36864
	ds_read_b128 v[210:213], v187 offset:37888
	ds_read_b128 v[214:217], v187 offset:38912
	ds_read_b128 v[218:221], v187 offset:39936
	global_load_lds_dwordx4 v[228:229], off
	v_lshl_add_u64 v[228:229], s[58:59], 0, v[156:157]
	s_mov_b32 m0, s67
	s_nop 0
	global_load_lds_dwordx4 v[228:229], off
	s_waitcnt vmcnt(8)
	s_waitcnt lgkmcnt(0)
	s_barrier
	s_waitcnt lgkmcnt(0)
	v_mfma_f32_16x16x32_bf16 v[124:127], v[128:131], v[190:193], v[124:127]
	v_mfma_f32_16x16x32_bf16 v[120:123], v[136:139], v[190:193], v[120:123]
	v_mfma_f32_16x16x32_bf16 v[108:111], v[128:131], v[198:201], v[108:111]
	v_mfma_f32_16x16x32_bf16 v[104:107], v[136:139], v[198:201], v[104:107]
	v_mfma_f32_16x16x32_bf16 v[92:95], v[128:131], v[206:209], v[92:95]
	v_mfma_f32_16x16x32_bf16 v[88:91], v[136:139], v[206:209], v[88:91]
	v_mfma_f32_16x16x32_bf16 v[76:79], v[128:131], v[214:217], v[76:79]
	v_mfma_f32_16x16x32_bf16 v[72:75], v[136:139], v[214:217], v[72:75]
	v_mfma_f32_16x16x32_bf16 v[124:127], v[132:135], v[194:197], v[124:127]
	v_mfma_f32_16x16x32_bf16 v[120:123], v[140:143], v[194:197], v[120:123]
	v_mfma_f32_16x16x32_bf16 v[108:111], v[132:135], v[202:205], v[108:111]
	v_mfma_f32_16x16x32_bf16 v[104:107], v[140:143], v[202:205], v[104:107]
	v_mfma_f32_16x16x32_bf16 v[92:95], v[132:135], v[210:213], v[92:95]
	v_mfma_f32_16x16x32_bf16 v[88:91], v[140:143], v[210:213], v[88:91]
	v_mfma_f32_16x16x32_bf16 v[76:79], v[132:135], v[218:221], v[76:79]
	v_mfma_f32_16x16x32_bf16 v[72:75], v[140:143], v[218:221], v[72:75]
	v_mfma_f32_16x16x32_bf16 v[116:119], v[144:147], v[190:193], v[116:119]
	v_mfma_f32_16x16x32_bf16 v[112:115], v[172:175], v[190:193], v[112:115]
	v_mfma_f32_16x16x32_bf16 v[100:103], v[144:147], v[198:201], v[100:103]
	v_mfma_f32_16x16x32_bf16 v[96:99], v[172:175], v[198:201], v[96:99]
	v_mfma_f32_16x16x32_bf16 v[84:87], v[144:147], v[206:209], v[84:87]
	v_mfma_f32_16x16x32_bf16 v[80:83], v[172:175], v[206:209], v[80:83]
	v_mfma_f32_16x16x32_bf16 v[68:71], v[144:147], v[214:217], v[68:71]
	v_mfma_f32_16x16x32_bf16 v[64:67], v[172:175], v[214:217], v[64:67]
	v_mfma_f32_16x16x32_bf16 v[116:119], v[148:151], v[194:197], v[116:119]
	v_mfma_f32_16x16x32_bf16 v[112:115], v[176:179], v[194:197], v[112:115]
	v_mfma_f32_16x16x32_bf16 v[100:103], v[148:151], v[202:205], v[100:103]
	v_mfma_f32_16x16x32_bf16 v[96:99], v[176:179], v[202:205], v[96:99]
	v_mfma_f32_16x16x32_bf16 v[84:87], v[148:151], v[210:213], v[84:87]
	v_mfma_f32_16x16x32_bf16 v[80:83], v[176:179], v[210:213], v[80:83]
	v_mfma_f32_16x16x32_bf16 v[68:71], v[148:151], v[218:221], v[68:71]
	v_mfma_f32_16x16x32_bf16 v[64:67], v[176:179], v[218:221], v[64:67]
	s_barrier
	s_add_i32 s58, s60, s63
	v_lshl_add_u64 v[180:181], v[180:181], 0, s[20:21]
	s_mov_b32 m0, s58
	ds_read_b128 v[190:193], v187 offset:49152
	ds_read_b128 v[194:197], v187 offset:50176
	ds_read_b128 v[198:201], v187 offset:51200
	ds_read_b128 v[202:205], v187 offset:52224
	ds_read_b128 v[206:209], v187 offset:53248
	ds_read_b128 v[210:213], v187 offset:54272
	ds_read_b128 v[214:217], v187 offset:55296
	ds_read_b128 v[218:221], v187 offset:56320
	global_load_lds_dwordx4 v[180:181], off
	s_add_i32 m0, s58, 0x2000
	s_add_u32 s56, s56, 0x40080
	v_lshl_add_u64 v[180:181], v[222:223], 0, s[20:21]
	s_addc_u32 s57, s57, 0
	s_add_i32 s58, s61, s63
	global_load_lds_dwordx4 v[180:181], off
	v_lshl_add_u64 v[180:181], s[56:57], 0, v[154:155]
	s_mov_b32 m0, s58
	s_nop 0
	global_load_lds_dwordx4 v[180:181], off
	v_lshl_add_u64 v[180:181], s[56:57], 0, v[158:159]
	s_add_i32 m0, s58, 0x2000
	s_nop 0
	global_load_lds_dwordx4 v[180:181], off
	v_lshl_add_u64 v[180:181], v[224:225], 0, s[20:21]
	s_mov_b32 m0, s69
	s_nop 0
	global_load_lds_dwordx4 v[180:181], off
	v_lshl_add_u64 v[180:181], v[226:227], 0, s[20:21]
	s_mov_b32 m0, s70
	s_nop 0
	global_load_lds_dwordx4 v[180:181], off
	s_waitcnt vmcnt(8)
	s_waitcnt lgkmcnt(0)
	s_barrier
	s_waitcnt lgkmcnt(0)
	v_mfma_f32_16x16x32_bf16 v[60:63], v[128:131], v[190:193], v[60:63]
	v_mfma_f32_16x16x32_bf16 v[56:59], v[136:139], v[190:193], v[56:59]
	v_mfma_f32_16x16x32_bf16 v[44:47], v[128:131], v[198:201], v[44:47]
	v_mfma_f32_16x16x32_bf16 v[40:43], v[136:139], v[198:201], v[40:43]
	v_mfma_f32_16x16x32_bf16 v[28:31], v[128:131], v[206:209], v[28:31]
	v_mfma_f32_16x16x32_bf16 v[24:27], v[136:139], v[206:209], v[24:27]
	v_mfma_f32_16x16x32_bf16 v[12:15], v[128:131], v[214:217], v[12:15]
	v_mfma_f32_16x16x32_bf16 v[8:11], v[136:139], v[214:217], v[8:11]
	v_mfma_f32_16x16x32_bf16 v[60:63], v[132:135], v[194:197], v[60:63]
	v_mfma_f32_16x16x32_bf16 v[56:59], v[140:143], v[194:197], v[56:59]
	v_mfma_f32_16x16x32_bf16 v[44:47], v[132:135], v[202:205], v[44:47]
	v_mfma_f32_16x16x32_bf16 v[40:43], v[140:143], v[202:205], v[40:43]
	v_mfma_f32_16x16x32_bf16 v[28:31], v[132:135], v[210:213], v[28:31]
	v_mfma_f32_16x16x32_bf16 v[24:27], v[140:143], v[210:213], v[24:27]
	v_mfma_f32_16x16x32_bf16 v[12:15], v[132:135], v[218:221], v[12:15]
	v_mfma_f32_16x16x32_bf16 v[8:11], v[140:143], v[218:221], v[8:11]
	v_mfma_f32_16x16x32_bf16 v[52:55], v[144:147], v[190:193], v[52:55]
	v_mfma_f32_16x16x32_bf16 v[48:51], v[172:175], v[190:193], v[48:51]
	v_mfma_f32_16x16x32_bf16 v[36:39], v[144:147], v[198:201], v[36:39]
	v_mfma_f32_16x16x32_bf16 v[32:35], v[172:175], v[198:201], v[32:35]
	v_mfma_f32_16x16x32_bf16 v[20:23], v[144:147], v[206:209], v[20:23]
	v_mfma_f32_16x16x32_bf16 v[16:19], v[172:175], v[206:209], v[16:19]
	v_mfma_f32_16x16x32_bf16 v[4:7], v[144:147], v[214:217], v[4:7]
	v_mfma_f32_16x16x32_bf16 v[0:3], v[172:175], v[214:217], v[0:3]
	v_mfma_f32_16x16x32_bf16 v[52:55], v[148:151], v[194:197], v[52:55]
	v_mfma_f32_16x16x32_bf16 v[48:51], v[176:179], v[194:197], v[48:51]
	v_mfma_f32_16x16x32_bf16 v[36:39], v[148:151], v[202:205], v[36:39]
	v_mfma_f32_16x16x32_bf16 v[32:35], v[176:179], v[202:205], v[32:35]
	v_mfma_f32_16x16x32_bf16 v[20:23], v[148:151], v[210:213], v[20:23]
	v_mfma_f32_16x16x32_bf16 v[16:19], v[176:179], v[210:213], v[16:19]
	v_mfma_f32_16x16x32_bf16 v[4:7], v[148:151], v[218:221], v[4:7]
	v_mfma_f32_16x16x32_bf16 v[0:3], v[176:179], v[218:221], v[0:3]
	s_barrier
	s_add_i32 s53, s53, 2
	s_add_u32 s54, s54, 0x100
	s_addc_u32 s55, s55, 0
	s_add_u32 s45, s45, 0x100
	s_addc_u32 s51, s51, 0
	s_cmp_gt_u32 s53, 13
	s_cbranch_scc0 .LBB0_1042
	s_and_b64 vcc, exec, s[22:23]
	s_cbranch_vccz .LBB0_1045
	s_barrier

.LBB0_1150:
	ds_read_b128 v[128:131], v167
	ds_read_b128 v[132:135], v167 offset:1024
	ds_read_b128 v[136:139], v167 offset:2048
	ds_read_b128 v[140:143], v167 offset:3072
	ds_read_b128 v[156:159], v168
	ds_read_b128 v[160:163], v168 offset:1024
	ds_read_b128 v[170:173], v168 offset:2048
	ds_read_b128 v[174:177], v168 offset:3072
	s_add_u32 s50, s48, 0xfffc0080
	s_addc_u32 s51, s49, -1
	s_cmp_eq_u32 s70, 12
	s_cselect_b32 s53, s8, s51
	s_cselect_b32 s52, s9, s50
	s_cselect_b32 s51, s39, s69
	s_cselect_b32 s50, s41, s47
	v_lshl_add_u64 v[210:211], s[48:49], 0, v[148:149]
	s_add_i32 m0, s56, 0xc000
	ds_read_b128 v[178:181], v169
	ds_read_b128 v[182:185], v169 offset:1024
	ds_read_b128 v[186:189], v169 offset:2048
	ds_read_b128 v[190:193], v169 offset:3072
	ds_read_b128 v[194:197], v169 offset:4096
	ds_read_b128 v[198:201], v169 offset:5120
	ds_read_b128 v[202:205], v169 offset:6144
	ds_read_b128 v[206:209], v169 offset:7168
	global_load_lds_dwordx4 v[210:211], off
	v_lshl_add_u64 v[210:211], s[48:49], 0, v[150:151]
	s_add_i32 m0, s56, 0xe000
	s_nop 0
	global_load_lds_dwordx4 v[210:211], off
	s_waitcnt vmcnt(8)
	s_waitcnt lgkmcnt(0)
	s_barrier
	s_waitcnt lgkmcnt(0)
	v_mfma_f32_16x16x32_bf16 v[124:127], v[128:131], v[178:181], v[124:127]
	v_mfma_f32_16x16x32_bf16 v[120:123], v[136:139], v[178:181], v[120:123]
	v_mfma_f32_16x16x32_bf16 v[108:111], v[128:131], v[186:189], v[108:111]
	v_mfma_f32_16x16x32_bf16 v[104:107], v[136:139], v[186:189], v[104:107]
	v_mfma_f32_16x16x32_bf16 v[92:95], v[128:131], v[194:197], v[92:95]
	v_mfma_f32_16x16x32_bf16 v[88:91], v[136:139], v[194:197], v[88:91]
	v_mfma_f32_16x16x32_bf16 v[76:79], v[128:131], v[202:205], v[76:79]
	v_mfma_f32_16x16x32_bf16 v[72:75], v[136:139], v[202:205], v[72:75]
	v_mfma_f32_16x16x32_bf16 v[124:127], v[132:135], v[182:185], v[124:127]
	v_mfma_f32_16x16x32_bf16 v[120:123], v[140:143], v[182:185], v[120:123]
	v_mfma_f32_16x16x32_bf16 v[108:111], v[132:135], v[190:193], v[108:111]
	v_mfma_f32_16x16x32_bf16 v[104:107], v[140:143], v[190:193], v[104:107]
	v_mfma_f32_16x16x32_bf16 v[92:95], v[132:135], v[198:201], v[92:95]
	v_mfma_f32_16x16x32_bf16 v[88:91], v[140:143], v[198:201], v[88:91]
	v_mfma_f32_16x16x32_bf16 v[76:79], v[132:135], v[206:209], v[76:79]
	v_mfma_f32_16x16x32_bf16 v[72:75], v[140:143], v[206:209], v[72:75]
	v_mfma_f32_16x16x32_bf16 v[116:119], v[156:159], v[178:181], v[116:119]
	v_mfma_f32_16x16x32_bf16 v[112:115], v[170:173], v[178:181], v[112:115]
	v_mfma_f32_16x16x32_bf16 v[100:103], v[156:159], v[186:189], v[100:103]
	v_mfma_f32_16x16x32_bf16 v[96:99], v[170:173], v[186:189], v[96:99]
	v_mfma_f32_16x16x32_bf16 v[84:87], v[156:159], v[194:197], v[84:87]
	v_mfma_f32_16x16x32_bf16 v[80:83], v[170:173], v[194:197], v[80:83]
	v_mfma_f32_16x16x32_bf16 v[68:71], v[156:159], v[202:205], v[68:71]
	v_mfma_f32_16x16x32_bf16 v[64:67], v[170:173], v[202:205], v[64:67]
	v_mfma_f32_16x16x32_bf16 v[116:119], v[160:163], v[182:185], v[116:119]
	v_mfma_f32_16x16x32_bf16 v[112:115], v[174:177], v[182:185], v[112:115]
	v_mfma_f32_16x16x32_bf16 v[100:103], v[160:163], v[190:193], v[100:103]
	v_mfma_f32_16x16x32_bf16 v[96:99], v[174:177], v[190:193], v[96:99]
	v_mfma_f32_16x16x32_bf16 v[84:87], v[160:163], v[198:201], v[84:87]
	v_mfma_f32_16x16x32_bf16 v[80:83], v[174:177], v[198:201], v[80:83]
	v_mfma_f32_16x16x32_bf16 v[68:71], v[160:163], v[206:209], v[68:71]
	v_mfma_f32_16x16x32_bf16 v[64:67], v[174:177], v[206:209], v[64:67]
	s_barrier
	s_add_i32 s71, s66, s55
	v_lshl_add_u64 v[210:211], s[50:51], 0, v[144:145]
	s_mov_b32 m0, s71
	ds_read_b128 v[178:181], v169 offset:16384
	ds_read_b128 v[182:185], v169 offset:17408
	ds_read_b128 v[186:189], v169 offset:18432
	ds_read_b128 v[190:193], v169 offset:19456
	ds_read_b128 v[194:197], v169 offset:20480
	ds_read_b128 v[198:201], v169 offset:21504
	ds_read_b128 v[202:205], v169 offset:22528
	ds_read_b128 v[206:209], v169 offset:23552
	global_load_lds_dwordx4 v[210:211], off
	s_add_i32 m0, s71, 0x2000
	s_add_u32 s72, s50, 0x40000
	v_lshl_add_u64 v[212:213], s[50:51], 0, v[146:147]
	s_addc_u32 s73, s51, 0
	s_add_i32 s71, s67, s55
	global_load_lds_dwordx4 v[212:213], off
	v_lshl_add_u64 v[214:215], s[72:73], 0, v[144:145]
	s_mov_b32 m0, s71
	v_lshl_add_u64 v[216:217], s[52:53], 0, v[146:147]
	global_load_lds_dwordx4 v[214:215], off
	v_lshl_add_u64 v[214:215], s[72:73], 0, v[146:147]
	s_add_i32 m0, s71, 0x2000
	s_nop 0
	global_load_lds_dwordx4 v[214:215], off
	v_lshl_add_u64 v[214:215], s[52:53], 0, v[144:145]
	s_mov_b32 m0, s56
	s_nop 0
	global_load_lds_dwordx4 v[214:215], off
	s_mov_b32 m0, s57
	s_nop 0
	global_load_lds_dwordx4 v[216:217], off
	s_waitcnt vmcnt(8)
	s_waitcnt lgkmcnt(0)
	s_barrier
	s_waitcnt lgkmcnt(0)
	v_mfma_f32_16x16x32_bf16 v[60:63], v[128:131], v[178:181], v[60:63]
	v_mfma_f32_16x16x32_bf16 v[56:59], v[136:139], v[178:181], v[56:59]
	v_mfma_f32_16x16x32_bf16 v[44:47], v[128:131], v[186:189], v[44:47]
	v_mfma_f32_16x16x32_bf16 v[40:43], v[136:139], v[186:189], v[40:43]
	v_mfma_f32_16x16x32_bf16 v[28:31], v[128:131], v[194:197], v[28:31]
	v_mfma_f32_16x16x32_bf16 v[24:27], v[136:139], v[194:197], v[24:27]
	v_mfma_f32_16x16x32_bf16 v[12:15], v[128:131], v[202:205], v[12:15]
	v_mfma_f32_16x16x32_bf16 v[8:11], v[136:139], v[202:205], v[8:11]
	v_mfma_f32_16x16x32_bf16 v[60:63], v[132:135], v[182:185], v[60:63]
	v_mfma_f32_16x16x32_bf16 v[56:59], v[140:143], v[182:185], v[56:59]
	v_mfma_f32_16x16x32_bf16 v[44:47], v[132:135], v[190:193], v[44:47]
	v_mfma_f32_16x16x32_bf16 v[40:43], v[140:143], v[190:193], v[40:43]
	v_mfma_f32_16x16x32_bf16 v[28:31], v[132:135], v[198:201], v[28:31]
	v_mfma_f32_16x16x32_bf16 v[24:27], v[140:143], v[198:201], v[24:27]
	v_mfma_f32_16x16x32_bf16 v[12:15], v[132:135], v[206:209], v[12:15]
	v_mfma_f32_16x16x32_bf16 v[8:11], v[140:143], v[206:209], v[8:11]
	v_mfma_f32_16x16x32_bf16 v[52:55], v[156:159], v[178:181], v[52:55]
	v_mfma_f32_16x16x32_bf16 v[48:51], v[170:173], v[178:181], v[48:51]
	v_mfma_f32_16x16x32_bf16 v[36:39], v[156:159], v[186:189], v[36:39]
	v_mfma_f32_16x16x32_bf16 v[32:35], v[170:173], v[186:189], v[32:35]
	v_mfma_f32_16x16x32_bf16 v[20:23], v[156:159], v[194:197], v[20:23]
	v_mfma_f32_16x16x32_bf16 v[16:19], v[170:173], v[194:197], v[16:19]
	v_mfma_f32_16x16x32_bf16 v[4:7], v[156:159], v[202:205], v[4:7]
	v_mfma_f32_16x16x32_bf16 v[0:3], v[170:173], v[202:205], v[0:3]
	v_mfma_f32_16x16x32_bf16 v[52:55], v[160:163], v[182:185], v[52:55]
	v_mfma_f32_16x16x32_bf16 v[48:51], v[174:177], v[182:185], v[48:51]
	v_mfma_f32_16x16x32_bf16 v[36:39], v[160:163], v[190:193], v[36:39]
	v_mfma_f32_16x16x32_bf16 v[32:35], v[174:177], v[190:193], v[32:35]
	v_mfma_f32_16x16x32_bf16 v[20:23], v[160:163], v[198:201], v[20:23]
	v_mfma_f32_16x16x32_bf16 v[16:19], v[174:177], v[198:201], v[16:19]
	v_mfma_f32_16x16x32_bf16 v[4:7], v[160:163], v[206:209], v[4:7]
	v_mfma_f32_16x16x32_bf16 v[0:3], v[174:177], v[206:209], v[0:3]
	s_barrier
	s_add_i32 s71, 0, 0x18000
	s_add_i32 s72, 0, 0x1c000
	v_add_u32_e32 v140, s71, v165
	v_add_u32_e32 v174, s72, v165
	ds_read_b128 v[128:131], v140
	ds_read_b128 v[132:135], v140 offset:1024
	ds_read_b128 v[136:139], v140 offset:2048
	ds_read_b128 v[140:143], v140 offset:3072
	ds_read_b128 v[156:159], v174
	ds_read_b128 v[160:163], v174 offset:1024
	ds_read_b128 v[170:173], v174 offset:2048
	ds_read_b128 v[174:177], v174 offset:3072
	s_add_u32 s52, s52, 0x40000
	s_addc_u32 s53, s53, 0
	s_mov_b32 m0, s58
	v_lshl_add_u64 v[218:219], s[52:53], 0, v[144:145]
	ds_read_b128 v[178:181], v169 offset:32768
	ds_read_b128 v[182:185], v169 offset:33792
	ds_read_b128 v[186:189], v169 offset:34816
	ds_read_b128 v[190:193], v169 offset:35840
	ds_read_b128 v[194:197], v169 offset:36864
	ds_read_b128 v[198:201], v169 offset:37888
	ds_read_b128 v[202:205], v169 offset:38912
	ds_read_b128 v[206:209], v169 offset:39936
	global_load_lds_dwordx4 v[218:219], off
	v_lshl_add_u64 v[218:219], s[52:53], 0, v[146:147]
	s_mov_b32 m0, s59
	s_nop 0
	global_load_lds_dwordx4 v[218:219], off
	s_waitcnt vmcnt(8)
	s_waitcnt lgkmcnt(0)
	s_barrier
	s_waitcnt lgkmcnt(0)
	v_mfma_f32_16x16x32_bf16 v[124:127], v[128:131], v[178:181], v[124:127]
	v_mfma_f32_16x16x32_bf16 v[120:123], v[136:139], v[178:181], v[120:123]
	v_mfma_f32_16x16x32_bf16 v[108:111], v[128:131], v[186:189], v[108:111]
	v_mfma_f32_16x16x32_bf16 v[104:107], v[136:139], v[186:189], v[104:107]
	v_mfma_f32_16x16x32_bf16 v[92:95], v[128:131], v[194:197], v[92:95]
	v_mfma_f32_16x16x32_bf16 v[88:91], v[136:139], v[194:197], v[88:91]
	v_mfma_f32_16x16x32_bf16 v[76:79], v[128:131], v[202:205], v[76:79]
	v_mfma_f32_16x16x32_bf16 v[72:75], v[136:139], v[202:205], v[72:75]
	v_mfma_f32_16x16x32_bf16 v[124:127], v[132:135], v[182:185], v[124:127]
	v_mfma_f32_16x16x32_bf16 v[120:123], v[140:143], v[182:185], v[120:123]
	v_mfma_f32_16x16x32_bf16 v[108:111], v[132:135], v[190:193], v[108:111]
	v_mfma_f32_16x16x32_bf16 v[104:107], v[140:143], v[190:193], v[104:107]
	v_mfma_f32_16x16x32_bf16 v[92:95], v[132:135], v[198:201], v[92:95]
	v_mfma_f32_16x16x32_bf16 v[88:91], v[140:143], v[198:201], v[88:91]
	v_mfma_f32_16x16x32_bf16 v[76:79], v[132:135], v[206:209], v[76:79]
	v_mfma_f32_16x16x32_bf16 v[72:75], v[140:143], v[206:209], v[72:75]
	v_mfma_f32_16x16x32_bf16 v[116:119], v[156:159], v[178:181], v[116:119]
	v_mfma_f32_16x16x32_bf16 v[112:115], v[170:173], v[178:181], v[112:115]
	v_mfma_f32_16x16x32_bf16 v[100:103], v[156:159], v[186:189], v[100:103]
	v_mfma_f32_16x16x32_bf16 v[96:99], v[170:173], v[186:189], v[96:99]
	v_mfma_f32_16x16x32_bf16 v[84:87], v[156:159], v[194:197], v[84:87]
	v_mfma_f32_16x16x32_bf16 v[80:83], v[170:173], v[194:197], v[80:83]
	v_mfma_f32_16x16x32_bf16 v[68:71], v[156:159], v[202:205], v[68:71]
	v_mfma_f32_16x16x32_bf16 v[64:67], v[170:173], v[202:205], v[64:67]
	v_mfma_f32_16x16x32_bf16 v[116:119], v[160:163], v[182:185], v[116:119]
	v_mfma_f32_16x16x32_bf16 v[112:115], v[174:177], v[182:185], v[112:115]
	v_mfma_f32_16x16x32_bf16 v[100:103], v[160:163], v[190:193], v[100:103]
	v_mfma_f32_16x16x32_bf16 v[96:99], v[174:177], v[190:193], v[96:99]
	v_mfma_f32_16x16x32_bf16 v[84:87], v[160:163], v[198:201], v[84:87]
	v_mfma_f32_16x16x32_bf16 v[80:83], v[174:177], v[198:201], v[80:83]
	v_mfma_f32_16x16x32_bf16 v[68:71], v[160:163], v[206:209], v[68:71]
	v_mfma_f32_16x16x32_bf16 v[64:67], v[174:177], v[206:209], v[64:67]
	s_barrier
	s_add_i32 s52, s71, s55
	v_lshl_add_u64 v[210:211], v[210:211], 0, s[22:23]
	s_mov_b32 m0, s52
	ds_read_b128 v[178:181], v169 offset:49152
	ds_read_b128 v[182:185], v169 offset:50176
	ds_read_b128 v[186:189], v169 offset:51200
	ds_read_b128 v[190:193], v169 offset:52224
	ds_read_b128 v[194:197], v169 offset:53248
	ds_read_b128 v[198:201], v169 offset:54272
	ds_read_b128 v[202:205], v169 offset:55296
	ds_read_b128 v[206:209], v169 offset:56320
	global_load_lds_dwordx4 v[210:211], off
	s_add_i32 m0, s52, 0x2000
	s_add_u32 s50, s50, 0x40080
	v_lshl_add_u64 v[210:211], v[212:213], 0, s[22:23]
	s_addc_u32 s51, s51, 0
	s_add_i32 s52, s72, s55
	global_load_lds_dwordx4 v[210:211], off
	v_lshl_add_u64 v[210:211], s[50:51], 0, v[144:145]
	s_mov_b32 m0, s52
	s_nop 0
	global_load_lds_dwordx4 v[210:211], off
	v_lshl_add_u64 v[210:211], s[50:51], 0, v[146:147]
	s_add_i32 m0, s52, 0x2000
	s_nop 0
	global_load_lds_dwordx4 v[210:211], off
	v_lshl_add_u64 v[210:211], v[214:215], 0, s[22:23]
	s_mov_b32 m0, s61
	s_nop 0
	global_load_lds_dwordx4 v[210:211], off
	v_lshl_add_u64 v[210:211], v[216:217], 0, s[22:23]
	s_mov_b32 m0, s62
	s_nop 0
	global_load_lds_dwordx4 v[210:211], off
	s_waitcnt vmcnt(8)
	s_waitcnt lgkmcnt(0)
	s_barrier
	s_waitcnt lgkmcnt(0)
	v_mfma_f32_16x16x32_bf16 v[60:63], v[128:131], v[178:181], v[60:63]
	v_mfma_f32_16x16x32_bf16 v[56:59], v[136:139], v[178:181], v[56:59]
	v_mfma_f32_16x16x32_bf16 v[44:47], v[128:131], v[186:189], v[44:47]
	v_mfma_f32_16x16x32_bf16 v[40:43], v[136:139], v[186:189], v[40:43]
	v_mfma_f32_16x16x32_bf16 v[28:31], v[128:131], v[194:197], v[28:31]
	v_mfma_f32_16x16x32_bf16 v[24:27], v[136:139], v[194:197], v[24:27]
	v_mfma_f32_16x16x32_bf16 v[12:15], v[128:131], v[202:205], v[12:15]
	v_mfma_f32_16x16x32_bf16 v[8:11], v[136:139], v[202:205], v[8:11]
	v_mfma_f32_16x16x32_bf16 v[60:63], v[132:135], v[182:185], v[60:63]
	v_mfma_f32_16x16x32_bf16 v[56:59], v[140:143], v[182:185], v[56:59]
	v_mfma_f32_16x16x32_bf16 v[44:47], v[132:135], v[190:193], v[44:47]
	v_mfma_f32_16x16x32_bf16 v[40:43], v[140:143], v[190:193], v[40:43]
	v_mfma_f32_16x16x32_bf16 v[28:31], v[132:135], v[198:201], v[28:31]
	v_mfma_f32_16x16x32_bf16 v[24:27], v[140:143], v[198:201], v[24:27]
	v_mfma_f32_16x16x32_bf16 v[12:15], v[132:135], v[206:209], v[12:15]
	v_mfma_f32_16x16x32_bf16 v[8:11], v[140:143], v[206:209], v[8:11]
	v_mfma_f32_16x16x32_bf16 v[52:55], v[156:159], v[178:181], v[52:55]
	v_mfma_f32_16x16x32_bf16 v[48:51], v[170:173], v[178:181], v[48:51]
	v_mfma_f32_16x16x32_bf16 v[36:39], v[156:159], v[186:189], v[36:39]
	v_mfma_f32_16x16x32_bf16 v[32:35], v[170:173], v[186:189], v[32:35]
	v_mfma_f32_16x16x32_bf16 v[20:23], v[156:159], v[194:197], v[20:23]
	v_mfma_f32_16x16x32_bf16 v[16:19], v[170:173], v[194:197], v[16:19]
	v_mfma_f32_16x16x32_bf16 v[4:7], v[156:159], v[202:205], v[4:7]
	v_mfma_f32_16x16x32_bf16 v[0:3], v[170:173], v[202:205], v[0:3]
	v_mfma_f32_16x16x32_bf16 v[52:55], v[160:163], v[182:185], v[52:55]
	v_mfma_f32_16x16x32_bf16 v[48:51], v[174:177], v[182:185], v[48:51]
	v_mfma_f32_16x16x32_bf16 v[36:39], v[160:163], v[190:193], v[36:39]
	v_mfma_f32_16x16x32_bf16 v[32:35], v[174:177], v[190:193], v[32:35]
	v_mfma_f32_16x16x32_bf16 v[20:23], v[160:163], v[198:201], v[20:23]
	v_mfma_f32_16x16x32_bf16 v[16:19], v[174:177], v[198:201], v[16:19]
	v_mfma_f32_16x16x32_bf16 v[4:7], v[160:163], v[206:209], v[4:7]
	v_mfma_f32_16x16x32_bf16 v[0:3], v[174:177], v[206:209], v[0:3]
	s_barrier
	s_add_i32 s70, s70, 2
	s_add_u32 s48, s48, 0x100
	s_addc_u32 s49, s49, 0
	s_add_u32 s47, s47, 0x100
	s_addc_u32 s69, s69, 0
	s_cmp_gt_u32 s70, 13
	s_cbranch_scc0 .LBB0_1150
	s_and_b64 vcc, exec, s[34:35]
	s_cbranch_vccz .LBB0_1153
	s_barrier

.LBB0_1234:
	ds_read_b128 v[144:147], v153
	ds_read_b128 v[158:161], v153 offset:1024
	ds_read_b128 v[162:165], v153 offset:2048
	ds_read_b128 v[166:169], v153 offset:3072
	ds_read_b128 v[170:173], v154
	ds_read_b128 v[174:177], v154 offset:1024
	ds_read_b128 v[178:181], v154 offset:2048
	ds_read_b128 v[182:185], v154 offset:3072
	s_add_u32 s42, s40, 0xfffc0080
	s_addc_u32 s43, s41, -1
	s_cmp_eq_u32 s65, 12
	s_cselect_b32 s45, s9, s43
	s_cselect_b32 s44, s23, s42
	s_cselect_b32 s43, s21, s64
	s_cselect_b32 s42, s62, s63
	v_lshl_add_u64 v[148:149], s[40:41], 0, v[136:137]
	s_add_i32 m0, s39, 0xc000
	ds_read_b128 v[186:189], v155
	ds_read_b128 v[190:193], v155 offset:1024
	ds_read_b128 v[194:197], v155 offset:2048
	ds_read_b128 v[198:201], v155 offset:3072
	ds_read_b128 v[202:205], v155 offset:4096
	ds_read_b128 v[206:209], v155 offset:5120
	ds_read_b128 v[210:213], v155 offset:6144
	ds_read_b128 v[214:217], v155 offset:7168
	global_load_lds_dwordx4 v[148:149], off
	v_lshl_add_u64 v[148:149], s[40:41], 0, v[138:139]
	s_add_i32 m0, s39, 0xe000
	s_nop 0
	global_load_lds_dwordx4 v[148:149], off
	s_waitcnt vmcnt(8)
	s_waitcnt lgkmcnt(0)
	s_barrier
	s_waitcnt lgkmcnt(0)
	v_mfma_f32_16x16x32_bf16 v[124:127], v[144:147], v[186:189], v[124:127]
	v_mfma_f32_16x16x32_bf16 v[120:123], v[162:165], v[186:189], v[120:123]
	v_mfma_f32_16x16x32_bf16 v[108:111], v[144:147], v[194:197], v[108:111]
	v_mfma_f32_16x16x32_bf16 v[104:107], v[162:165], v[194:197], v[104:107]
	v_mfma_f32_16x16x32_bf16 v[92:95], v[144:147], v[202:205], v[92:95]
	v_mfma_f32_16x16x32_bf16 v[88:91], v[162:165], v[202:205], v[88:91]
	v_mfma_f32_16x16x32_bf16 v[76:79], v[144:147], v[210:213], v[76:79]
	v_mfma_f32_16x16x32_bf16 v[72:75], v[162:165], v[210:213], v[72:75]
	v_mfma_f32_16x16x32_bf16 v[124:127], v[158:161], v[190:193], v[124:127]
	v_mfma_f32_16x16x32_bf16 v[120:123], v[166:169], v[190:193], v[120:123]
	v_mfma_f32_16x16x32_bf16 v[108:111], v[158:161], v[198:201], v[108:111]
	v_mfma_f32_16x16x32_bf16 v[104:107], v[166:169], v[198:201], v[104:107]
	v_mfma_f32_16x16x32_bf16 v[92:95], v[158:161], v[206:209], v[92:95]
	v_mfma_f32_16x16x32_bf16 v[88:91], v[166:169], v[206:209], v[88:91]
	v_mfma_f32_16x16x32_bf16 v[76:79], v[158:161], v[214:217], v[76:79]
	v_mfma_f32_16x16x32_bf16 v[72:75], v[166:169], v[214:217], v[72:75]
	v_mfma_f32_16x16x32_bf16 v[116:119], v[170:173], v[186:189], v[116:119]
	v_mfma_f32_16x16x32_bf16 v[112:115], v[178:181], v[186:189], v[112:115]
	v_mfma_f32_16x16x32_bf16 v[100:103], v[170:173], v[194:197], v[100:103]
	v_mfma_f32_16x16x32_bf16 v[96:99], v[178:181], v[194:197], v[96:99]
	v_mfma_f32_16x16x32_bf16 v[84:87], v[170:173], v[202:205], v[84:87]
	v_mfma_f32_16x16x32_bf16 v[80:83], v[178:181], v[202:205], v[80:83]
	v_mfma_f32_16x16x32_bf16 v[68:71], v[170:173], v[210:213], v[68:71]
	v_mfma_f32_16x16x32_bf16 v[64:67], v[178:181], v[210:213], v[64:67]
	v_mfma_f32_16x16x32_bf16 v[116:119], v[174:177], v[190:193], v[116:119]
	v_mfma_f32_16x16x32_bf16 v[112:115], v[182:185], v[190:193], v[112:115]
	v_mfma_f32_16x16x32_bf16 v[100:103], v[174:177], v[198:201], v[100:103]
	v_mfma_f32_16x16x32_bf16 v[96:99], v[182:185], v[198:201], v[96:99]
	v_mfma_f32_16x16x32_bf16 v[84:87], v[174:177], v[206:209], v[84:87]
	v_mfma_f32_16x16x32_bf16 v[80:83], v[182:185], v[206:209], v[80:83]
	v_mfma_f32_16x16x32_bf16 v[68:71], v[174:177], v[214:217], v[68:71]
	v_mfma_f32_16x16x32_bf16 v[64:67], v[182:185], v[214:217], v[64:67]
	s_barrier
	s_add_i32 s66, s58, s47
	v_lshl_add_u64 v[148:149], s[42:43], 0, v[132:133]
	s_mov_b32 m0, s66
	ds_read_b128 v[186:189], v155 offset:16384
	ds_read_b128 v[190:193], v155 offset:17408
	ds_read_b128 v[194:197], v155 offset:18432
	ds_read_b128 v[198:201], v155 offset:19456
	ds_read_b128 v[202:205], v155 offset:20480
	ds_read_b128 v[206:209], v155 offset:21504
	ds_read_b128 v[210:213], v155 offset:22528
	ds_read_b128 v[214:217], v155 offset:23552
	global_load_lds_dwordx4 v[148:149], off
	s_add_i32 m0, s66, 0x2000
	s_add_u32 s66, s42, 0x40000
	v_lshl_add_u64 v[218:219], s[42:43], 0, v[128:129]
	s_addc_u32 s67, s43, 0
	s_add_i32 s68, s59, s47
	global_load_lds_dwordx4 v[218:219], off
	v_lshl_add_u64 v[220:221], s[66:67], 0, v[132:133]
	s_mov_b32 m0, s68
	v_lshl_add_u64 v[222:223], s[44:45], 0, v[130:131]
	global_load_lds_dwordx4 v[220:221], off
	v_lshl_add_u64 v[220:221], s[66:67], 0, v[128:129]
	s_add_i32 m0, s68, 0x2000
	s_nop 0
	global_load_lds_dwordx4 v[220:221], off
	v_lshl_add_u64 v[220:221], s[44:45], 0, v[134:135]
	s_mov_b32 m0, s39
	s_nop 0
	global_load_lds_dwordx4 v[220:221], off
	s_mov_b32 m0, s50
	s_nop 0
	global_load_lds_dwordx4 v[222:223], off
	s_waitcnt vmcnt(8)
	s_waitcnt lgkmcnt(0)
	s_barrier
	s_waitcnt lgkmcnt(0)
	v_mfma_f32_16x16x32_bf16 v[60:63], v[144:147], v[186:189], v[60:63]
	v_mfma_f32_16x16x32_bf16 v[56:59], v[162:165], v[186:189], v[56:59]
	v_mfma_f32_16x16x32_bf16 v[44:47], v[144:147], v[194:197], v[44:47]
	v_mfma_f32_16x16x32_bf16 v[40:43], v[162:165], v[194:197], v[40:43]
	v_mfma_f32_16x16x32_bf16 v[28:31], v[144:147], v[202:205], v[28:31]
	v_mfma_f32_16x16x32_bf16 v[24:27], v[162:165], v[202:205], v[24:27]
	v_mfma_f32_16x16x32_bf16 v[12:15], v[144:147], v[210:213], v[12:15]
	v_mfma_f32_16x16x32_bf16 v[8:11], v[162:165], v[210:213], v[8:11]
	v_mfma_f32_16x16x32_bf16 v[60:63], v[158:161], v[190:193], v[60:63]
	v_mfma_f32_16x16x32_bf16 v[56:59], v[166:169], v[190:193], v[56:59]
	v_mfma_f32_16x16x32_bf16 v[44:47], v[158:161], v[198:201], v[44:47]
	v_mfma_f32_16x16x32_bf16 v[40:43], v[166:169], v[198:201], v[40:43]
	v_mfma_f32_16x16x32_bf16 v[28:31], v[158:161], v[206:209], v[28:31]
	v_mfma_f32_16x16x32_bf16 v[24:27], v[166:169], v[206:209], v[24:27]
	v_mfma_f32_16x16x32_bf16 v[12:15], v[158:161], v[214:217], v[12:15]
	v_mfma_f32_16x16x32_bf16 v[8:11], v[166:169], v[214:217], v[8:11]
	v_mfma_f32_16x16x32_bf16 v[52:55], v[170:173], v[186:189], v[52:55]
	v_mfma_f32_16x16x32_bf16 v[48:51], v[178:181], v[186:189], v[48:51]
	v_mfma_f32_16x16x32_bf16 v[36:39], v[170:173], v[194:197], v[36:39]
	v_mfma_f32_16x16x32_bf16 v[32:35], v[178:181], v[194:197], v[32:35]
	v_mfma_f32_16x16x32_bf16 v[20:23], v[170:173], v[202:205], v[20:23]
	v_mfma_f32_16x16x32_bf16 v[16:19], v[178:181], v[202:205], v[16:19]
	v_mfma_f32_16x16x32_bf16 v[4:7], v[170:173], v[210:213], v[4:7]
	v_mfma_f32_16x16x32_bf16 v[0:3], v[178:181], v[210:213], v[0:3]
	v_mfma_f32_16x16x32_bf16 v[52:55], v[174:177], v[190:193], v[52:55]
	v_mfma_f32_16x16x32_bf16 v[48:51], v[182:185], v[190:193], v[48:51]
	v_mfma_f32_16x16x32_bf16 v[36:39], v[174:177], v[198:201], v[36:39]
	v_mfma_f32_16x16x32_bf16 v[32:35], v[182:185], v[198:201], v[32:35]
	v_mfma_f32_16x16x32_bf16 v[20:23], v[174:177], v[206:209], v[20:23]
	v_mfma_f32_16x16x32_bf16 v[16:19], v[182:185], v[206:209], v[16:19]
	v_mfma_f32_16x16x32_bf16 v[4:7], v[174:177], v[214:217], v[4:7]
	v_mfma_f32_16x16x32_bf16 v[0:3], v[182:185], v[214:217], v[0:3]
	s_barrier
	s_add_i32 s66, 0, 0x18000
	v_add_u32_e32 v157, s66, v151
	s_add_i32 s67, 0, 0x1c000
	ds_read_b128 v[144:147], v157
	ds_read_b128 v[158:161], v157 offset:1024
	ds_read_b128 v[162:165], v157 offset:2048
	ds_read_b128 v[166:169], v157 offset:3072
	v_add_u32_e32 v157, s67, v151
	ds_read_b128 v[170:173], v157
	ds_read_b128 v[174:177], v157 offset:1024
	ds_read_b128 v[178:181], v157 offset:2048
	ds_read_b128 v[182:185], v157 offset:3072
	s_add_u32 s44, s44, 0x40000
	s_addc_u32 s45, s45, 0
	s_mov_b32 m0, s51
	v_lshl_add_u64 v[224:225], s[44:45], 0, v[134:135]
	ds_read_b128 v[186:189], v155 offset:32768
	ds_read_b128 v[190:193], v155 offset:33792
	ds_read_b128 v[194:197], v155 offset:34816
	ds_read_b128 v[198:201], v155 offset:35840
	ds_read_b128 v[202:205], v155 offset:36864
	ds_read_b128 v[206:209], v155 offset:37888
	ds_read_b128 v[210:213], v155 offset:38912
	ds_read_b128 v[214:217], v155 offset:39936
	global_load_lds_dwordx4 v[224:225], off
	v_lshl_add_u64 v[224:225], s[44:45], 0, v[130:131]
	s_mov_b32 m0, s52
	s_nop 0
	global_load_lds_dwordx4 v[224:225], off
	s_waitcnt vmcnt(8)
	s_waitcnt lgkmcnt(0)
	s_barrier
	s_waitcnt lgkmcnt(0)
	v_mfma_f32_16x16x32_bf16 v[124:127], v[144:147], v[186:189], v[124:127]
	v_mfma_f32_16x16x32_bf16 v[120:123], v[162:165], v[186:189], v[120:123]
	v_mfma_f32_16x16x32_bf16 v[108:111], v[144:147], v[194:197], v[108:111]
	v_mfma_f32_16x16x32_bf16 v[104:107], v[162:165], v[194:197], v[104:107]
	v_mfma_f32_16x16x32_bf16 v[92:95], v[144:147], v[202:205], v[92:95]
	v_mfma_f32_16x16x32_bf16 v[88:91], v[162:165], v[202:205], v[88:91]
	v_mfma_f32_16x16x32_bf16 v[76:79], v[144:147], v[210:213], v[76:79]
	v_mfma_f32_16x16x32_bf16 v[72:75], v[162:165], v[210:213], v[72:75]
	v_mfma_f32_16x16x32_bf16 v[124:127], v[158:161], v[190:193], v[124:127]
	v_mfma_f32_16x16x32_bf16 v[120:123], v[166:169], v[190:193], v[120:123]
	v_mfma_f32_16x16x32_bf16 v[108:111], v[158:161], v[198:201], v[108:111]
	v_mfma_f32_16x16x32_bf16 v[104:107], v[166:169], v[198:201], v[104:107]
	v_mfma_f32_16x16x32_bf16 v[92:95], v[158:161], v[206:209], v[92:95]
	v_mfma_f32_16x16x32_bf16 v[88:91], v[166:169], v[206:209], v[88:91]
	v_mfma_f32_16x16x32_bf16 v[76:79], v[158:161], v[214:217], v[76:79]
	v_mfma_f32_16x16x32_bf16 v[72:75], v[166:169], v[214:217], v[72:75]
	v_mfma_f32_16x16x32_bf16 v[116:119], v[170:173], v[186:189], v[116:119]
	v_mfma_f32_16x16x32_bf16 v[112:115], v[178:181], v[186:189], v[112:115]
	v_mfma_f32_16x16x32_bf16 v[100:103], v[170:173], v[194:197], v[100:103]
	v_mfma_f32_16x16x32_bf16 v[96:99], v[178:181], v[194:197], v[96:99]
	v_mfma_f32_16x16x32_bf16 v[84:87], v[170:173], v[202:205], v[84:87]
	v_mfma_f32_16x16x32_bf16 v[80:83], v[178:181], v[202:205], v[80:83]
	v_mfma_f32_16x16x32_bf16 v[68:71], v[170:173], v[210:213], v[68:71]
	v_mfma_f32_16x16x32_bf16 v[64:67], v[178:181], v[210:213], v[64:67]
	v_mfma_f32_16x16x32_bf16 v[116:119], v[174:177], v[190:193], v[116:119]
	v_mfma_f32_16x16x32_bf16 v[112:115], v[182:185], v[190:193], v[112:115]
	v_mfma_f32_16x16x32_bf16 v[100:103], v[174:177], v[198:201], v[100:103]
	v_mfma_f32_16x16x32_bf16 v[96:99], v[182:185], v[198:201], v[96:99]
	v_mfma_f32_16x16x32_bf16 v[84:87], v[174:177], v[206:209], v[84:87]
	v_mfma_f32_16x16x32_bf16 v[80:83], v[182:185], v[206:209], v[80:83]
	v_mfma_f32_16x16x32_bf16 v[68:71], v[174:177], v[214:217], v[68:71]
	v_mfma_f32_16x16x32_bf16 v[64:67], v[182:185], v[214:217], v[64:67]
	s_barrier
	s_add_i32 s44, s66, s47
	v_lshl_add_u64 v[148:149], v[148:149], 0, s[16:17]
	s_mov_b32 m0, s44
	ds_read_b128 v[186:189], v155 offset:49152
	ds_read_b128 v[190:193], v155 offset:50176
	ds_read_b128 v[194:197], v155 offset:51200
	ds_read_b128 v[198:201], v155 offset:52224
	ds_read_b128 v[202:205], v155 offset:53248
	ds_read_b128 v[206:209], v155 offset:54272
	ds_read_b128 v[210:213], v155 offset:55296
	ds_read_b128 v[214:217], v155 offset:56320
	global_load_lds_dwordx4 v[148:149], off
	s_add_i32 m0, s44, 0x2000
	s_add_u32 s42, s42, 0x40080
	v_lshl_add_u64 v[148:149], v[218:219], 0, s[16:17]
	s_addc_u32 s43, s43, 0
	s_add_i32 s44, s67, s47
	global_load_lds_dwordx4 v[148:149], off
	v_lshl_add_u64 v[148:149], s[42:43], 0, v[132:133]
	s_mov_b32 m0, s44
	s_nop 0
	global_load_lds_dwordx4 v[148:149], off
	v_lshl_add_u64 v[148:149], s[42:43], 0, v[128:129]
	s_add_i32 m0, s44, 0x2000
	s_nop 0
	global_load_lds_dwordx4 v[148:149], off
	v_lshl_add_u64 v[148:149], v[220:221], 0, s[16:17]
	s_mov_b32 m0, s54
	s_nop 0
	global_load_lds_dwordx4 v[148:149], off
	v_lshl_add_u64 v[148:149], v[222:223], 0, s[16:17]
	s_mov_b32 m0, s55
	s_nop 0
	global_load_lds_dwordx4 v[148:149], off
	s_waitcnt vmcnt(8)
	s_waitcnt lgkmcnt(0)
	s_barrier
	s_waitcnt lgkmcnt(0)
	v_mfma_f32_16x16x32_bf16 v[60:63], v[144:147], v[186:189], v[60:63]
	v_mfma_f32_16x16x32_bf16 v[56:59], v[162:165], v[186:189], v[56:59]
	v_mfma_f32_16x16x32_bf16 v[44:47], v[144:147], v[194:197], v[44:47]
	v_mfma_f32_16x16x32_bf16 v[40:43], v[162:165], v[194:197], v[40:43]
	v_mfma_f32_16x16x32_bf16 v[28:31], v[144:147], v[202:205], v[28:31]
	v_mfma_f32_16x16x32_bf16 v[24:27], v[162:165], v[202:205], v[24:27]
	v_mfma_f32_16x16x32_bf16 v[12:15], v[144:147], v[210:213], v[12:15]
	v_mfma_f32_16x16x32_bf16 v[8:11], v[162:165], v[210:213], v[8:11]
	v_mfma_f32_16x16x32_bf16 v[60:63], v[158:161], v[190:193], v[60:63]
	v_mfma_f32_16x16x32_bf16 v[56:59], v[166:169], v[190:193], v[56:59]
	v_mfma_f32_16x16x32_bf16 v[44:47], v[158:161], v[198:201], v[44:47]
	v_mfma_f32_16x16x32_bf16 v[40:43], v[166:169], v[198:201], v[40:43]
	v_mfma_f32_16x16x32_bf16 v[28:31], v[158:161], v[206:209], v[28:31]
	v_mfma_f32_16x16x32_bf16 v[24:27], v[166:169], v[206:209], v[24:27]
	v_mfma_f32_16x16x32_bf16 v[12:15], v[158:161], v[214:217], v[12:15]
	v_mfma_f32_16x16x32_bf16 v[8:11], v[166:169], v[214:217], v[8:11]
	v_mfma_f32_16x16x32_bf16 v[52:55], v[170:173], v[186:189], v[52:55]
	v_mfma_f32_16x16x32_bf16 v[48:51], v[178:181], v[186:189], v[48:51]
	v_mfma_f32_16x16x32_bf16 v[36:39], v[170:173], v[194:197], v[36:39]
	v_mfma_f32_16x16x32_bf16 v[32:35], v[178:181], v[194:197], v[32:35]
	v_mfma_f32_16x16x32_bf16 v[20:23], v[170:173], v[202:205], v[20:23]
	v_mfma_f32_16x16x32_bf16 v[16:19], v[178:181], v[202:205], v[16:19]
	v_mfma_f32_16x16x32_bf16 v[4:7], v[170:173], v[210:213], v[4:7]
	v_mfma_f32_16x16x32_bf16 v[0:3], v[178:181], v[210:213], v[0:3]
	v_mfma_f32_16x16x32_bf16 v[52:55], v[174:177], v[190:193], v[52:55]
	v_mfma_f32_16x16x32_bf16 v[48:51], v[182:185], v[190:193], v[48:51]
	v_mfma_f32_16x16x32_bf16 v[36:39], v[174:177], v[198:201], v[36:39]
	v_mfma_f32_16x16x32_bf16 v[32:35], v[182:185], v[198:201], v[32:35]
	v_mfma_f32_16x16x32_bf16 v[20:23], v[174:177], v[206:209], v[20:23]
	v_mfma_f32_16x16x32_bf16 v[16:19], v[182:185], v[206:209], v[16:19]
	v_mfma_f32_16x16x32_bf16 v[4:7], v[174:177], v[214:217], v[4:7]
	v_mfma_f32_16x16x32_bf16 v[0:3], v[182:185], v[214:217], v[0:3]
	s_barrier
	s_add_i32 s65, s65, 2
	s_add_u32 s40, s40, 0x100
	s_addc_u32 s41, s41, 0
	s_add_u32 s63, s63, 0x100
	s_addc_u32 s64, s64, 0
	s_cmp_gt_u32 s65, 13
	s_cbranch_scc0 .LBB0_1234
	s_and_b64 vcc, exec, s[18:19]
	s_cbranch_vccz .LBB0_1237
	s_barrier

.LBB0_1314:
	ds_read_b128 v[140:143], v151
	ds_read_b128 v[144:147], v151 offset:1024
	ds_read_b128 v[154:157], v151 offset:2048
	ds_read_b128 v[158:161], v151 offset:3072
	ds_read_b128 v[162:165], v152
	ds_read_b128 v[166:169], v152 offset:1024
	ds_read_b128 v[170:173], v152 offset:2048
	ds_read_b128 v[174:177], v152 offset:3072
	s_add_u32 s20, s18, 0x100
	s_addc_u32 s21, s19, 0
	s_cmp_eq_u32 s49, 40
	s_cselect_b32 s27, s5, s21
	s_cselect_b32 s26, s4, s20
	s_cselect_b32 s23, s17, s48
	s_cselect_b32 s22, s16, s47
	v_lshl_add_u64 v[210:211], s[18:19], 0, v[132:133]
	s_add_i32 m0, s33, 0xc000
	ds_read_b128 v[178:181], v153
	ds_read_b128 v[182:185], v153 offset:1024
	ds_read_b128 v[186:189], v153 offset:2048
	ds_read_b128 v[190:193], v153 offset:3072
	ds_read_b128 v[194:197], v153 offset:4096
	ds_read_b128 v[198:201], v153 offset:5120
	ds_read_b128 v[202:205], v153 offset:6144
	ds_read_b128 v[206:209], v153 offset:7168
	global_load_lds_dwordx4 v[210:211], off
	v_lshl_add_u64 v[210:211], s[18:19], 0, v[134:135]
	s_add_i32 m0, s33, 0xe000
	s_nop 0
	global_load_lds_dwordx4 v[210:211], off
	s_waitcnt vmcnt(8)
	s_waitcnt lgkmcnt(0)
	s_barrier
	s_waitcnt lgkmcnt(0)
	v_mfma_f32_16x16x32_bf16 v[124:127], v[140:143], v[178:181], v[124:127]
	v_mfma_f32_16x16x32_bf16 v[120:123], v[154:157], v[178:181], v[120:123]
	v_mfma_f32_16x16x32_bf16 v[108:111], v[140:143], v[186:189], v[108:111]
	v_mfma_f32_16x16x32_bf16 v[104:107], v[154:157], v[186:189], v[104:107]
	v_mfma_f32_16x16x32_bf16 v[96:99], v[140:143], v[194:197], v[96:99]
	v_mfma_f32_16x16x32_bf16 v[88:91], v[154:157], v[194:197], v[88:91]
	v_mfma_f32_16x16x32_bf16 v[80:83], v[140:143], v[202:205], v[80:83]
	v_mfma_f32_16x16x32_bf16 v[72:75], v[154:157], v[202:205], v[72:75]
	v_mfma_f32_16x16x32_bf16 v[124:127], v[144:147], v[182:185], v[124:127]
	v_mfma_f32_16x16x32_bf16 v[120:123], v[158:161], v[182:185], v[120:123]
	v_mfma_f32_16x16x32_bf16 v[108:111], v[144:147], v[190:193], v[108:111]
	v_mfma_f32_16x16x32_bf16 v[104:107], v[158:161], v[190:193], v[104:107]
	v_mfma_f32_16x16x32_bf16 v[96:99], v[144:147], v[198:201], v[96:99]
	v_mfma_f32_16x16x32_bf16 v[88:91], v[158:161], v[198:201], v[88:91]
	v_mfma_f32_16x16x32_bf16 v[80:83], v[144:147], v[206:209], v[80:83]
	v_mfma_f32_16x16x32_bf16 v[72:75], v[158:161], v[206:209], v[72:75]
	v_mfma_f32_16x16x32_bf16 v[116:119], v[162:165], v[178:181], v[116:119]
	v_mfma_f32_16x16x32_bf16 v[112:115], v[170:173], v[178:181], v[112:115]
	v_mfma_f32_16x16x32_bf16 v[100:103], v[162:165], v[186:189], v[100:103]
	v_mfma_f32_16x16x32_bf16 v[92:95], v[170:173], v[186:189], v[92:95]
	v_mfma_f32_16x16x32_bf16 v[84:87], v[162:165], v[194:197], v[84:87]
	v_mfma_f32_16x16x32_bf16 v[76:79], v[170:173], v[194:197], v[76:79]
	v_mfma_f32_16x16x32_bf16 v[68:71], v[162:165], v[202:205], v[68:71]
	v_mfma_f32_16x16x32_bf16 v[64:67], v[170:173], v[202:205], v[64:67]
	v_mfma_f32_16x16x32_bf16 v[116:119], v[166:169], v[182:185], v[116:119]
	v_mfma_f32_16x16x32_bf16 v[112:115], v[174:177], v[182:185], v[112:115]
	v_mfma_f32_16x16x32_bf16 v[100:103], v[166:169], v[190:193], v[100:103]
	v_mfma_f32_16x16x32_bf16 v[92:95], v[174:177], v[190:193], v[92:95]
	v_mfma_f32_16x16x32_bf16 v[84:87], v[166:169], v[198:201], v[84:87]
	v_mfma_f32_16x16x32_bf16 v[76:79], v[174:177], v[198:201], v[76:79]
	v_mfma_f32_16x16x32_bf16 v[68:71], v[166:169], v[206:209], v[68:71]
	v_mfma_f32_16x16x32_bf16 v[64:67], v[174:177], v[206:209], v[64:67]
	s_barrier
	s_add_i32 s18, s41, s31
	v_lshl_add_u64 v[210:211], s[22:23], 0, v[128:129]
	s_mov_b32 m0, s18
	ds_read_b128 v[178:181], v153 offset:16384
	ds_read_b128 v[182:185], v153 offset:17408
	ds_read_b128 v[186:189], v153 offset:18432
	ds_read_b128 v[190:193], v153 offset:19456
	ds_read_b128 v[194:197], v153 offset:20480
	ds_read_b128 v[198:201], v153 offset:21504
	ds_read_b128 v[202:205], v153 offset:22528
	ds_read_b128 v[206:209], v153 offset:23552
	global_load_lds_dwordx4 v[210:211], off
	s_add_i32 m0, s18, 0x2000
	s_add_u32 s18, s22, 0xb0000
	v_lshl_add_u64 v[212:213], s[22:23], 0, v[130:131]
	s_addc_u32 s19, s23, 0
	s_add_i32 s50, s42, s31
	global_load_lds_dwordx4 v[212:213], off
	v_lshl_add_u64 v[214:215], s[18:19], 0, v[128:129]
	s_mov_b32 m0, s50
	v_lshl_add_u64 v[216:217], s[26:27], 0, v[130:131]
	global_load_lds_dwordx4 v[214:215], off
	v_lshl_add_u64 v[214:215], s[18:19], 0, v[130:131]
	s_add_i32 m0, s50, 0x2000
	s_nop 0
	global_load_lds_dwordx4 v[214:215], off
	v_lshl_add_u64 v[214:215], s[26:27], 0, v[128:129]
	s_mov_b32 m0, s33
	s_nop 0
	global_load_lds_dwordx4 v[214:215], off
	s_mov_b32 m0, s34
	s_nop 0
	global_load_lds_dwordx4 v[216:217], off
	s_waitcnt vmcnt(8)
	s_waitcnt lgkmcnt(0)
	s_barrier
	s_waitcnt lgkmcnt(0)
	v_mfma_f32_16x16x32_bf16 v[60:63], v[140:143], v[178:181], v[60:63]
	v_mfma_f32_16x16x32_bf16 v[56:59], v[154:157], v[178:181], v[56:59]
	v_mfma_f32_16x16x32_bf16 v[48:51], v[140:143], v[186:189], v[48:51]
	v_mfma_f32_16x16x32_bf16 v[40:43], v[154:157], v[186:189], v[40:43]
	v_mfma_f32_16x16x32_bf16 v[32:35], v[140:143], v[194:197], v[32:35]
	v_mfma_f32_16x16x32_bf16 v[24:27], v[154:157], v[194:197], v[24:27]
	v_mfma_f32_16x16x32_bf16 v[16:19], v[140:143], v[202:205], v[16:19]
	v_mfma_f32_16x16x32_bf16 v[8:11], v[154:157], v[202:205], v[8:11]
	v_mfma_f32_16x16x32_bf16 v[60:63], v[144:147], v[182:185], v[60:63]
	v_mfma_f32_16x16x32_bf16 v[56:59], v[158:161], v[182:185], v[56:59]
	v_mfma_f32_16x16x32_bf16 v[48:51], v[144:147], v[190:193], v[48:51]
	v_mfma_f32_16x16x32_bf16 v[40:43], v[158:161], v[190:193], v[40:43]
	v_mfma_f32_16x16x32_bf16 v[32:35], v[144:147], v[198:201], v[32:35]
	v_mfma_f32_16x16x32_bf16 v[24:27], v[158:161], v[198:201], v[24:27]
	v_mfma_f32_16x16x32_bf16 v[16:19], v[144:147], v[206:209], v[16:19]
	v_mfma_f32_16x16x32_bf16 v[8:11], v[158:161], v[206:209], v[8:11]
	v_mfma_f32_16x16x32_bf16 v[52:55], v[162:165], v[178:181], v[52:55]
	v_mfma_f32_16x16x32_bf16 v[44:47], v[170:173], v[178:181], v[44:47]
	v_mfma_f32_16x16x32_bf16 v[36:39], v[162:165], v[186:189], v[36:39]
	v_mfma_f32_16x16x32_bf16 v[28:31], v[170:173], v[186:189], v[28:31]
	v_mfma_f32_16x16x32_bf16 v[20:23], v[162:165], v[194:197], v[20:23]
	v_mfma_f32_16x16x32_bf16 v[12:15], v[170:173], v[194:197], v[12:15]
	v_mfma_f32_16x16x32_bf16 v[4:7], v[162:165], v[202:205], v[4:7]
	v_mfma_f32_16x16x32_bf16 v[0:3], v[170:173], v[202:205], v[0:3]
	v_mfma_f32_16x16x32_bf16 v[52:55], v[166:169], v[182:185], v[52:55]
	v_mfma_f32_16x16x32_bf16 v[44:47], v[174:177], v[182:185], v[44:47]
	v_mfma_f32_16x16x32_bf16 v[36:39], v[166:169], v[190:193], v[36:39]
	v_mfma_f32_16x16x32_bf16 v[28:31], v[174:177], v[190:193], v[28:31]
	v_mfma_f32_16x16x32_bf16 v[20:23], v[166:169], v[198:201], v[20:23]
	v_mfma_f32_16x16x32_bf16 v[12:15], v[174:177], v[198:201], v[12:15]
	v_mfma_f32_16x16x32_bf16 v[4:7], v[166:169], v[206:209], v[4:7]
	v_mfma_f32_16x16x32_bf16 v[0:3], v[174:177], v[206:209], v[0:3]
	s_barrier
	s_add_i32 s50, 0, 0x18000
	s_add_i32 s51, 0, 0x1c000
	v_add_u32_e32 v158, s50, v149
	v_add_u32_e32 v174, s51, v149
	ds_read_b128 v[140:143], v158
	ds_read_b128 v[144:147], v158 offset:1024
	ds_read_b128 v[154:157], v158 offset:2048
	ds_read_b128 v[158:161], v158 offset:3072
	ds_read_b128 v[162:165], v174
	ds_read_b128 v[166:169], v174 offset:1024
	ds_read_b128 v[170:173], v174 offset:2048
	ds_read_b128 v[174:177], v174 offset:3072
	s_add_u32 s18, s26, 0xb0000
	s_addc_u32 s19, s27, 0
	s_mov_b32 m0, s35
	v_lshl_add_u64 v[218:219], s[18:19], 0, v[128:129]
	ds_read_b128 v[178:181], v153 offset:32768
	ds_read_b128 v[182:185], v153 offset:33792
	ds_read_b128 v[186:189], v153 offset:34816
	ds_read_b128 v[190:193], v153 offset:35840
	ds_read_b128 v[194:197], v153 offset:36864
	ds_read_b128 v[198:201], v153 offset:37888
	ds_read_b128 v[202:205], v153 offset:38912
	ds_read_b128 v[206:209], v153 offset:39936
	global_load_lds_dwordx4 v[218:219], off
	v_lshl_add_u64 v[218:219], s[18:19], 0, v[130:131]
	s_mov_b32 m0, s36
	s_nop 0
	global_load_lds_dwordx4 v[218:219], off
	s_waitcnt vmcnt(8)
	s_waitcnt lgkmcnt(0)
	s_barrier
	s_waitcnt lgkmcnt(0)
	v_mfma_f32_16x16x32_bf16 v[124:127], v[140:143], v[178:181], v[124:127]
	v_mfma_f32_16x16x32_bf16 v[120:123], v[154:157], v[178:181], v[120:123]
	v_mfma_f32_16x16x32_bf16 v[108:111], v[140:143], v[186:189], v[108:111]
	v_mfma_f32_16x16x32_bf16 v[104:107], v[154:157], v[186:189], v[104:107]
	v_mfma_f32_16x16x32_bf16 v[96:99], v[140:143], v[194:197], v[96:99]
	v_mfma_f32_16x16x32_bf16 v[88:91], v[154:157], v[194:197], v[88:91]
	v_mfma_f32_16x16x32_bf16 v[80:83], v[140:143], v[202:205], v[80:83]
	v_mfma_f32_16x16x32_bf16 v[72:75], v[154:157], v[202:205], v[72:75]
	v_mfma_f32_16x16x32_bf16 v[124:127], v[144:147], v[182:185], v[124:127]
	v_mfma_f32_16x16x32_bf16 v[120:123], v[158:161], v[182:185], v[120:123]
	v_mfma_f32_16x16x32_bf16 v[108:111], v[144:147], v[190:193], v[108:111]
	v_mfma_f32_16x16x32_bf16 v[104:107], v[158:161], v[190:193], v[104:107]
	v_mfma_f32_16x16x32_bf16 v[96:99], v[144:147], v[198:201], v[96:99]
	v_mfma_f32_16x16x32_bf16 v[88:91], v[158:161], v[198:201], v[88:91]
	v_mfma_f32_16x16x32_bf16 v[80:83], v[144:147], v[206:209], v[80:83]
	v_mfma_f32_16x16x32_bf16 v[72:75], v[158:161], v[206:209], v[72:75]
	v_mfma_f32_16x16x32_bf16 v[116:119], v[162:165], v[178:181], v[116:119]
	v_mfma_f32_16x16x32_bf16 v[112:115], v[170:173], v[178:181], v[112:115]
	v_mfma_f32_16x16x32_bf16 v[100:103], v[162:165], v[186:189], v[100:103]
	v_mfma_f32_16x16x32_bf16 v[92:95], v[170:173], v[186:189], v[92:95]
	v_mfma_f32_16x16x32_bf16 v[84:87], v[162:165], v[194:197], v[84:87]
	v_mfma_f32_16x16x32_bf16 v[76:79], v[170:173], v[194:197], v[76:79]
	v_mfma_f32_16x16x32_bf16 v[68:71], v[162:165], v[202:205], v[68:71]
	v_mfma_f32_16x16x32_bf16 v[64:67], v[170:173], v[202:205], v[64:67]
	v_mfma_f32_16x16x32_bf16 v[116:119], v[166:169], v[182:185], v[116:119]
	v_mfma_f32_16x16x32_bf16 v[112:115], v[174:177], v[182:185], v[112:115]
	v_mfma_f32_16x16x32_bf16 v[100:103], v[166:169], v[190:193], v[100:103]
	v_mfma_f32_16x16x32_bf16 v[92:95], v[174:177], v[190:193], v[92:95]
	v_mfma_f32_16x16x32_bf16 v[84:87], v[166:169], v[198:201], v[84:87]
	v_mfma_f32_16x16x32_bf16 v[76:79], v[174:177], v[198:201], v[76:79]
	v_mfma_f32_16x16x32_bf16 v[68:71], v[166:169], v[206:209], v[68:71]
	v_mfma_f32_16x16x32_bf16 v[64:67], v[174:177], v[206:209], v[64:67]
	s_barrier
	s_add_i32 s18, s50, s31
	v_lshl_add_u64 v[210:211], v[210:211], 0, s[8:9]
	s_mov_b32 m0, s18
	ds_read_b128 v[178:181], v153 offset:49152
	ds_read_b128 v[182:185], v153 offset:50176
	ds_read_b128 v[186:189], v153 offset:51200
	ds_read_b128 v[190:193], v153 offset:52224
	ds_read_b128 v[194:197], v153 offset:53248
	ds_read_b128 v[198:201], v153 offset:54272
	ds_read_b128 v[202:205], v153 offset:55296
	ds_read_b128 v[206:209], v153 offset:56320
	global_load_lds_dwordx4 v[210:211], off
	s_add_i32 m0, s18, 0x2000
	s_add_u32 s18, s22, 0xb0080
	v_lshl_add_u64 v[210:211], v[212:213], 0, s[8:9]
	s_addc_u32 s19, s23, 0
	s_add_i32 s22, s51, s31
	global_load_lds_dwordx4 v[210:211], off
	v_lshl_add_u64 v[210:211], s[18:19], 0, v[128:129]
	s_mov_b32 m0, s22
	s_nop 0
	global_load_lds_dwordx4 v[210:211], off
	v_lshl_add_u64 v[210:211], s[18:19], 0, v[130:131]
	s_add_i32 m0, s22, 0x2000
	s_nop 0
	global_load_lds_dwordx4 v[210:211], off
	v_lshl_add_u64 v[210:211], v[214:215], 0, s[8:9]
	s_mov_b32 m0, s38
	s_nop 0
	global_load_lds_dwordx4 v[210:211], off
	v_lshl_add_u64 v[210:211], v[216:217], 0, s[8:9]
	s_mov_b32 m0, s39
	s_nop 0
	global_load_lds_dwordx4 v[210:211], off
	s_waitcnt vmcnt(8)
	s_waitcnt lgkmcnt(0)
	s_barrier
	s_waitcnt lgkmcnt(0)
	v_mfma_f32_16x16x32_bf16 v[60:63], v[140:143], v[178:181], v[60:63]
	v_mfma_f32_16x16x32_bf16 v[56:59], v[154:157], v[178:181], v[56:59]
	v_mfma_f32_16x16x32_bf16 v[48:51], v[140:143], v[186:189], v[48:51]
	v_mfma_f32_16x16x32_bf16 v[40:43], v[154:157], v[186:189], v[40:43]
	v_mfma_f32_16x16x32_bf16 v[32:35], v[140:143], v[194:197], v[32:35]
	v_mfma_f32_16x16x32_bf16 v[24:27], v[154:157], v[194:197], v[24:27]
	v_mfma_f32_16x16x32_bf16 v[16:19], v[140:143], v[202:205], v[16:19]
	v_mfma_f32_16x16x32_bf16 v[8:11], v[154:157], v[202:205], v[8:11]
	v_mfma_f32_16x16x32_bf16 v[60:63], v[144:147], v[182:185], v[60:63]
	v_mfma_f32_16x16x32_bf16 v[56:59], v[158:161], v[182:185], v[56:59]
	v_mfma_f32_16x16x32_bf16 v[48:51], v[144:147], v[190:193], v[48:51]
	v_mfma_f32_16x16x32_bf16 v[40:43], v[158:161], v[190:193], v[40:43]
	v_mfma_f32_16x16x32_bf16 v[32:35], v[144:147], v[198:201], v[32:35]
	v_mfma_f32_16x16x32_bf16 v[24:27], v[158:161], v[198:201], v[24:27]
	v_mfma_f32_16x16x32_bf16 v[16:19], v[144:147], v[206:209], v[16:19]
	v_mfma_f32_16x16x32_bf16 v[8:11], v[158:161], v[206:209], v[8:11]
	v_mfma_f32_16x16x32_bf16 v[52:55], v[162:165], v[178:181], v[52:55]
	v_mfma_f32_16x16x32_bf16 v[44:47], v[170:173], v[178:181], v[44:47]
	v_mfma_f32_16x16x32_bf16 v[36:39], v[162:165], v[186:189], v[36:39]
	v_mfma_f32_16x16x32_bf16 v[28:31], v[170:173], v[186:189], v[28:31]
	v_mfma_f32_16x16x32_bf16 v[20:23], v[162:165], v[194:197], v[20:23]
	v_mfma_f32_16x16x32_bf16 v[12:15], v[170:173], v[194:197], v[12:15]
	v_mfma_f32_16x16x32_bf16 v[4:7], v[162:165], v[202:205], v[4:7]
	v_mfma_f32_16x16x32_bf16 v[0:3], v[170:173], v[202:205], v[0:3]
	v_mfma_f32_16x16x32_bf16 v[52:55], v[166:169], v[182:185], v[52:55]
	v_mfma_f32_16x16x32_bf16 v[44:47], v[174:177], v[182:185], v[44:47]
	v_mfma_f32_16x16x32_bf16 v[36:39], v[166:169], v[190:193], v[36:39]
	v_mfma_f32_16x16x32_bf16 v[28:31], v[174:177], v[190:193], v[28:31]
	v_mfma_f32_16x16x32_bf16 v[20:23], v[166:169], v[198:201], v[20:23]
	v_mfma_f32_16x16x32_bf16 v[12:15], v[174:177], v[198:201], v[12:15]
	v_mfma_f32_16x16x32_bf16 v[4:7], v[166:169], v[206:209], v[4:7]
	v_mfma_f32_16x16x32_bf16 v[0:3], v[174:177], v[206:209], v[0:3]
	s_barrier
	s_add_i32 s49, s49, 2
	s_add_u32 s47, s47, 0x100
	s_addc_u32 s48, s48, 0
	s_cmp_gt_u32 s49, 41
	s_mov_b64 s[18:19], s[20:21]
	s_cbranch_scc0 .LBB0_1314
	s_and_b64 vcc, exec, s[14:15]
	s_cbranch_vccz .LBB0_1317
	s_barrier
